# LDS-DMA pieces rebalanced across the four load segments (2/4/4/6 instead of 2/6/2/6) with matching vmcnt waits
# speedup vs baseline: 1.0008x; 1.0008x over previous
; #define PG8_STAGE(bufoff, gbase, voff) do { _Pragma("unroll") for (int _i = 0; _i < 2; ++_i) \
;         __builtin_amdgcn_global_load_lds((const unsigned*)((const char*)(gbase) + (voff)[_i]), (LAS unsigned*)(lds + (bufoff) + ldsw + _i * 8192), 16, 0, 0); } while (0)
; #define PG8_LDA(dst, b, h) do { _Pragma("unroll") for (int m = 0; m < 4; ++m) _Pragma("unroll") for (int k = 0; k < 2; ++k) dst[m][k] = *(const LAS h16x8*)(lds + PG8_SA(b, h) + aoff + m * 2048 + k * 1024); } while (0)
; #define PG8_LDB(dst, b, h) do { _Pragma("unroll") for (int n = 0; n < 2; ++n) _Pragma("unroll") for (int k = 0; k < 2; ++k) dst[n][k] = *(const LAS h16x8*)(lds + PG8_SB(b, h) + boff + n * 2048 + k * 1024); } while (0)
; #define PG8_MMA(ai, bj, At, Bt_) do { __builtin_amdgcn_s_setprio(1); _Pragma("unroll") for (int m = 0; m < 4; ++m) _Pragma("unroll") for (int n = 0; n < 2; ++n) _Pragma("unroll") for (int k = 0; k < 2; ++k) \
;         acc[ai][bj][m][n] = __builtin_amdgcn_mfma_f32_16x16x32_f16(Bt_[n][k], At[m][k], acc[ai][bj][m][n], 0, 0, 0); __builtin_amdgcn_s_setprio(0); } while (0)
; #define PG8_WAIT_V(n) asm volatile("s_waitcnt vmcnt(" #n ")" ::: "memory")
; template <class Epi, class AMap>
; __device__ __forceinline__ void gemm_phase(LAS unsigned char* lds, const AMap am, const int lda, const h16* Bt, const int ldb, const int M, const int N, const int K, const Epi& E) {
;     ...
;         for (int t = 0; t < nt; t += 2) {
;             const bool last = (t == nt - 2);
;             const char* a1 = cA + (size_t)(t + 1) * kstep;
;             const char* a2 = last ? nA : cA + (size_t)(t + 2) * kstep; const char* b2 = last ? nB : cB + (size_t)(t + 2) * kstep;
;             const char* a3 = a2 + kstep; const char* b3 = b2 + kstep;
;             PG8_LDB(B0, 0, 0); PG8_SCHED; PG8_LDA(At, 0, 0); PG8_STAGE(PG8_SA(1, 1), a1 + hstepA, voffA);
;             PG8_WAIT_L(8); PG8_BAR; PG8_WAIT_L(0); PG8_MMA(0, 0, At, B0); PG8_BAR; PG8_SCHED;
;             PG8_LDB(B1, 0, 1); PG8_STAGE(PG8_SB(0, 0), b2, voffB);
;             PG8_BAR; PG8_WAIT_L(0); PG8_MMA(0, 1, At, B1); PG8_BAR;
;             PG8_LDA(At, 0, 1); PG8_STAGE(PG8_SA(0, 0), a2, voffA);
;             PG8_BAR; PG8_WAIT_L(0); PG8_MMA(1, 0, At, B0); PG8_BAR; PG8_SCHED;
;             PG8_STAGE(PG8_SB(0, 1), b2 + hstepB, voffB);
;             PG8_WAIT_V(6); PG8_BAR; PG8_MMA(1, 1, At, B1); PG8_BAR;
.LBB0_61:
	s_add_u32 s26, s22, 0x100
	s_addc_u32 s27, s23, 0
	s_add_i32 s51, 0, 0x10000
	v_add_u32_e32 v144, s51, v147
	ds_read_b128 v[140:143], v144
	ds_read_b128 v[150:153], v144 offset:1024
	ds_read_b128 v[154:157], v144 offset:2048
	ds_read_b128 v[158:161], v144 offset:3072
	s_cmpk_eq_i32 s29, 0x52
	s_cselect_b32 s45, s1, s27
	s_cselect_b32 s44, s0, s26
	s_cselect_b32 s43, s41, s21
	s_cselect_b32 s42, s40, s20
	v_lshl_add_u64 v[144:145], s[22:23], 0, v[136:137]
	s_add_i32 m0, s63, 0xc000
	ds_read_b128 v[162:165], v149
	ds_read_b128 v[166:169], v149 offset:1024
	ds_read_b128 v[170:173], v149 offset:2048
	ds_read_b128 v[174:177], v149 offset:3072
	ds_read_b128 v[178:181], v149 offset:4096
	ds_read_b128 v[182:185], v149 offset:5120
	ds_read_b128 v[186:189], v149 offset:6144
	ds_read_b128 v[190:193], v149 offset:7168
	global_load_lds_dwordx4 v[144:145], off
	v_lshl_add_u64 v[144:145], s[22:23], 0, v[138:139]
	s_add_i32 m0, s63, 0xe000
	s_nop 0
	global_load_lds_dwordx4 v[144:145], off
	s_waitcnt lgkmcnt(11)
	s_add_i32 s60, 0, 0x14000
	v_add_u32_e32 v144, s60, v147
	s_add_i32 s22, s51, s48
	ds_read_b128 v[194:197], v144
	ds_read_b128 v[198:201], v144 offset:1024
	ds_read_b128 v[202:205], v144 offset:2048
	ds_read_b128 v[220:223], v144 offset:3072
	s_waitcnt vmcnt(8) lgkmcnt(0)
	s_barrier
	v_mfma_f32_16x16x32_f16 v[126:129], v[140:143], v[162:165], v[126:129]
	v_mfma_f32_16x16x32_f16 v[122:125], v[154:157], v[162:165], v[122:125]
	v_mfma_f32_16x16x32_f16 v[110:113], v[140:143], v[170:173], v[110:113]
	v_mfma_f32_16x16x32_f16 v[106:109], v[154:157], v[170:173], v[106:109]
	v_mfma_f32_16x16x32_f16 v[94:97], v[140:143], v[178:181], v[94:97]
	v_mfma_f32_16x16x32_f16 v[90:93], v[154:157], v[178:181], v[90:93]
	v_mfma_f32_16x16x32_f16 v[78:81], v[140:143], v[186:189], v[78:81]
	v_mfma_f32_16x16x32_f16 v[74:77], v[154:157], v[186:189], v[74:77]
	v_mfma_f32_16x16x32_f16 v[126:129], v[150:153], v[166:169], v[126:129]
	v_mfma_f32_16x16x32_f16 v[122:125], v[158:161], v[166:169], v[122:125]
	v_mfma_f32_16x16x32_f16 v[110:113], v[150:153], v[174:177], v[110:113]
	v_mfma_f32_16x16x32_f16 v[106:109], v[158:161], v[174:177], v[106:109]
	v_mfma_f32_16x16x32_f16 v[94:97], v[150:153], v[182:185], v[94:97]
	v_mfma_f32_16x16x32_f16 v[90:93], v[158:161], v[182:185], v[90:93]
	v_mfma_f32_16x16x32_f16 v[78:81], v[150:153], v[190:193], v[78:81]
	v_mfma_f32_16x16x32_f16 v[74:77], v[158:161], v[190:193], v[74:77]
	v_mfma_f32_16x16x32_f16 v[118:121], v[194:197], v[162:165], v[118:121]
	v_mfma_f32_16x16x32_f16 v[114:117], v[202:205], v[162:165], v[114:117]
	v_mfma_f32_16x16x32_f16 v[102:105], v[194:197], v[170:173], v[102:105]
	v_mfma_f32_16x16x32_f16 v[98:101], v[202:205], v[170:173], v[98:101]
	v_mfma_f32_16x16x32_f16 v[86:89], v[194:197], v[178:181], v[86:89]
	v_mfma_f32_16x16x32_f16 v[82:85], v[202:205], v[178:181], v[82:85]
	v_mfma_f32_16x16x32_f16 v[70:73], v[194:197], v[186:189], v[70:73]
	v_mfma_f32_16x16x32_f16 v[66:69], v[202:205], v[186:189], v[66:69]
	v_mfma_f32_16x16x32_f16 v[118:121], v[198:201], v[166:169], v[118:121]
	v_mfma_f32_16x16x32_f16 v[114:117], v[220:223], v[166:169], v[114:117]
	v_mfma_f32_16x16x32_f16 v[102:105], v[198:201], v[174:177], v[102:105]
	v_mfma_f32_16x16x32_f16 v[98:101], v[220:223], v[174:177], v[98:101]
	v_mfma_f32_16x16x32_f16 v[86:89], v[198:201], v[182:185], v[86:89]
	v_mfma_f32_16x16x32_f16 v[82:85], v[220:223], v[182:185], v[82:85]
	v_mfma_f32_16x16x32_f16 v[70:73], v[198:201], v[190:193], v[70:73]
	v_mfma_f32_16x16x32_f16 v[66:69], v[220:223], v[190:193], v[66:69]
	s_barrier
	v_lshl_add_u64 v[144:145], s[42:43], 0, v[0:1]
	s_mov_b32 m0, s22
	v_lshl_add_u64 v[206:207], s[42:43], 0, v[134:135]
	global_load_lds_dwordx4 v[144:145], off
	s_add_i32 m0, s22, 0x2000
	s_nop 0
	global_load_lds_dwordx4 v[206:207], off
	s_mov_b32 m0, s63
	v_lshl_add_u64 v[212:213], s[44:45], 0, v[130:131]
	ds_read_b128 v[162:165], v149 offset:16384
	ds_read_b128 v[166:169], v149 offset:17408
	ds_read_b128 v[170:173], v149 offset:18432
	ds_read_b128 v[174:177], v149 offset:19456
	ds_read_b128 v[178:181], v149 offset:20480
	ds_read_b128 v[182:185], v149 offset:21504
	ds_read_b128 v[186:189], v149 offset:22528
	ds_read_b128 v[190:193], v149 offset:23552
	global_load_lds_dwordx4 v[212:213], off
	v_lshl_add_u64 v[214:215], s[44:45], 0, v[132:133]
	s_mov_b32 m0, s64
	s_nop 0
	global_load_lds_dwordx4 v[214:215], off
	s_waitcnt vmcnt(6) lgkmcnt(0)
	s_barrier
	v_mfma_f32_16x16x32_f16 v[62:65], v[140:143], v[162:165], v[62:65]
	v_mfma_f32_16x16x32_f16 v[58:61], v[154:157], v[162:165], v[58:61]
	v_mfma_f32_16x16x32_f16 v[46:49], v[140:143], v[170:173], v[46:49]
	v_mfma_f32_16x16x32_f16 v[42:45], v[154:157], v[170:173], v[42:45]
	v_mfma_f32_16x16x32_f16 v[30:33], v[140:143], v[178:181], v[30:33]
	v_mfma_f32_16x16x32_f16 v[26:29], v[154:157], v[178:181], v[26:29]
	v_mfma_f32_16x16x32_f16 v[14:17], v[140:143], v[186:189], v[14:17]
	v_mfma_f32_16x16x32_f16 v[10:13], v[154:157], v[186:189], v[10:13]
	v_mfma_f32_16x16x32_f16 v[62:65], v[150:153], v[166:169], v[62:65]
	v_mfma_f32_16x16x32_f16 v[58:61], v[158:161], v[166:169], v[58:61]
	v_mfma_f32_16x16x32_f16 v[46:49], v[150:153], v[174:177], v[46:49]
	v_mfma_f32_16x16x32_f16 v[42:45], v[158:161], v[174:177], v[42:45]
	v_mfma_f32_16x16x32_f16 v[30:33], v[150:153], v[182:185], v[30:33]
	v_mfma_f32_16x16x32_f16 v[26:29], v[158:161], v[182:185], v[26:29]
	v_mfma_f32_16x16x32_f16 v[14:17], v[150:153], v[190:193], v[14:17]
	v_mfma_f32_16x16x32_f16 v[10:13], v[158:161], v[190:193], v[10:13]
	v_mfma_f32_16x16x32_f16 v[54:57], v[194:197], v[162:165], v[54:57]
	v_mfma_f32_16x16x32_f16 v[50:53], v[202:205], v[162:165], v[50:53]
	v_mfma_f32_16x16x32_f16 v[38:41], v[194:197], v[170:173], v[38:41]
	v_mfma_f32_16x16x32_f16 v[34:37], v[202:205], v[170:173], v[34:37]
	v_mfma_f32_16x16x32_f16 v[22:25], v[194:197], v[178:181], v[22:25]
	v_mfma_f32_16x16x32_f16 v[18:21], v[202:205], v[178:181], v[18:21]
	v_mfma_f32_16x16x32_f16 v[6:9], v[194:197], v[186:189], v[6:9]
	v_mfma_f32_16x16x32_f16 v[2:5], v[202:205], v[186:189], v[2:5]
	v_mfma_f32_16x16x32_f16 v[54:57], v[198:201], v[166:169], v[54:57]
	v_mfma_f32_16x16x32_f16 v[50:53], v[220:223], v[166:169], v[50:53]
	v_mfma_f32_16x16x32_f16 v[38:41], v[198:201], v[174:177], v[38:41]
	v_mfma_f32_16x16x32_f16 v[34:37], v[220:223], v[174:177], v[34:37]
	v_mfma_f32_16x16x32_f16 v[22:25], v[198:201], v[182:185], v[22:25]
	v_mfma_f32_16x16x32_f16 v[18:21], v[220:223], v[182:185], v[18:21]
	v_mfma_f32_16x16x32_f16 v[6:9], v[198:201], v[190:193], v[6:9]
	v_mfma_f32_16x16x32_f16 v[2:5], v[220:223], v[190:193], v[2:5]
	s_barrier
; #define PG8_STAGE(bufoff, gbase, voff) do { _Pragma("unroll") for (int _i = 0; _i < 2; ++_i) \
;         __builtin_amdgcn_global_load_lds((const unsigned*)((const char*)(gbase) + (voff)[_i]), (LAS unsigned*)(lds + (bufoff) + ldsw + _i * 8192), 16, 0, 0); } while (0)
; #define PG8_LDA(dst, b, h) do { _Pragma("unroll") for (int m = 0; m < 4; ++m) _Pragma("unroll") for (int k = 0; k < 2; ++k) dst[m][k] = *(const LAS h16x8*)(lds + PG8_SA(b, h) + aoff + m * 2048 + k * 1024); } while (0)
; #define PG8_LDB(dst, b, h) do { _Pragma("unroll") for (int n = 0; n < 2; ++n) _Pragma("unroll") for (int k = 0; k < 2; ++k) dst[n][k] = *(const LAS h16x8*)(lds + PG8_SB(b, h) + boff + n * 2048 + k * 1024); } while (0)
; #define PG8_MMA(ai, bj, At, Bt_) do { __builtin_amdgcn_s_setprio(1); _Pragma("unroll") for (int m = 0; m < 4; ++m) _Pragma("unroll") for (int n = 0; n < 2; ++n) _Pragma("unroll") for (int k = 0; k < 2; ++k) \
;         acc[ai][bj][m][n] = __builtin_amdgcn_mfma_f32_16x16x32_f16(Bt_[n][k], At[m][k], acc[ai][bj][m][n], 0, 0, 0); __builtin_amdgcn_s_setprio(0); } while (0)
; #define PG8_WAIT_V(n) asm volatile("s_waitcnt vmcnt(" #n ")" ::: "memory")
; #define PG8_WAIT_L(n) asm volatile("s_waitcnt lgkmcnt(" #n ")" ::: "memory")
; #define PG8_BAR __builtin_amdgcn_s_barrier()
; #define PG8_SCHED __builtin_amdgcn_sched_barrier(0)
; template <class Epi, class AMap>
; __device__ __forceinline__ void gemm_phase(LAS unsigned char* lds, const AMap am, const int lda, const h16* Bt, const int ldb, const int M, const int N, const int K, const Epi& E) {
;     ...
;             PG8_STAGE(PG8_SB(0, 1), b2 + hstepB, voffB);
;             PG8_WAIT_V(6); PG8_BAR; PG8_MMA(1, 1, At, B1); PG8_BAR;
;             PG8_LDB(B0, 1, 0); PG8_SCHED; PG8_LDA(At, 1, 0); PG8_STAGE(PG8_SA(0, 1), a2 + hstepA, voffA);
;             PG8_WAIT_L(8); PG8_BAR; PG8_WAIT_L(0); PG8_MMA(0, 0, At, B0); PG8_BAR; PG8_SCHED;
;             PG8_LDB(B1, 1, 1); PG8_STAGE(PG8_SB(1, 0), b3, voffB);
;             PG8_BAR; PG8_WAIT_L(0); PG8_MMA(0, 1, At, B1); PG8_BAR;
	s_add_u32 s22, s42, 0x158000
	s_addc_u32 s23, s43, 0
	s_add_i32 s51, s60, s48
	v_lshl_add_u64 v[232:233], s[22:23], 0, v[0:1]
	s_mov_b32 m0, s51
	s_nop 0
	global_load_lds_dwordx4 v[232:233], off
	v_lshl_add_u64 v[232:233], s[22:23], 0, v[134:135]
	s_add_i32 m0, s51, 0x2000
	s_nop 0
	global_load_lds_dwordx4 v[232:233], off
	s_add_i32 s51, 0, 0x18000
	v_add_u32_e32 v234, s51, v147
	ds_read_b128 v[140:143], v234
	ds_read_b128 v[150:153], v234 offset:1024
	ds_read_b128 v[154:157], v234 offset:2048
	ds_read_b128 v[158:161], v234 offset:3072
	s_add_u32 s22, s44, 0x158000
	s_addc_u32 s23, s45, 0
	s_mov_b32 m0, s65
	v_lshl_add_u64 v[232:233], s[22:23], 0, v[130:131]
	ds_read_b128 v[162:165], v149 offset:32768
	ds_read_b128 v[166:169], v149 offset:33792
	ds_read_b128 v[170:173], v149 offset:34816
	ds_read_b128 v[174:177], v149 offset:35840
	ds_read_b128 v[178:181], v149 offset:36864
	ds_read_b128 v[182:185], v149 offset:37888
	ds_read_b128 v[186:189], v149 offset:38912
	ds_read_b128 v[190:193], v149 offset:39936
	global_load_lds_dwordx4 v[232:233], off
	v_lshl_add_u64 v[232:233], s[22:23], 0, v[132:133]
	s_mov_b32 m0, s68
	s_nop 0
	global_load_lds_dwordx4 v[232:233], off
	s_waitcnt lgkmcnt(11)
	s_add_i32 s44, 0, 0x1c000
	s_add_i32 s22, s51, s48
	v_add_u32_e32 v216, s44, v147
	v_lshl_add_u64 v[144:145], v[144:145], 0, s[92:93]
	s_mov_b32 m0, s22
	ds_read_b128 v[194:197], v216
	ds_read_b128 v[198:201], v216 offset:1024
	ds_read_b128 v[202:205], v216 offset:2048
	ds_read_b128 v[220:223], v216 offset:3072
	s_waitcnt vmcnt(8) lgkmcnt(0)
	s_barrier
	v_mfma_f32_16x16x32_f16 v[126:129], v[140:143], v[162:165], v[126:129]
	v_mfma_f32_16x16x32_f16 v[122:125], v[154:157], v[162:165], v[122:125]
	v_mfma_f32_16x16x32_f16 v[110:113], v[140:143], v[170:173], v[110:113]
	v_mfma_f32_16x16x32_f16 v[106:109], v[154:157], v[170:173], v[106:109]
	v_mfma_f32_16x16x32_f16 v[94:97], v[140:143], v[178:181], v[94:97]
	v_mfma_f32_16x16x32_f16 v[90:93], v[154:157], v[178:181], v[90:93]
	v_mfma_f32_16x16x32_f16 v[78:81], v[140:143], v[186:189], v[78:81]
	v_mfma_f32_16x16x32_f16 v[74:77], v[154:157], v[186:189], v[74:77]
	v_mfma_f32_16x16x32_f16 v[126:129], v[150:153], v[166:169], v[126:129]
	v_mfma_f32_16x16x32_f16 v[122:125], v[158:161], v[166:169], v[122:125]
	v_mfma_f32_16x16x32_f16 v[110:113], v[150:153], v[174:177], v[110:113]
	v_mfma_f32_16x16x32_f16 v[106:109], v[158:161], v[174:177], v[106:109]
	v_mfma_f32_16x16x32_f16 v[94:97], v[150:153], v[182:185], v[94:97]
	v_mfma_f32_16x16x32_f16 v[90:93], v[158:161], v[182:185], v[90:93]
	v_mfma_f32_16x16x32_f16 v[78:81], v[150:153], v[190:193], v[78:81]
	v_mfma_f32_16x16x32_f16 v[74:77], v[158:161], v[190:193], v[74:77]
	v_mfma_f32_16x16x32_f16 v[118:121], v[194:197], v[162:165], v[118:121]
	v_mfma_f32_16x16x32_f16 v[114:117], v[202:205], v[162:165], v[114:117]
	v_mfma_f32_16x16x32_f16 v[102:105], v[194:197], v[170:173], v[102:105]
	v_mfma_f32_16x16x32_f16 v[98:101], v[202:205], v[170:173], v[98:101]
	v_mfma_f32_16x16x32_f16 v[86:89], v[194:197], v[178:181], v[86:89]
	v_mfma_f32_16x16x32_f16 v[82:85], v[202:205], v[178:181], v[82:85]
	v_mfma_f32_16x16x32_f16 v[70:73], v[194:197], v[186:189], v[70:73]
	v_mfma_f32_16x16x32_f16 v[66:69], v[202:205], v[186:189], v[66:69]
	v_mfma_f32_16x16x32_f16 v[118:121], v[198:201], v[166:169], v[118:121]
	v_mfma_f32_16x16x32_f16 v[114:117], v[220:223], v[166:169], v[114:117]
	v_mfma_f32_16x16x32_f16 v[102:105], v[198:201], v[174:177], v[102:105]
	v_mfma_f32_16x16x32_f16 v[98:101], v[220:223], v[174:177], v[98:101]
	v_mfma_f32_16x16x32_f16 v[86:89], v[198:201], v[182:185], v[86:89]
	v_mfma_f32_16x16x32_f16 v[82:85], v[220:223], v[182:185], v[82:85]
	v_mfma_f32_16x16x32_f16 v[70:73], v[198:201], v[190:193], v[70:73]
	v_mfma_f32_16x16x32_f16 v[66:69], v[220:223], v[190:193], v[66:69]
	s_barrier
; #define PG8_STAGE(bufoff, gbase, voff) do { _Pragma("unroll") for (int _i = 0; _i < 2; ++_i) \
;         __builtin_amdgcn_global_load_lds((const unsigned*)((const char*)(gbase) + (voff)[_i]), (LAS unsigned*)(lds + (bufoff) + ldsw + _i * 8192), 16, 0, 0); } while (0)
; #define PG8_LDA(dst, b, h) do { _Pragma("unroll") for (int m = 0; m < 4; ++m) _Pragma("unroll") for (int k = 0; k < 2; ++k) dst[m][k] = *(const LAS h16x8*)(lds + PG8_SA(b, h) + aoff + m * 2048 + k * 1024); } while (0)
; #define PG8_LDB(dst, b, h) do { _Pragma("unroll") for (int n = 0; n < 2; ++n) _Pragma("unroll") for (int k = 0; k < 2; ++k) dst[n][k] = *(const LAS h16x8*)(lds + PG8_SB(b, h) + boff + n * 2048 + k * 1024); } while (0)
; #define PG8_MMA(ai, bj, At, Bt_) do { __builtin_amdgcn_s_setprio(1); _Pragma("unroll") for (int m = 0; m < 4; ++m) _Pragma("unroll") for (int n = 0; n < 2; ++n) _Pragma("unroll") for (int k = 0; k < 2; ++k) \
;         acc[ai][bj][m][n] = __builtin_amdgcn_mfma_f32_16x16x32_f16(Bt_[n][k], At[m][k], acc[ai][bj][m][n], 0, 0, 0); __builtin_amdgcn_s_setprio(0); } while (0)
; #define PG8_WAIT_V(n) asm volatile("s_waitcnt vmcnt(" #n ")" ::: "memory")
; #define PG8_WAIT_L(n) asm volatile("s_waitcnt lgkmcnt(" #n ")" ::: "memory")
; #define PG8_BAR __builtin_amdgcn_s_barrier()
; #define PG8_SCHED __builtin_amdgcn_sched_barrier(0)
; template <class Epi, class AMap>
; __device__ __forceinline__ void gemm_phase(LAS unsigned char* lds, const AMap am, const int lda, const h16* Bt, const int ldb, const int M, const int N, const int K, const Epi& E) {
;     ...
;             PG8_LDB(B1, 1, 1); PG8_STAGE(PG8_SB(1, 0), b3, voffB);
;             PG8_BAR; PG8_WAIT_L(0); PG8_MMA(0, 1, At, B1); PG8_BAR;
;             PG8_LDA(At, 1, 1); PG8_STAGE(PG8_SA(1, 0), a3, voffA);
;             PG8_BAR; PG8_WAIT_L(0); PG8_MMA(1, 0, At, B0); PG8_BAR; PG8_SCHED;
;             PG8_STAGE(PG8_SB(1, 1), b3 + hstepB, voffB);
;             PG8_WAIT_V(6); PG8_BAR; PG8_MMA(1, 1, At, B1); PG8_BAR;
;         }
;     ...
;     if (wr == 0) PG8_BAR;
	global_load_lds_dwordx4 v[144:145], off
	v_lshl_add_u64 v[144:145], v[206:207], 0, s[92:93]
	s_add_i32 m0, s22, 0x2000
	s_nop 0
	global_load_lds_dwordx4 v[144:145], off
	s_mov_b32 m0, s69
	v_lshl_add_u64 v[144:145], v[212:213], 0, s[92:93]
	ds_read_b128 v[162:165], v149 offset:49152
	ds_read_b128 v[166:169], v149 offset:50176
	ds_read_b128 v[170:173], v149 offset:51200
	ds_read_b128 v[174:177], v149 offset:52224
	ds_read_b128 v[178:181], v149 offset:53248
	ds_read_b128 v[182:185], v149 offset:54272
	ds_read_b128 v[186:189], v149 offset:55296
	ds_read_b128 v[190:193], v149 offset:56320
	global_load_lds_dwordx4 v[144:145], off
	v_lshl_add_u64 v[144:145], v[214:215], 0, s[92:93]
	s_mov_b32 m0, s70
	s_nop 0
	global_load_lds_dwordx4 v[144:145], off
	s_add_u32 s22, s42, 0x158080
	s_addc_u32 s23, s43, 0
	s_add_i32 s42, s44, s48
	v_lshl_add_u64 v[232:233], s[22:23], 0, v[0:1]
	s_mov_b32 m0, s42
	s_nop 0
	global_load_lds_dwordx4 v[232:233], off
	v_lshl_add_u64 v[232:233], s[22:23], 0, v[134:135]
	s_add_i32 m0, s42, 0x2000
	s_nop 0
	global_load_lds_dwordx4 v[232:233], off
	s_add_i32 s29, s29, 2
	s_add_u32 s20, s20, 0x100
	s_addc_u32 s21, s21, 0
	s_cmpk_gt_u32 s29, 0x53
	s_mov_b64 s[22:23], s[26:27]
	s_waitcnt vmcnt(8) lgkmcnt(0)
	s_barrier
	v_mfma_f32_16x16x32_f16 v[62:65], v[140:143], v[162:165], v[62:65]
	v_mfma_f32_16x16x32_f16 v[58:61], v[154:157], v[162:165], v[58:61]
	v_mfma_f32_16x16x32_f16 v[46:49], v[140:143], v[170:173], v[46:49]
	v_mfma_f32_16x16x32_f16 v[42:45], v[154:157], v[170:173], v[42:45]
	v_mfma_f32_16x16x32_f16 v[30:33], v[140:143], v[178:181], v[30:33]
	v_mfma_f32_16x16x32_f16 v[26:29], v[154:157], v[178:181], v[26:29]
	v_mfma_f32_16x16x32_f16 v[14:17], v[140:143], v[186:189], v[14:17]
	v_mfma_f32_16x16x32_f16 v[10:13], v[154:157], v[186:189], v[10:13]
	v_mfma_f32_16x16x32_f16 v[62:65], v[150:153], v[166:169], v[62:65]
	v_mfma_f32_16x16x32_f16 v[58:61], v[158:161], v[166:169], v[58:61]
	v_mfma_f32_16x16x32_f16 v[46:49], v[150:153], v[174:177], v[46:49]
	v_mfma_f32_16x16x32_f16 v[42:45], v[158:161], v[174:177], v[42:45]
	v_mfma_f32_16x16x32_f16 v[30:33], v[150:153], v[182:185], v[30:33]
	v_mfma_f32_16x16x32_f16 v[26:29], v[158:161], v[182:185], v[26:29]
	v_mfma_f32_16x16x32_f16 v[14:17], v[150:153], v[190:193], v[14:17]
	v_mfma_f32_16x16x32_f16 v[10:13], v[158:161], v[190:193], v[10:13]
	v_mfma_f32_16x16x32_f16 v[54:57], v[194:197], v[162:165], v[54:57]
	v_mfma_f32_16x16x32_f16 v[50:53], v[202:205], v[162:165], v[50:53]
	v_mfma_f32_16x16x32_f16 v[38:41], v[194:197], v[170:173], v[38:41]
	v_mfma_f32_16x16x32_f16 v[34:37], v[202:205], v[170:173], v[34:37]
	v_mfma_f32_16x16x32_f16 v[22:25], v[194:197], v[178:181], v[22:25]
	v_mfma_f32_16x16x32_f16 v[18:21], v[202:205], v[178:181], v[18:21]
	v_mfma_f32_16x16x32_f16 v[6:9], v[194:197], v[186:189], v[6:9]
	v_mfma_f32_16x16x32_f16 v[2:5], v[202:205], v[186:189], v[2:5]
	v_mfma_f32_16x16x32_f16 v[54:57], v[198:201], v[166:169], v[54:57]
	v_mfma_f32_16x16x32_f16 v[50:53], v[220:223], v[166:169], v[50:53]
	v_mfma_f32_16x16x32_f16 v[38:41], v[198:201], v[174:177], v[38:41]
	v_mfma_f32_16x16x32_f16 v[34:37], v[220:223], v[174:177], v[34:37]
	v_mfma_f32_16x16x32_f16 v[22:25], v[198:201], v[182:185], v[22:25]
	v_mfma_f32_16x16x32_f16 v[18:21], v[220:223], v[182:185], v[18:21]
	v_mfma_f32_16x16x32_f16 v[6:9], v[198:201], v[190:193], v[6:9]
	v_mfma_f32_16x16x32_f16 v[2:5], v[220:223], v[190:193], v[2:5]
	s_barrier
	s_cbranch_scc0 .LBB0_61
	s_cmpk_gt_u32 s46, 0xff
	s_cbranch_scc1 .Lgx0
	s_barrier

; #define PG8_STAGE(bufoff, gbase, voff) do { _Pragma("unroll") for (int _i = 0; _i < 2; ++_i) \
;         __builtin_amdgcn_global_load_lds((const unsigned*)((const char*)(gbase) + (voff)[_i]), (LAS unsigned*)(lds + (bufoff) + ldsw + _i * 8192), 16, 0, 0); } while (0)
; #define PG8_LDA(dst, b, h) do { _Pragma("unroll") for (int m = 0; m < 4; ++m) _Pragma("unroll") for (int k = 0; k < 2; ++k) dst[m][k] = *(const LAS h16x8*)(lds + PG8_SA(b, h) + aoff + m * 2048 + k * 1024); } while (0)
; #define PG8_LDB(dst, b, h) do { _Pragma("unroll") for (int n = 0; n < 2; ++n) _Pragma("unroll") for (int k = 0; k < 2; ++k) dst[n][k] = *(const LAS h16x8*)(lds + PG8_SB(b, h) + boff + n * 2048 + k * 1024); } while (0)
; #define PG8_MMA(ai, bj, At, Bt_) do { __builtin_amdgcn_s_setprio(1); _Pragma("unroll") for (int m = 0; m < 4; ++m) _Pragma("unroll") for (int n = 0; n < 2; ++n) _Pragma("unroll") for (int k = 0; k < 2; ++k) \
;         acc[ai][bj][m][n] = __builtin_amdgcn_mfma_f32_16x16x32_f16(Bt_[n][k], At[m][k], acc[ai][bj][m][n], 0, 0, 0); __builtin_amdgcn_s_setprio(0); } while (0)
; #define PG8_WAIT_V(n) asm volatile("s_waitcnt vmcnt(" #n ")" ::: "memory")
; template <class Epi, class AMap>
; __device__ __forceinline__ void gemm_phase(LAS unsigned char* lds, const AMap am, const int lda, const h16* Bt, const int ldb, const int M, const int N, const int K, const Epi& E) {
;     ...
;         for (int t = 0; t < nt; t += 2) {
;             const bool last = (t == nt - 2);
;             const char* a1 = cA + (size_t)(t + 1) * kstep;
;             const char* a2 = last ? nA : cA + (size_t)(t + 2) * kstep; const char* b2 = last ? nB : cB + (size_t)(t + 2) * kstep;
;             const char* a3 = a2 + kstep; const char* b3 = b2 + kstep;
;             PG8_LDB(B0, 0, 0); PG8_SCHED; PG8_LDA(At, 0, 0); PG8_STAGE(PG8_SA(1, 1), a1 + hstepA, voffA);
;             PG8_WAIT_L(8); PG8_BAR; PG8_WAIT_L(0); PG8_MMA(0, 0, At, B0); PG8_BAR; PG8_SCHED;
;             PG8_LDB(B1, 0, 1); PG8_STAGE(PG8_SB(0, 0), b2, voffB);
;             PG8_BAR; PG8_WAIT_L(0); PG8_MMA(0, 1, At, B1); PG8_BAR;
;             PG8_LDA(At, 0, 1); PG8_STAGE(PG8_SA(0, 0), a2, voffA);
;             PG8_BAR; PG8_WAIT_L(0); PG8_MMA(1, 0, At, B0); PG8_BAR; PG8_SCHED;
;             PG8_STAGE(PG8_SB(0, 1), b2 + hstepB, voffB);
;             PG8_WAIT_V(6); PG8_BAR; PG8_MMA(1, 1, At, B1); PG8_BAR;
.LBB0_92:
	s_add_u32 s0, vcc_lo, 0xfff80080
	s_addc_u32 s1, vcc_hi, -1
	s_add_i32 s67, 0, 0x10000
	v_add_u32_e32 v226, s67, v169
	ds_read_b128 v[66:69], v226
	ds_read_b128 v[70:73], v226 offset:1024
	ds_read_b128 v[74:77], v226 offset:2048
	ds_read_b128 v[78:81], v226 offset:3072
	s_cmp_eq_u32 s60, 28
	s_cselect_b32 s27, s69, s1
	s_cselect_b32 s26, s29, s0
	s_cselect_b32 s49, s73, s66
	s_cselect_b32 s48, s20, s21
	v_lshl_add_u64 v[192:193], vcc, 0, v[172:173]
	s_add_i32 m0, s81, 0xc000
	ds_read_b128 v[90:93], v195
	ds_read_b128 v[94:97], v195 offset:1024
	ds_read_b128 v[98:101], v195 offset:2048
	ds_read_b128 v[102:105], v195 offset:3072
	ds_read_b128 v[176:179], v195 offset:4096
	ds_read_b128 v[180:183], v195 offset:5120
	ds_read_b128 v[184:187], v195 offset:6144
	ds_read_b128 v[188:191], v195 offset:7168
	global_load_lds_dwordx4 v[192:193], off
	v_lshl_add_u64 v[192:193], vcc, 0, v[174:175]
	s_add_i32 m0, s81, 0xe000
	s_nop 0
	global_load_lds_dwordx4 v[192:193], off
	s_waitcnt lgkmcnt(11)
	s_add_i32 s65, 0, 0x14000
	v_add_u32_e32 v192, s65, v169
	s_add_i32 s0, s67, s64
	ds_read_b128 v[196:199], v192
	ds_read_b128 v[200:203], v192 offset:1024
	ds_read_b128 v[204:207], v192 offset:2048
	ds_read_b128 v[220:223], v192 offset:3072
	s_waitcnt vmcnt(8) lgkmcnt(0)
	s_barrier
	v_mfma_f32_16x16x32_f16 v[158:161], v[66:69], v[90:93], v[158:161]
	v_mfma_f32_16x16x32_f16 v[154:157], v[74:77], v[90:93], v[154:157]
	v_mfma_f32_16x16x32_f16 v[142:145], v[66:69], v[98:101], v[142:145]
	v_mfma_f32_16x16x32_f16 v[134:137], v[74:77], v[98:101], v[134:137]
	v_mfma_f32_16x16x32_f16 v[126:129], v[66:69], v[176:179], v[126:129]
	v_mfma_f32_16x16x32_f16 v[118:121], v[74:77], v[176:179], v[118:121]
	v_mfma_f32_16x16x32_f16 v[110:113], v[66:69], v[184:187], v[110:113]
	v_mfma_f32_16x16x32_f16 v[106:109], v[74:77], v[184:187], v[106:109]
	v_mfma_f32_16x16x32_f16 v[158:161], v[70:73], v[94:97], v[158:161]
	v_mfma_f32_16x16x32_f16 v[154:157], v[78:81], v[94:97], v[154:157]
	v_mfma_f32_16x16x32_f16 v[142:145], v[70:73], v[102:105], v[142:145]
	v_mfma_f32_16x16x32_f16 v[134:137], v[78:81], v[102:105], v[134:137]
	v_mfma_f32_16x16x32_f16 v[126:129], v[70:73], v[180:183], v[126:129]
	v_mfma_f32_16x16x32_f16 v[118:121], v[78:81], v[180:183], v[118:121]
	v_mfma_f32_16x16x32_f16 v[110:113], v[70:73], v[188:191], v[110:113]
	v_mfma_f32_16x16x32_f16 v[106:109], v[78:81], v[188:191], v[106:109]
	v_mfma_f32_16x16x32_f16 v[150:153], v[196:199], v[90:93], v[150:153]
	v_mfma_f32_16x16x32_f16 v[146:149], v[204:207], v[90:93], v[146:149]
	v_mfma_f32_16x16x32_f16 v[150:153], v[200:203], v[94:97], v[150:153]
	v_mfma_f32_16x16x32_f16 v[146:149], v[220:223], v[94:97], v[146:149]
	v_mfma_f32_16x16x32_f16 v[138:141], v[196:199], v[98:101], v[138:141]
	v_mfma_f32_16x16x32_f16 v[130:133], v[204:207], v[98:101], v[130:133]
	v_mfma_f32_16x16x32_f16 v[114:117], v[204:207], v[176:179], v[114:117]
	v_mfma_f32_16x16x32_f16 v[86:89], v[196:199], v[184:187], v[86:89]
	v_mfma_f32_16x16x32_f16 v[82:85], v[204:207], v[184:187], v[82:85]
	v_mfma_f32_16x16x32_f16 v[138:141], v[200:203], v[102:105], v[138:141]
	v_mfma_f32_16x16x32_f16 v[130:133], v[220:223], v[102:105], v[130:133]
	v_mfma_f32_16x16x32_f16 v[122:125], v[196:199], v[176:179], v[122:125]
	v_mfma_f32_16x16x32_f16 v[114:117], v[220:223], v[180:183], v[114:117]
	v_mfma_f32_16x16x32_f16 v[86:89], v[200:203], v[188:191], v[86:89]
	v_mfma_f32_16x16x32_f16 v[82:85], v[220:223], v[188:191], v[82:85]
	v_mfma_f32_16x16x32_f16 v[122:125], v[200:203], v[180:183], v[122:125]
	s_barrier
	v_lshl_add_u64 v[192:193], s[48:49], 0, v[0:1]
	s_mov_b32 m0, s0
	v_lshl_add_u64 v[212:213], s[48:49], 0, v[162:163]
	global_load_lds_dwordx4 v[192:193], off
	s_add_i32 m0, s0, 0x2000
	s_nop 0
	global_load_lds_dwordx4 v[212:213], off
	s_mov_b32 m0, s81
	v_lshl_add_u64 v[214:215], s[26:27], 0, v[166:167]
	ds_read_b128 v[90:93], v195 offset:16384
	ds_read_b128 v[94:97], v195 offset:17408
	ds_read_b128 v[98:101], v195 offset:18432
	ds_read_b128 v[102:105], v195 offset:19456
	ds_read_b128 v[176:179], v195 offset:20480
	ds_read_b128 v[180:183], v195 offset:21504
	ds_read_b128 v[184:187], v195 offset:22528
	ds_read_b128 v[188:191], v195 offset:23552
	global_load_lds_dwordx4 v[214:215], off
	v_lshl_add_u64 v[216:217], s[26:27], 0, v[164:165]
	s_mov_b32 m0, s82
	s_nop 0
	global_load_lds_dwordx4 v[216:217], off
	s_waitcnt vmcnt(6) lgkmcnt(0)
	s_barrier
	v_mfma_f32_16x16x32_f16 v[62:65], v[66:69], v[90:93], v[62:65]
	v_mfma_f32_16x16x32_f16 v[58:61], v[74:77], v[90:93], v[58:61]
	v_mfma_f32_16x16x32_f16 v[46:49], v[66:69], v[98:101], v[46:49]
	v_mfma_f32_16x16x32_f16 v[38:41], v[74:77], v[98:101], v[38:41]
	v_mfma_f32_16x16x32_f16 v[30:33], v[66:69], v[176:179], v[30:33]
	v_mfma_f32_16x16x32_f16 v[22:25], v[74:77], v[176:179], v[22:25]
	v_mfma_f32_16x16x32_f16 v[14:17], v[66:69], v[184:187], v[14:17]
	v_mfma_f32_16x16x32_f16 v[10:13], v[74:77], v[184:187], v[10:13]
	v_mfma_f32_16x16x32_f16 v[62:65], v[70:73], v[94:97], v[62:65]
	v_mfma_f32_16x16x32_f16 v[58:61], v[78:81], v[94:97], v[58:61]
	v_mfma_f32_16x16x32_f16 v[46:49], v[70:73], v[102:105], v[46:49]
	v_mfma_f32_16x16x32_f16 v[38:41], v[78:81], v[102:105], v[38:41]
	v_mfma_f32_16x16x32_f16 v[30:33], v[70:73], v[180:183], v[30:33]
	v_mfma_f32_16x16x32_f16 v[22:25], v[78:81], v[180:183], v[22:25]
	v_mfma_f32_16x16x32_f16 v[14:17], v[70:73], v[188:191], v[14:17]
	v_mfma_f32_16x16x32_f16 v[10:13], v[78:81], v[188:191], v[10:13]
	v_mfma_f32_16x16x32_f16 v[54:57], v[196:199], v[90:93], v[54:57]
	v_mfma_f32_16x16x32_f16 v[50:53], v[204:207], v[90:93], v[50:53]
	v_mfma_f32_16x16x32_f16 v[42:45], v[196:199], v[98:101], v[42:45]
	v_mfma_f32_16x16x32_f16 v[34:37], v[204:207], v[98:101], v[34:37]
	v_mfma_f32_16x16x32_f16 v[26:29], v[196:199], v[176:179], v[26:29]
	v_mfma_f32_16x16x32_f16 v[18:21], v[204:207], v[176:179], v[18:21]
	v_mfma_f32_16x16x32_f16 v[6:9], v[196:199], v[184:187], v[6:9]
	v_mfma_f32_16x16x32_f16 v[2:5], v[204:207], v[184:187], v[2:5]
	v_mfma_f32_16x16x32_f16 v[54:57], v[200:203], v[94:97], v[54:57]
	v_mfma_f32_16x16x32_f16 v[50:53], v[220:223], v[94:97], v[50:53]
	v_mfma_f32_16x16x32_f16 v[42:45], v[200:203], v[102:105], v[42:45]
	v_mfma_f32_16x16x32_f16 v[34:37], v[220:223], v[102:105], v[34:37]
	v_mfma_f32_16x16x32_f16 v[26:29], v[200:203], v[180:183], v[26:29]
	v_mfma_f32_16x16x32_f16 v[18:21], v[220:223], v[180:183], v[18:21]
	v_mfma_f32_16x16x32_f16 v[6:9], v[200:203], v[188:191], v[6:9]
	v_mfma_f32_16x16x32_f16 v[2:5], v[220:223], v[188:191], v[2:5]
	s_barrier
; #define PG8_STAGE(bufoff, gbase, voff) do { _Pragma("unroll") for (int _i = 0; _i < 2; ++_i) \
;         __builtin_amdgcn_global_load_lds((const unsigned*)((const char*)(gbase) + (voff)[_i]), (LAS unsigned*)(lds + (bufoff) + ldsw + _i * 8192), 16, 0, 0); } while (0)
; #define PG8_LDA(dst, b, h) do { _Pragma("unroll") for (int m = 0; m < 4; ++m) _Pragma("unroll") for (int k = 0; k < 2; ++k) dst[m][k] = *(const LAS h16x8*)(lds + PG8_SA(b, h) + aoff + m * 2048 + k * 1024); } while (0)
; #define PG8_LDB(dst, b, h) do { _Pragma("unroll") for (int n = 0; n < 2; ++n) _Pragma("unroll") for (int k = 0; k < 2; ++k) dst[n][k] = *(const LAS h16x8*)(lds + PG8_SB(b, h) + boff + n * 2048 + k * 1024); } while (0)
; #define PG8_MMA(ai, bj, At, Bt_) do { __builtin_amdgcn_s_setprio(1); _Pragma("unroll") for (int m = 0; m < 4; ++m) _Pragma("unroll") for (int n = 0; n < 2; ++n) _Pragma("unroll") for (int k = 0; k < 2; ++k) \
;         acc[ai][bj][m][n] = __builtin_amdgcn_mfma_f32_16x16x32_f16(Bt_[n][k], At[m][k], acc[ai][bj][m][n], 0, 0, 0); __builtin_amdgcn_s_setprio(0); } while (0)
; #define PG8_WAIT_V(n) asm volatile("s_waitcnt vmcnt(" #n ")" ::: "memory")
; #define PG8_WAIT_L(n) asm volatile("s_waitcnt lgkmcnt(" #n ")" ::: "memory")
; #define PG8_BAR __builtin_amdgcn_s_barrier()
; #define PG8_SCHED __builtin_amdgcn_sched_barrier(0)
; template <class Epi, class AMap>
; __device__ __forceinline__ void gemm_phase(LAS unsigned char* lds, const AMap am, const int lda, const h16* Bt, const int ldb, const int M, const int N, const int K, const Epi& E) {
;     ...
;             PG8_STAGE(PG8_SB(0, 1), b2 + hstepB, voffB);
;             PG8_WAIT_V(6); PG8_BAR; PG8_MMA(1, 1, At, B1); PG8_BAR;
;             PG8_LDB(B0, 1, 0); PG8_SCHED; PG8_LDA(At, 1, 0); PG8_STAGE(PG8_SA(0, 1), a2 + hstepA, voffA);
;             PG8_WAIT_L(8); PG8_BAR; PG8_WAIT_L(0); PG8_MMA(0, 0, At, B0); PG8_BAR; PG8_SCHED;
;             PG8_LDB(B1, 1, 1); PG8_STAGE(PG8_SB(1, 0), b3, voffB);
;             PG8_BAR; PG8_WAIT_L(0); PG8_MMA(0, 1, At, B1); PG8_BAR;
	s_add_u32 s0, s48, 0x80000
	s_addc_u32 s1, s49, 0
	s_add_i32 s65, s65, s64
	v_lshl_add_u64 v[224:225], s[0:1], 0, v[0:1]
	s_mov_b32 m0, s65
	s_nop 0
	global_load_lds_dwordx4 v[224:225], off
	v_lshl_add_u64 v[224:225], s[0:1], 0, v[162:163]
	s_add_i32 m0, s65, 0x2000
	s_nop 0
	global_load_lds_dwordx4 v[224:225], off
	s_add_i32 s65, 0, 0x18000
	v_add_u32_e32 v226, s65, v169
	ds_read_b128 v[66:69], v226
	ds_read_b128 v[70:73], v226 offset:1024
	ds_read_b128 v[74:77], v226 offset:2048
	ds_read_b128 v[78:81], v226 offset:3072
	s_add_u32 s0, s26, 0x80000
	s_addc_u32 s1, s27, 0
	s_mov_b32 m0, s83
	v_lshl_add_u64 v[224:225], s[0:1], 0, v[166:167]
	ds_read_b128 v[90:93], v195 offset:32768
	ds_read_b128 v[94:97], v195 offset:33792
	ds_read_b128 v[98:101], v195 offset:34816
	ds_read_b128 v[102:105], v195 offset:35840
	ds_read_b128 v[176:179], v195 offset:36864
	ds_read_b128 v[180:183], v195 offset:37888
	ds_read_b128 v[184:187], v195 offset:38912
	ds_read_b128 v[188:191], v195 offset:39936
	global_load_lds_dwordx4 v[224:225], off
	v_lshl_add_u64 v[224:225], s[0:1], 0, v[164:165]
	s_mov_b32 m0, s50
	s_nop 0
	global_load_lds_dwordx4 v[224:225], off
	s_waitcnt lgkmcnt(11)
	s_add_i32 s26, 0, 0x1c000
	v_add_u32_e32 v226, s26, v169
	s_add_i32 s0, s65, s64
	ds_read_b128 v[196:199], v226
	ds_read_b128 v[200:203], v226 offset:1024
	ds_read_b128 v[204:207], v226 offset:2048
	ds_read_b128 v[220:223], v226 offset:3072
	s_waitcnt vmcnt(8) lgkmcnt(0)
	s_barrier
	v_mfma_f32_16x16x32_f16 v[158:161], v[66:69], v[90:93], v[158:161]
	v_mfma_f32_16x16x32_f16 v[158:161], v[70:73], v[94:97], v[158:161]
	v_mfma_f32_16x16x32_f16 v[154:157], v[74:77], v[90:93], v[154:157]
	v_mfma_f32_16x16x32_f16 v[154:157], v[78:81], v[94:97], v[154:157]
	v_mfma_f32_16x16x32_f16 v[142:145], v[66:69], v[98:101], v[142:145]
	v_mfma_f32_16x16x32_f16 v[134:137], v[74:77], v[98:101], v[134:137]
	v_mfma_f32_16x16x32_f16 v[126:129], v[66:69], v[176:179], v[126:129]
	v_mfma_f32_16x16x32_f16 v[118:121], v[74:77], v[176:179], v[118:121]
	v_mfma_f32_16x16x32_f16 v[110:113], v[66:69], v[184:187], v[110:113]
	v_mfma_f32_16x16x32_f16 v[106:109], v[74:77], v[184:187], v[106:109]
	v_mfma_f32_16x16x32_f16 v[142:145], v[70:73], v[102:105], v[142:145]
	v_mfma_f32_16x16x32_f16 v[134:137], v[78:81], v[102:105], v[134:137]
	v_mfma_f32_16x16x32_f16 v[126:129], v[70:73], v[180:183], v[126:129]
	v_mfma_f32_16x16x32_f16 v[118:121], v[78:81], v[180:183], v[118:121]
	v_mfma_f32_16x16x32_f16 v[110:113], v[70:73], v[188:191], v[110:113]
	v_mfma_f32_16x16x32_f16 v[106:109], v[78:81], v[188:191], v[106:109]
	v_mfma_f32_16x16x32_f16 v[146:149], v[204:207], v[90:93], v[146:149]
	v_mfma_f32_16x16x32_f16 v[150:153], v[196:199], v[90:93], v[150:153]
	v_mfma_f32_16x16x32_f16 v[146:149], v[220:223], v[94:97], v[146:149]
	v_mfma_f32_16x16x32_f16 v[138:141], v[196:199], v[98:101], v[138:141]
	v_mfma_f32_16x16x32_f16 v[150:153], v[200:203], v[94:97], v[150:153]
	v_mfma_f32_16x16x32_f16 v[138:141], v[200:203], v[102:105], v[138:141]
	v_mfma_f32_16x16x32_f16 v[130:133], v[204:207], v[98:101], v[130:133]
	v_mfma_f32_16x16x32_f16 v[130:133], v[220:223], v[102:105], v[130:133]
	v_mfma_f32_16x16x32_f16 v[122:125], v[196:199], v[176:179], v[122:125]
	v_mfma_f32_16x16x32_f16 v[122:125], v[200:203], v[180:183], v[122:125]
	v_mfma_f32_16x16x32_f16 v[114:117], v[204:207], v[176:179], v[114:117]
	v_mfma_f32_16x16x32_f16 v[86:89], v[196:199], v[184:187], v[86:89]
	v_mfma_f32_16x16x32_f16 v[82:85], v[204:207], v[184:187], v[82:85]
	v_mfma_f32_16x16x32_f16 v[114:117], v[220:223], v[180:183], v[114:117]
	v_mfma_f32_16x16x32_f16 v[86:89], v[200:203], v[188:191], v[86:89]
	v_mfma_f32_16x16x32_f16 v[82:85], v[220:223], v[188:191], v[82:85]
	s_barrier
; #define PG8_STAGE(bufoff, gbase, voff) do { _Pragma("unroll") for (int _i = 0; _i < 2; ++_i) \
;         __builtin_amdgcn_global_load_lds((const unsigned*)((const char*)(gbase) + (voff)[_i]), (LAS unsigned*)(lds + (bufoff) + ldsw + _i * 8192), 16, 0, 0); } while (0)
; #define PG8_LDA(dst, b, h) do { _Pragma("unroll") for (int m = 0; m < 4; ++m) _Pragma("unroll") for (int k = 0; k < 2; ++k) dst[m][k] = *(const LAS h16x8*)(lds + PG8_SA(b, h) + aoff + m * 2048 + k * 1024); } while (0)
; #define PG8_LDB(dst, b, h) do { _Pragma("unroll") for (int n = 0; n < 2; ++n) _Pragma("unroll") for (int k = 0; k < 2; ++k) dst[n][k] = *(const LAS h16x8*)(lds + PG8_SB(b, h) + boff + n * 2048 + k * 1024); } while (0)
; #define PG8_MMA(ai, bj, At, Bt_) do { __builtin_amdgcn_s_setprio(1); _Pragma("unroll") for (int m = 0; m < 4; ++m) _Pragma("unroll") for (int n = 0; n < 2; ++n) _Pragma("unroll") for (int k = 0; k < 2; ++k) \
;         acc[ai][bj][m][n] = __builtin_amdgcn_mfma_f32_16x16x32_f16(Bt_[n][k], At[m][k], acc[ai][bj][m][n], 0, 0, 0); __builtin_amdgcn_s_setprio(0); } while (0)
; #define PG8_WAIT_V(n) asm volatile("s_waitcnt vmcnt(" #n ")" ::: "memory")
; #define PG8_WAIT_L(n) asm volatile("s_waitcnt lgkmcnt(" #n ")" ::: "memory")
; #define PG8_BAR __builtin_amdgcn_s_barrier()
; #define PG8_SCHED __builtin_amdgcn_sched_barrier(0)
; template <class Epi, class AMap>
; __device__ __forceinline__ void gemm_phase(LAS unsigned char* lds, const AMap am, const int lda, const h16* Bt, const int ldb, const int M, const int N, const int K, const Epi& E) {
;     ...
;             PG8_LDB(B1, 1, 1); PG8_STAGE(PG8_SB(1, 0), b3, voffB);
;             PG8_BAR; PG8_WAIT_L(0); PG8_MMA(0, 1, At, B1); PG8_BAR;
;             PG8_LDA(At, 1, 1); PG8_STAGE(PG8_SA(1, 0), a3, voffA);
;             PG8_BAR; PG8_WAIT_L(0); PG8_MMA(1, 0, At, B0); PG8_BAR; PG8_SCHED;
;             PG8_STAGE(PG8_SB(1, 1), b3 + hstepB, voffB);
;             PG8_WAIT_V(6); PG8_BAR; PG8_MMA(1, 1, At, B1); PG8_BAR;
;         }
;     ...
;     if (wr == 0) PG8_BAR;
	v_lshl_add_u64 v[224:225], v[192:193], 0, s[92:93]
	s_mov_b32 m0, s0
	s_nop 0
	global_load_lds_dwordx4 v[224:225], off
	v_lshl_add_u64 v[224:225], v[212:213], 0, s[92:93]
	s_add_i32 m0, s0, 0x2000
	s_nop 0
	global_load_lds_dwordx4 v[224:225], off
	s_mov_b32 m0, s89
	v_lshl_add_u64 v[192:193], v[214:215], 0, s[92:93]
	ds_read_b128 v[90:93], v195 offset:49152
	ds_read_b128 v[94:97], v195 offset:50176
	ds_read_b128 v[98:101], v195 offset:51200
	ds_read_b128 v[102:105], v195 offset:52224
	ds_read_b128 v[176:179], v195 offset:53248
	ds_read_b128 v[180:183], v195 offset:54272
	ds_read_b128 v[184:187], v195 offset:55296
	ds_read_b128 v[188:191], v195 offset:56320
	global_load_lds_dwordx4 v[192:193], off
	v_lshl_add_u64 v[192:193], v[216:217], 0, s[92:93]
	s_mov_b32 m0, s35
	s_nop 0
	global_load_lds_dwordx4 v[192:193], off
	s_add_u32 s0, s48, 0x80080
	s_addc_u32 s1, s49, 0
	s_add_i32 s26, s26, s64
	v_lshl_add_u64 v[224:225], s[0:1], 0, v[0:1]
	s_mov_b32 m0, s26
	s_nop 0
	global_load_lds_dwordx4 v[224:225], off
	v_lshl_add_u64 v[224:225], s[0:1], 0, v[162:163]
	s_add_i32 m0, s26, 0x2000
	s_nop 0
	global_load_lds_dwordx4 v[224:225], off
	s_add_i32 s60, s60, 2
	s_add_u32 vcc_lo, vcc_lo, 0x100
	s_addc_u32 vcc_hi, vcc_hi, 0
	s_add_u32 s21, s21, 0x100
	s_addc_u32 s66, s66, 0
	s_cmp_gt_u32 s60, 29
	s_waitcnt vmcnt(8) lgkmcnt(0)
	s_barrier
	v_mfma_f32_16x16x32_f16 v[62:65], v[66:69], v[90:93], v[62:65]
	v_mfma_f32_16x16x32_f16 v[58:61], v[74:77], v[90:93], v[58:61]
	v_mfma_f32_16x16x32_f16 v[46:49], v[66:69], v[98:101], v[46:49]
	v_mfma_f32_16x16x32_f16 v[38:41], v[74:77], v[98:101], v[38:41]
	v_mfma_f32_16x16x32_f16 v[30:33], v[66:69], v[176:179], v[30:33]
	v_mfma_f32_16x16x32_f16 v[22:25], v[74:77], v[176:179], v[22:25]
	v_mfma_f32_16x16x32_f16 v[14:17], v[66:69], v[184:187], v[14:17]
	v_mfma_f32_16x16x32_f16 v[10:13], v[74:77], v[184:187], v[10:13]
	v_mfma_f32_16x16x32_f16 v[62:65], v[70:73], v[94:97], v[62:65]
	v_mfma_f32_16x16x32_f16 v[58:61], v[78:81], v[94:97], v[58:61]
	v_mfma_f32_16x16x32_f16 v[46:49], v[70:73], v[102:105], v[46:49]
	v_mfma_f32_16x16x32_f16 v[38:41], v[78:81], v[102:105], v[38:41]
	v_mfma_f32_16x16x32_f16 v[30:33], v[70:73], v[180:183], v[30:33]
	v_mfma_f32_16x16x32_f16 v[22:25], v[78:81], v[180:183], v[22:25]
	v_mfma_f32_16x16x32_f16 v[14:17], v[70:73], v[188:191], v[14:17]
	v_mfma_f32_16x16x32_f16 v[10:13], v[78:81], v[188:191], v[10:13]
	v_mfma_f32_16x16x32_f16 v[54:57], v[196:199], v[90:93], v[54:57]
	v_mfma_f32_16x16x32_f16 v[50:53], v[204:207], v[90:93], v[50:53]
	v_mfma_f32_16x16x32_f16 v[42:45], v[196:199], v[98:101], v[42:45]
	v_mfma_f32_16x16x32_f16 v[34:37], v[204:207], v[98:101], v[34:37]
	v_mfma_f32_16x16x32_f16 v[26:29], v[196:199], v[176:179], v[26:29]
	v_mfma_f32_16x16x32_f16 v[18:21], v[204:207], v[176:179], v[18:21]
	v_mfma_f32_16x16x32_f16 v[6:9], v[196:199], v[184:187], v[6:9]
	v_mfma_f32_16x16x32_f16 v[2:5], v[204:207], v[184:187], v[2:5]
	v_mfma_f32_16x16x32_f16 v[54:57], v[200:203], v[94:97], v[54:57]
	v_mfma_f32_16x16x32_f16 v[50:53], v[220:223], v[94:97], v[50:53]
	v_mfma_f32_16x16x32_f16 v[42:45], v[200:203], v[102:105], v[42:45]
	v_mfma_f32_16x16x32_f16 v[34:37], v[220:223], v[102:105], v[34:37]
	v_mfma_f32_16x16x32_f16 v[26:29], v[200:203], v[180:183], v[26:29]
	v_mfma_f32_16x16x32_f16 v[18:21], v[220:223], v[180:183], v[18:21]
	v_mfma_f32_16x16x32_f16 v[6:9], v[200:203], v[188:191], v[6:9]
	v_mfma_f32_16x16x32_f16 v[2:5], v[220:223], v[188:191], v[2:5]
	s_barrier
	s_cbranch_scc0 .LBB0_92
	s_cmpk_gt_u32 s10, 0xff
	s_cbranch_scc1 .Lgx1
	s_barrier

; #define PG8_STAGE(bufoff, gbase, voff) do { _Pragma("unroll") for (int _i = 0; _i < 2; ++_i) \
;         __builtin_amdgcn_global_load_lds((const unsigned*)((const char*)(gbase) + (voff)[_i]), (LAS unsigned*)(lds + (bufoff) + ldsw + _i * 8192), 16, 0, 0); } while (0)
; #define PG8_LDA(dst, b, h) do { _Pragma("unroll") for (int m = 0; m < 4; ++m) _Pragma("unroll") for (int k = 0; k < 2; ++k) dst[m][k] = *(const LAS h16x8*)(lds + PG8_SA(b, h) + aoff + m * 2048 + k * 1024); } while (0)
; #define PG8_LDB(dst, b, h) do { _Pragma("unroll") for (int n = 0; n < 2; ++n) _Pragma("unroll") for (int k = 0; k < 2; ++k) dst[n][k] = *(const LAS h16x8*)(lds + PG8_SB(b, h) + boff + n * 2048 + k * 1024); } while (0)
; #define PG8_MMA(ai, bj, At, Bt_) do { __builtin_amdgcn_s_setprio(1); _Pragma("unroll") for (int m = 0; m < 4; ++m) _Pragma("unroll") for (int n = 0; n < 2; ++n) _Pragma("unroll") for (int k = 0; k < 2; ++k) \
;         acc[ai][bj][m][n] = __builtin_amdgcn_mfma_f32_16x16x32_f16(Bt_[n][k], At[m][k], acc[ai][bj][m][n], 0, 0, 0); __builtin_amdgcn_s_setprio(0); } while (0)
; #define PG8_WAIT_V(n) asm volatile("s_waitcnt vmcnt(" #n ")" ::: "memory")
; template <class Epi, class AMap>
; __device__ __forceinline__ void gemm_phase(LAS unsigned char* lds, const AMap am, const int lda, const h16* Bt, const int ldb, const int M, const int N, const int K, const Epi& E) {
;     ...
;         for (int t = 0; t < nt; t += 2) {
;             const bool last = (t == nt - 2);
;             const char* a1 = cA + (size_t)(t + 1) * kstep;
;             const char* a2 = last ? nA : cA + (size_t)(t + 2) * kstep; const char* b2 = last ? nB : cB + (size_t)(t + 2) * kstep;
;             const char* a3 = a2 + kstep; const char* b3 = b2 + kstep;
;             PG8_LDB(B0, 0, 0); PG8_SCHED; PG8_LDA(At, 0, 0); PG8_STAGE(PG8_SA(1, 1), a1 + hstepA, voffA);
;             PG8_WAIT_L(8); PG8_BAR; PG8_WAIT_L(0); PG8_MMA(0, 0, At, B0); PG8_BAR; PG8_SCHED;
;             PG8_LDB(B1, 0, 1); PG8_STAGE(PG8_SB(0, 0), b2, voffB);
;             PG8_BAR; PG8_WAIT_L(0); PG8_MMA(0, 1, At, B1); PG8_BAR;
;             PG8_LDA(At, 0, 1); PG8_STAGE(PG8_SA(0, 0), a2, voffA);
;             PG8_BAR; PG8_WAIT_L(0); PG8_MMA(1, 0, At, B0); PG8_BAR; PG8_SCHED;
;             PG8_STAGE(PG8_SB(0, 1), b2 + hstepB, voffB);
;             PG8_WAIT_V(6); PG8_BAR; PG8_MMA(1, 1, At, B1); PG8_BAR;
.LBB0_147:
	s_add_u32 s46, s26, 0xfff80080
	s_addc_u32 s47, s27, -1
	s_add_i32 s60, 0, 0x10000
	v_add_u32_e32 v144, s60, v147
	ds_read_b128 v[140:143], v144
	ds_read_b128 v[150:153], v144 offset:1024
	ds_read_b128 v[154:157], v144 offset:2048
	ds_read_b128 v[158:161], v144 offset:3072
	s_cmp_eq_u32 s51, 28
	s_cselect_b32 s49, s41, s47
	s_cselect_b32 s48, s29, s46
	s_cselect_b32 s47, s1, s50
	s_cselect_b32 s46, s20, s21
	v_lshl_add_u64 v[144:145], s[26:27], 0, v[136:137]
	s_add_i32 m0, s23, 0xc000
	ds_read_b128 v[162:165], v149
	ds_read_b128 v[166:169], v149 offset:1024
	ds_read_b128 v[170:173], v149 offset:2048
	ds_read_b128 v[174:177], v149 offset:3072
	ds_read_b128 v[178:181], v149 offset:4096
	ds_read_b128 v[182:185], v149 offset:5120
	ds_read_b128 v[186:189], v149 offset:6144
	ds_read_b128 v[190:193], v149 offset:7168
	global_load_lds_dwordx4 v[144:145], off
	v_lshl_add_u64 v[144:145], s[26:27], 0, v[138:139]
	s_add_i32 m0, s23, 0xe000
	s_nop 0
	global_load_lds_dwordx4 v[144:145], off
	s_waitcnt lgkmcnt(11)
	s_add_i32 s66, 0, 0x14000
	v_add_u32_e32 v144, s66, v147
	s_add_i32 s60, s60, s64
	ds_read_b128 v[194:197], v144
	ds_read_b128 v[198:201], v144 offset:1024
	ds_read_b128 v[202:205], v144 offset:2048
	ds_read_b128 v[220:223], v144 offset:3072
	s_waitcnt vmcnt(8) lgkmcnt(0)
	s_barrier
	v_mfma_f32_16x16x32_f16 v[126:129], v[140:143], v[162:165], v[126:129]
	v_mfma_f32_16x16x32_f16 v[122:125], v[154:157], v[162:165], v[122:125]
	v_mfma_f32_16x16x32_f16 v[110:113], v[140:143], v[170:173], v[110:113]
	v_mfma_f32_16x16x32_f16 v[106:109], v[154:157], v[170:173], v[106:109]
	v_mfma_f32_16x16x32_f16 v[94:97], v[140:143], v[178:181], v[94:97]
	v_mfma_f32_16x16x32_f16 v[90:93], v[154:157], v[178:181], v[90:93]
	v_mfma_f32_16x16x32_f16 v[78:81], v[140:143], v[186:189], v[78:81]
	v_mfma_f32_16x16x32_f16 v[74:77], v[154:157], v[186:189], v[74:77]
	v_mfma_f32_16x16x32_f16 v[126:129], v[150:153], v[166:169], v[126:129]
	v_mfma_f32_16x16x32_f16 v[122:125], v[158:161], v[166:169], v[122:125]
	v_mfma_f32_16x16x32_f16 v[110:113], v[150:153], v[174:177], v[110:113]
	v_mfma_f32_16x16x32_f16 v[106:109], v[158:161], v[174:177], v[106:109]
	v_mfma_f32_16x16x32_f16 v[94:97], v[150:153], v[182:185], v[94:97]
	v_mfma_f32_16x16x32_f16 v[90:93], v[158:161], v[182:185], v[90:93]
	v_mfma_f32_16x16x32_f16 v[78:81], v[150:153], v[190:193], v[78:81]
	v_mfma_f32_16x16x32_f16 v[74:77], v[158:161], v[190:193], v[74:77]
	v_mfma_f32_16x16x32_f16 v[118:121], v[194:197], v[162:165], v[118:121]
	v_mfma_f32_16x16x32_f16 v[114:117], v[202:205], v[162:165], v[114:117]
	v_mfma_f32_16x16x32_f16 v[102:105], v[194:197], v[170:173], v[102:105]
	v_mfma_f32_16x16x32_f16 v[98:101], v[202:205], v[170:173], v[98:101]
	v_mfma_f32_16x16x32_f16 v[86:89], v[194:197], v[178:181], v[86:89]
	v_mfma_f32_16x16x32_f16 v[82:85], v[202:205], v[178:181], v[82:85]
	v_mfma_f32_16x16x32_f16 v[70:73], v[194:197], v[186:189], v[70:73]
	v_mfma_f32_16x16x32_f16 v[66:69], v[202:205], v[186:189], v[66:69]
	v_mfma_f32_16x16x32_f16 v[118:121], v[198:201], v[166:169], v[118:121]
	v_mfma_f32_16x16x32_f16 v[114:117], v[220:223], v[166:169], v[114:117]
	v_mfma_f32_16x16x32_f16 v[102:105], v[198:201], v[174:177], v[102:105]
	v_mfma_f32_16x16x32_f16 v[98:101], v[220:223], v[174:177], v[98:101]
	v_mfma_f32_16x16x32_f16 v[86:89], v[198:201], v[182:185], v[86:89]
	v_mfma_f32_16x16x32_f16 v[82:85], v[220:223], v[182:185], v[82:85]
	v_mfma_f32_16x16x32_f16 v[70:73], v[198:201], v[190:193], v[70:73]
	v_mfma_f32_16x16x32_f16 v[66:69], v[220:223], v[190:193], v[66:69]
	s_barrier
	v_lshl_add_u64 v[144:145], s[46:47], 0, v[0:1]
	s_mov_b32 m0, s60
	v_lshl_add_u64 v[206:207], s[46:47], 0, v[134:135]
	global_load_lds_dwordx4 v[144:145], off
	s_add_i32 m0, s60, 0x2000
	s_nop 0
	global_load_lds_dwordx4 v[206:207], off
	s_mov_b32 m0, s23
	v_lshl_add_u64 v[212:213], s[48:49], 0, v[130:131]
	ds_read_b128 v[162:165], v149 offset:16384
	ds_read_b128 v[166:169], v149 offset:17408
	ds_read_b128 v[170:173], v149 offset:18432
	ds_read_b128 v[174:177], v149 offset:19456
	ds_read_b128 v[178:181], v149 offset:20480
	ds_read_b128 v[182:185], v149 offset:21504
	ds_read_b128 v[186:189], v149 offset:22528
	ds_read_b128 v[190:193], v149 offset:23552
	global_load_lds_dwordx4 v[212:213], off
	v_lshl_add_u64 v[214:215], s[48:49], 0, v[132:133]
	s_mov_b32 m0, s71
	s_nop 0
	global_load_lds_dwordx4 v[214:215], off
	s_waitcnt vmcnt(6) lgkmcnt(0)
	s_barrier
	v_mfma_f32_16x16x32_f16 v[62:65], v[140:143], v[162:165], v[62:65]
	v_mfma_f32_16x16x32_f16 v[58:61], v[154:157], v[162:165], v[58:61]
	v_mfma_f32_16x16x32_f16 v[46:49], v[140:143], v[170:173], v[46:49]
	v_mfma_f32_16x16x32_f16 v[42:45], v[154:157], v[170:173], v[42:45]
	v_mfma_f32_16x16x32_f16 v[30:33], v[140:143], v[178:181], v[30:33]
	v_mfma_f32_16x16x32_f16 v[26:29], v[154:157], v[178:181], v[26:29]
	v_mfma_f32_16x16x32_f16 v[14:17], v[140:143], v[186:189], v[14:17]
	v_mfma_f32_16x16x32_f16 v[10:13], v[154:157], v[186:189], v[10:13]
	v_mfma_f32_16x16x32_f16 v[62:65], v[150:153], v[166:169], v[62:65]
	v_mfma_f32_16x16x32_f16 v[58:61], v[158:161], v[166:169], v[58:61]
	v_mfma_f32_16x16x32_f16 v[46:49], v[150:153], v[174:177], v[46:49]
	v_mfma_f32_16x16x32_f16 v[42:45], v[158:161], v[174:177], v[42:45]
	v_mfma_f32_16x16x32_f16 v[30:33], v[150:153], v[182:185], v[30:33]
	v_mfma_f32_16x16x32_f16 v[26:29], v[158:161], v[182:185], v[26:29]
	v_mfma_f32_16x16x32_f16 v[14:17], v[150:153], v[190:193], v[14:17]
	v_mfma_f32_16x16x32_f16 v[10:13], v[158:161], v[190:193], v[10:13]
	v_mfma_f32_16x16x32_f16 v[54:57], v[194:197], v[162:165], v[54:57]
	v_mfma_f32_16x16x32_f16 v[50:53], v[202:205], v[162:165], v[50:53]
	v_mfma_f32_16x16x32_f16 v[38:41], v[194:197], v[170:173], v[38:41]
	v_mfma_f32_16x16x32_f16 v[34:37], v[202:205], v[170:173], v[34:37]
	v_mfma_f32_16x16x32_f16 v[22:25], v[194:197], v[178:181], v[22:25]
	v_mfma_f32_16x16x32_f16 v[18:21], v[202:205], v[178:181], v[18:21]
	v_mfma_f32_16x16x32_f16 v[6:9], v[194:197], v[186:189], v[6:9]
	v_mfma_f32_16x16x32_f16 v[2:5], v[202:205], v[186:189], v[2:5]
	v_mfma_f32_16x16x32_f16 v[54:57], v[198:201], v[166:169], v[54:57]
	v_mfma_f32_16x16x32_f16 v[50:53], v[220:223], v[166:169], v[50:53]
	v_mfma_f32_16x16x32_f16 v[38:41], v[198:201], v[174:177], v[38:41]
	v_mfma_f32_16x16x32_f16 v[34:37], v[220:223], v[174:177], v[34:37]
	v_mfma_f32_16x16x32_f16 v[22:25], v[198:201], v[182:185], v[22:25]
	v_mfma_f32_16x16x32_f16 v[18:21], v[220:223], v[182:185], v[18:21]
	v_mfma_f32_16x16x32_f16 v[6:9], v[198:201], v[190:193], v[6:9]
	v_mfma_f32_16x16x32_f16 v[2:5], v[220:223], v[190:193], v[2:5]
	s_barrier
; #define PG8_STAGE(bufoff, gbase, voff) do { _Pragma("unroll") for (int _i = 0; _i < 2; ++_i) \
;         __builtin_amdgcn_global_load_lds((const unsigned*)((const char*)(gbase) + (voff)[_i]), (LAS unsigned*)(lds + (bufoff) + ldsw + _i * 8192), 16, 0, 0); } while (0)
; #define PG8_LDA(dst, b, h) do { _Pragma("unroll") for (int m = 0; m < 4; ++m) _Pragma("unroll") for (int k = 0; k < 2; ++k) dst[m][k] = *(const LAS h16x8*)(lds + PG8_SA(b, h) + aoff + m * 2048 + k * 1024); } while (0)
; #define PG8_LDB(dst, b, h) do { _Pragma("unroll") for (int n = 0; n < 2; ++n) _Pragma("unroll") for (int k = 0; k < 2; ++k) dst[n][k] = *(const LAS h16x8*)(lds + PG8_SB(b, h) + boff + n * 2048 + k * 1024); } while (0)
; #define PG8_MMA(ai, bj, At, Bt_) do { __builtin_amdgcn_s_setprio(1); _Pragma("unroll") for (int m = 0; m < 4; ++m) _Pragma("unroll") for (int n = 0; n < 2; ++n) _Pragma("unroll") for (int k = 0; k < 2; ++k) \
;         acc[ai][bj][m][n] = __builtin_amdgcn_mfma_f32_16x16x32_f16(Bt_[n][k], At[m][k], acc[ai][bj][m][n], 0, 0, 0); __builtin_amdgcn_s_setprio(0); } while (0)
; #define PG8_WAIT_V(n) asm volatile("s_waitcnt vmcnt(" #n ")" ::: "memory")
; #define PG8_WAIT_L(n) asm volatile("s_waitcnt lgkmcnt(" #n ")" ::: "memory")
; #define PG8_BAR __builtin_amdgcn_s_barrier()
; #define PG8_SCHED __builtin_amdgcn_sched_barrier(0)
; template <class Epi, class AMap>
; __device__ __forceinline__ void gemm_phase(LAS unsigned char* lds, const AMap am, const int lda, const h16* Bt, const int ldb, const int M, const int N, const int K, const Epi& E) {
;     ...
;             PG8_STAGE(PG8_SB(0, 1), b2 + hstepB, voffB);
;             PG8_WAIT_V(6); PG8_BAR; PG8_MMA(1, 1, At, B1); PG8_BAR;
;             PG8_LDB(B0, 1, 0); PG8_SCHED; PG8_LDA(At, 1, 0); PG8_STAGE(PG8_SA(0, 1), a2 + hstepA, voffA);
;             PG8_WAIT_L(8); PG8_BAR; PG8_WAIT_L(0); PG8_MMA(0, 0, At, B0); PG8_BAR; PG8_SCHED;
;             PG8_LDB(B1, 1, 1); PG8_STAGE(PG8_SB(1, 0), b3, voffB);
;             PG8_BAR; PG8_WAIT_L(0); PG8_MMA(0, 1, At, B1); PG8_BAR;
	s_add_u32 s78, s46, 0x80000
	s_addc_u32 s79, s47, 0
	s_add_i32 s60, s66, s64
	v_lshl_add_u64 v[232:233], s[78:79], 0, v[0:1]
	s_mov_b32 m0, s60
	s_nop 0
	global_load_lds_dwordx4 v[232:233], off
	v_lshl_add_u64 v[232:233], s[78:79], 0, v[134:135]
	s_add_i32 m0, s60, 0x2000
	s_nop 0
	global_load_lds_dwordx4 v[232:233], off
	s_add_i32 s60, 0, 0x18000
	v_add_u32_e32 v234, s60, v147
	ds_read_b128 v[140:143], v234
	ds_read_b128 v[150:153], v234 offset:1024
	ds_read_b128 v[154:157], v234 offset:2048
	ds_read_b128 v[158:161], v234 offset:3072
	s_add_u32 s48, s48, 0x80000
	s_addc_u32 s49, s49, 0
	s_mov_b32 m0, s72
	v_lshl_add_u64 v[232:233], s[48:49], 0, v[130:131]
	ds_read_b128 v[162:165], v149 offset:32768
	ds_read_b128 v[166:169], v149 offset:33792
	ds_read_b128 v[170:173], v149 offset:34816
	ds_read_b128 v[174:177], v149 offset:35840
	ds_read_b128 v[178:181], v149 offset:36864
	ds_read_b128 v[182:185], v149 offset:37888
	ds_read_b128 v[186:189], v149 offset:38912
	ds_read_b128 v[190:193], v149 offset:39936
	global_load_lds_dwordx4 v[232:233], off
	v_lshl_add_u64 v[232:233], s[48:49], 0, v[132:133]
	s_mov_b32 m0, s73
	s_nop 0
	global_load_lds_dwordx4 v[232:233], off
	s_waitcnt lgkmcnt(11)
	s_add_i32 s48, 0, 0x1c000
	s_add_i32 s49, s60, s64
	v_add_u32_e32 v216, s48, v147
	v_lshl_add_u64 v[144:145], v[144:145], 0, s[92:93]
	s_mov_b32 m0, s49
	ds_read_b128 v[194:197], v216
	ds_read_b128 v[198:201], v216 offset:1024
	ds_read_b128 v[202:205], v216 offset:2048
	ds_read_b128 v[220:223], v216 offset:3072
	s_waitcnt vmcnt(8) lgkmcnt(0)
	s_barrier
	v_mfma_f32_16x16x32_f16 v[126:129], v[140:143], v[162:165], v[126:129]
	v_mfma_f32_16x16x32_f16 v[122:125], v[154:157], v[162:165], v[122:125]
	v_mfma_f32_16x16x32_f16 v[110:113], v[140:143], v[170:173], v[110:113]
	v_mfma_f32_16x16x32_f16 v[106:109], v[154:157], v[170:173], v[106:109]
	v_mfma_f32_16x16x32_f16 v[94:97], v[140:143], v[178:181], v[94:97]
	v_mfma_f32_16x16x32_f16 v[90:93], v[154:157], v[178:181], v[90:93]
	v_mfma_f32_16x16x32_f16 v[78:81], v[140:143], v[186:189], v[78:81]
	v_mfma_f32_16x16x32_f16 v[74:77], v[154:157], v[186:189], v[74:77]
	v_mfma_f32_16x16x32_f16 v[126:129], v[150:153], v[166:169], v[126:129]
	v_mfma_f32_16x16x32_f16 v[122:125], v[158:161], v[166:169], v[122:125]
	v_mfma_f32_16x16x32_f16 v[110:113], v[150:153], v[174:177], v[110:113]
	v_mfma_f32_16x16x32_f16 v[106:109], v[158:161], v[174:177], v[106:109]
	v_mfma_f32_16x16x32_f16 v[94:97], v[150:153], v[182:185], v[94:97]
	v_mfma_f32_16x16x32_f16 v[90:93], v[158:161], v[182:185], v[90:93]
	v_mfma_f32_16x16x32_f16 v[78:81], v[150:153], v[190:193], v[78:81]
	v_mfma_f32_16x16x32_f16 v[74:77], v[158:161], v[190:193], v[74:77]
	v_mfma_f32_16x16x32_f16 v[118:121], v[194:197], v[162:165], v[118:121]
	v_mfma_f32_16x16x32_f16 v[114:117], v[202:205], v[162:165], v[114:117]
	v_mfma_f32_16x16x32_f16 v[102:105], v[194:197], v[170:173], v[102:105]
	v_mfma_f32_16x16x32_f16 v[98:101], v[202:205], v[170:173], v[98:101]
	v_mfma_f32_16x16x32_f16 v[86:89], v[194:197], v[178:181], v[86:89]
	v_mfma_f32_16x16x32_f16 v[82:85], v[202:205], v[178:181], v[82:85]
	v_mfma_f32_16x16x32_f16 v[70:73], v[194:197], v[186:189], v[70:73]
	v_mfma_f32_16x16x32_f16 v[66:69], v[202:205], v[186:189], v[66:69]
	v_mfma_f32_16x16x32_f16 v[118:121], v[198:201], v[166:169], v[118:121]
	v_mfma_f32_16x16x32_f16 v[114:117], v[220:223], v[166:169], v[114:117]
	v_mfma_f32_16x16x32_f16 v[102:105], v[198:201], v[174:177], v[102:105]
	v_mfma_f32_16x16x32_f16 v[98:101], v[220:223], v[174:177], v[98:101]
	v_mfma_f32_16x16x32_f16 v[86:89], v[198:201], v[182:185], v[86:89]
	v_mfma_f32_16x16x32_f16 v[82:85], v[220:223], v[182:185], v[82:85]
	v_mfma_f32_16x16x32_f16 v[70:73], v[198:201], v[190:193], v[70:73]
	v_mfma_f32_16x16x32_f16 v[66:69], v[220:223], v[190:193], v[66:69]
	s_barrier
; #define PG8_STAGE(bufoff, gbase, voff) do { _Pragma("unroll") for (int _i = 0; _i < 2; ++_i) \
;         __builtin_amdgcn_global_load_lds((const unsigned*)((const char*)(gbase) + (voff)[_i]), (LAS unsigned*)(lds + (bufoff) + ldsw + _i * 8192), 16, 0, 0); } while (0)
; #define PG8_LDA(dst, b, h) do { _Pragma("unroll") for (int m = 0; m < 4; ++m) _Pragma("unroll") for (int k = 0; k < 2; ++k) dst[m][k] = *(const LAS h16x8*)(lds + PG8_SA(b, h) + aoff + m * 2048 + k * 1024); } while (0)
; #define PG8_LDB(dst, b, h) do { _Pragma("unroll") for (int n = 0; n < 2; ++n) _Pragma("unroll") for (int k = 0; k < 2; ++k) dst[n][k] = *(const LAS h16x8*)(lds + PG8_SB(b, h) + boff + n * 2048 + k * 1024); } while (0)
; #define PG8_MMA(ai, bj, At, Bt_) do { __builtin_amdgcn_s_setprio(1); _Pragma("unroll") for (int m = 0; m < 4; ++m) _Pragma("unroll") for (int n = 0; n < 2; ++n) _Pragma("unroll") for (int k = 0; k < 2; ++k) \
;         acc[ai][bj][m][n] = __builtin_amdgcn_mfma_f32_16x16x32_f16(Bt_[n][k], At[m][k], acc[ai][bj][m][n], 0, 0, 0); __builtin_amdgcn_s_setprio(0); } while (0)
; #define PG8_WAIT_V(n) asm volatile("s_waitcnt vmcnt(" #n ")" ::: "memory")
; #define PG8_WAIT_L(n) asm volatile("s_waitcnt lgkmcnt(" #n ")" ::: "memory")
; #define PG8_BAR __builtin_amdgcn_s_barrier()
; #define PG8_SCHED __builtin_amdgcn_sched_barrier(0)
; template <class Epi, class AMap>
; __device__ __forceinline__ void gemm_phase(LAS unsigned char* lds, const AMap am, const int lda, const h16* Bt, const int ldb, const int M, const int N, const int K, const Epi& E) {
;     ...
;             PG8_LDB(B1, 1, 1); PG8_STAGE(PG8_SB(1, 0), b3, voffB);
;             PG8_BAR; PG8_WAIT_L(0); PG8_MMA(0, 1, At, B1); PG8_BAR;
;             PG8_LDA(At, 1, 1); PG8_STAGE(PG8_SA(1, 0), a3, voffA);
;             PG8_BAR; PG8_WAIT_L(0); PG8_MMA(1, 0, At, B0); PG8_BAR; PG8_SCHED;
;             PG8_STAGE(PG8_SB(1, 1), b3 + hstepB, voffB);
;             PG8_WAIT_V(6); PG8_BAR; PG8_MMA(1, 1, At, B1); PG8_BAR;
;         }
;     ...
;     if (wr == 0) PG8_BAR;
	global_load_lds_dwordx4 v[144:145], off
	v_lshl_add_u64 v[144:145], v[206:207], 0, s[92:93]
	s_add_i32 m0, s49, 0x2000
	s_nop 0
	global_load_lds_dwordx4 v[144:145], off
	s_mov_b32 m0, s74
	v_lshl_add_u64 v[144:145], v[212:213], 0, s[92:93]
	ds_read_b128 v[162:165], v149 offset:49152
	ds_read_b128 v[166:169], v149 offset:50176
	ds_read_b128 v[170:173], v149 offset:51200
	ds_read_b128 v[174:177], v149 offset:52224
	ds_read_b128 v[178:181], v149 offset:53248
	ds_read_b128 v[182:185], v149 offset:54272
	ds_read_b128 v[186:189], v149 offset:55296
	ds_read_b128 v[190:193], v149 offset:56320
	global_load_lds_dwordx4 v[144:145], off
	v_lshl_add_u64 v[144:145], v[214:215], 0, s[92:93]
	s_mov_b32 m0, s75
	s_nop 0
	global_load_lds_dwordx4 v[144:145], off
	s_add_u32 s46, s46, 0x80080
	s_addc_u32 s47, s47, 0
	s_add_i32 s48, s48, s64
	v_lshl_add_u64 v[232:233], s[46:47], 0, v[0:1]
	s_mov_b32 m0, s48
	s_nop 0
	global_load_lds_dwordx4 v[232:233], off
	v_lshl_add_u64 v[232:233], s[46:47], 0, v[134:135]
	s_add_i32 m0, s48, 0x2000
	s_nop 0
	global_load_lds_dwordx4 v[232:233], off
	s_add_i32 s51, s51, 2
	s_add_u32 s26, s26, 0x100
	s_addc_u32 s27, s27, 0
	s_add_u32 s21, s21, 0x100
	s_addc_u32 s50, s50, 0
	s_cmp_gt_u32 s51, 29
	s_waitcnt vmcnt(8) lgkmcnt(0)
	s_barrier
	v_mfma_f32_16x16x32_f16 v[62:65], v[140:143], v[162:165], v[62:65]
	v_mfma_f32_16x16x32_f16 v[58:61], v[154:157], v[162:165], v[58:61]
	v_mfma_f32_16x16x32_f16 v[46:49], v[140:143], v[170:173], v[46:49]
	v_mfma_f32_16x16x32_f16 v[42:45], v[154:157], v[170:173], v[42:45]
	v_mfma_f32_16x16x32_f16 v[30:33], v[140:143], v[178:181], v[30:33]
	v_mfma_f32_16x16x32_f16 v[26:29], v[154:157], v[178:181], v[26:29]
	v_mfma_f32_16x16x32_f16 v[14:17], v[140:143], v[186:189], v[14:17]
	v_mfma_f32_16x16x32_f16 v[10:13], v[154:157], v[186:189], v[10:13]
	v_mfma_f32_16x16x32_f16 v[62:65], v[150:153], v[166:169], v[62:65]
	v_mfma_f32_16x16x32_f16 v[58:61], v[158:161], v[166:169], v[58:61]
	v_mfma_f32_16x16x32_f16 v[46:49], v[150:153], v[174:177], v[46:49]
	v_mfma_f32_16x16x32_f16 v[42:45], v[158:161], v[174:177], v[42:45]
	v_mfma_f32_16x16x32_f16 v[30:33], v[150:153], v[182:185], v[30:33]
	v_mfma_f32_16x16x32_f16 v[26:29], v[158:161], v[182:185], v[26:29]
	v_mfma_f32_16x16x32_f16 v[14:17], v[150:153], v[190:193], v[14:17]
	v_mfma_f32_16x16x32_f16 v[10:13], v[158:161], v[190:193], v[10:13]
	v_mfma_f32_16x16x32_f16 v[54:57], v[194:197], v[162:165], v[54:57]
	v_mfma_f32_16x16x32_f16 v[50:53], v[202:205], v[162:165], v[50:53]
	v_mfma_f32_16x16x32_f16 v[38:41], v[194:197], v[170:173], v[38:41]
	v_mfma_f32_16x16x32_f16 v[34:37], v[202:205], v[170:173], v[34:37]
	v_mfma_f32_16x16x32_f16 v[22:25], v[194:197], v[178:181], v[22:25]
	v_mfma_f32_16x16x32_f16 v[18:21], v[202:205], v[178:181], v[18:21]
	v_mfma_f32_16x16x32_f16 v[6:9], v[194:197], v[186:189], v[6:9]
	v_mfma_f32_16x16x32_f16 v[2:5], v[202:205], v[186:189], v[2:5]
	v_mfma_f32_16x16x32_f16 v[54:57], v[198:201], v[166:169], v[54:57]
	v_mfma_f32_16x16x32_f16 v[50:53], v[220:223], v[166:169], v[50:53]
	v_mfma_f32_16x16x32_f16 v[38:41], v[198:201], v[174:177], v[38:41]
	v_mfma_f32_16x16x32_f16 v[34:37], v[220:223], v[174:177], v[34:37]
	v_mfma_f32_16x16x32_f16 v[22:25], v[198:201], v[182:185], v[22:25]
	v_mfma_f32_16x16x32_f16 v[18:21], v[220:223], v[182:185], v[18:21]
	v_mfma_f32_16x16x32_f16 v[6:9], v[198:201], v[190:193], v[6:9]
	v_mfma_f32_16x16x32_f16 v[2:5], v[220:223], v[190:193], v[2:5]
	s_barrier
	s_cbranch_scc0 .LBB0_147
	s_cmpk_gt_u32 s62, 0xff
	s_cbranch_scc1 .Lgx2
	s_barrier

; #define PG8_STAGE(bufoff, gbase, voff) do { _Pragma("unroll") for (int _i = 0; _i < 2; ++_i) \
;         __builtin_amdgcn_global_load_lds((const unsigned*)((const char*)(gbase) + (voff)[_i]), (LAS unsigned*)(lds + (bufoff) + ldsw + _i * 8192), 16, 0, 0); } while (0)
; #define PG8_LDA(dst, b, h) do { _Pragma("unroll") for (int m = 0; m < 4; ++m) _Pragma("unroll") for (int k = 0; k < 2; ++k) dst[m][k] = *(const LAS h16x8*)(lds + PG8_SA(b, h) + aoff + m * 2048 + k * 1024); } while (0)
; #define PG8_LDB(dst, b, h) do { _Pragma("unroll") for (int n = 0; n < 2; ++n) _Pragma("unroll") for (int k = 0; k < 2; ++k) dst[n][k] = *(const LAS h16x8*)(lds + PG8_SB(b, h) + boff + n * 2048 + k * 1024); } while (0)
; #define PG8_MMA(ai, bj, At, Bt_) do { __builtin_amdgcn_s_setprio(1); _Pragma("unroll") for (int m = 0; m < 4; ++m) _Pragma("unroll") for (int n = 0; n < 2; ++n) _Pragma("unroll") for (int k = 0; k < 2; ++k) \
;         acc[ai][bj][m][n] = __builtin_amdgcn_mfma_f32_16x16x32_f16(Bt_[n][k], At[m][k], acc[ai][bj][m][n], 0, 0, 0); __builtin_amdgcn_s_setprio(0); } while (0)
; #define PG8_WAIT_V(n) asm volatile("s_waitcnt vmcnt(" #n ")" ::: "memory")
; template <class Epi, class AMap>
; __device__ __forceinline__ void gemm_phase(LAS unsigned char* lds, const AMap am, const int lda, const h16* Bt, const int ldb, const int M, const int N, const int K, const Epi& E) {
;     ...
;         for (int t = 0; t < nt; t += 2) {
;             const bool last = (t == nt - 2);
;             const char* a1 = cA + (size_t)(t + 1) * kstep;
;             const char* a2 = last ? nA : cA + (size_t)(t + 2) * kstep; const char* b2 = last ? nB : cB + (size_t)(t + 2) * kstep;
;             const char* a3 = a2 + kstep; const char* b3 = b2 + kstep;
;             PG8_LDB(B0, 0, 0); PG8_SCHED; PG8_LDA(At, 0, 0); PG8_STAGE(PG8_SA(1, 1), a1 + hstepA, voffA);
;             PG8_WAIT_L(8); PG8_BAR; PG8_WAIT_L(0); PG8_MMA(0, 0, At, B0); PG8_BAR; PG8_SCHED;
;             PG8_LDB(B1, 0, 1); PG8_STAGE(PG8_SB(0, 0), b2, voffB);
;             PG8_BAR; PG8_WAIT_L(0); PG8_MMA(0, 1, At, B1); PG8_BAR;
;             PG8_LDA(At, 0, 1); PG8_STAGE(PG8_SA(0, 0), a2, voffA);
;             PG8_BAR; PG8_WAIT_L(0); PG8_MMA(1, 0, At, B0); PG8_BAR; PG8_SCHED;
;             PG8_STAGE(PG8_SB(0, 1), b2 + hstepB, voffB);
;             PG8_WAIT_V(6); PG8_BAR; PG8_MMA(1, 1, At, B1); PG8_BAR;
.LBB0_268:
	s_add_u32 s42, s40, 0xfff80080
	s_addc_u32 s43, s41, -1
	s_add_i32 s45, 0, 0x10000
	v_add_u32_e32 v0, s45, v149
	ds_read_b128 v[142:145], v0
	ds_read_b128 v[154:157], v0 offset:1024
	ds_read_b128 v[158:161], v0 offset:2048
	ds_read_b128 v[162:165], v0 offset:3072
	s_cmp_eq_u32 s35, 28
	s_cselect_b32 s49, s23, s43
	s_cselect_b32 s48, s27, s42
	s_cselect_b32 s43, s1, s29
	s_cselect_b32 s42, s20, s21
	v_lshl_add_u64 v[146:147], s[40:41], 0, v[138:139]
	s_add_i32 m0, s72, 0xc000
	ds_read_b128 v[166:169], v153
	ds_read_b128 v[170:173], v153 offset:1024
	ds_read_b128 v[174:177], v153 offset:2048
	ds_read_b128 v[178:181], v153 offset:3072
	ds_read_b128 v[182:185], v153 offset:4096
	ds_read_b128 v[186:189], v153 offset:5120
	ds_read_b128 v[190:193], v153 offset:6144
	ds_read_b128 v[194:197], v153 offset:7168
	global_load_lds_dwordx4 v[146:147], off
	v_lshl_add_u64 v[146:147], s[40:41], 0, v[140:141]
	s_add_i32 m0, s72, 0xe000
	s_nop 0
	global_load_lds_dwordx4 v[146:147], off
	s_waitcnt lgkmcnt(11)
	s_add_i32 s60, 0, 0x14000
	s_add_i32 s45, s45, s65
	v_add_u32_e32 v0, s60, v149
	v_lshl_add_u64 v[146:147], s[42:43], 0, v[132:133]
	s_mov_b32 m0, s45
	ds_read_b128 v[198:201], v0
	ds_read_b128 v[202:205], v0 offset:1024
	ds_read_b128 v[220:223], v0 offset:2048
	ds_read_b128 v[224:227], v0 offset:3072
	s_waitcnt vmcnt(8) lgkmcnt(0)
	s_barrier
	v_mfma_f32_16x16x32_f16 v[126:129], v[142:145], v[166:169], v[126:129]
	v_mfma_f32_16x16x32_f16 v[122:125], v[158:161], v[166:169], v[122:125]
	v_mfma_f32_16x16x32_f16 v[110:113], v[142:145], v[174:177], v[110:113]
	v_mfma_f32_16x16x32_f16 v[106:109], v[158:161], v[174:177], v[106:109]
	v_mfma_f32_16x16x32_f16 v[94:97], v[142:145], v[182:185], v[94:97]
	v_mfma_f32_16x16x32_f16 v[90:93], v[158:161], v[182:185], v[90:93]
	v_mfma_f32_16x16x32_f16 v[78:81], v[142:145], v[190:193], v[78:81]
	v_mfma_f32_16x16x32_f16 v[74:77], v[158:161], v[190:193], v[74:77]
	v_mfma_f32_16x16x32_f16 v[126:129], v[154:157], v[170:173], v[126:129]
	v_mfma_f32_16x16x32_f16 v[122:125], v[162:165], v[170:173], v[122:125]
	v_mfma_f32_16x16x32_f16 v[110:113], v[154:157], v[178:181], v[110:113]
	v_mfma_f32_16x16x32_f16 v[106:109], v[162:165], v[178:181], v[106:109]
	v_mfma_f32_16x16x32_f16 v[94:97], v[154:157], v[186:189], v[94:97]
	v_mfma_f32_16x16x32_f16 v[90:93], v[162:165], v[186:189], v[90:93]
	v_mfma_f32_16x16x32_f16 v[78:81], v[154:157], v[194:197], v[78:81]
	v_mfma_f32_16x16x32_f16 v[74:77], v[162:165], v[194:197], v[74:77]
	v_mfma_f32_16x16x32_f16 v[118:121], v[198:201], v[166:169], v[118:121]
	v_mfma_f32_16x16x32_f16 v[114:117], v[220:223], v[166:169], v[114:117]
	v_mfma_f32_16x16x32_f16 v[102:105], v[198:201], v[174:177], v[102:105]
	v_mfma_f32_16x16x32_f16 v[98:101], v[220:223], v[174:177], v[98:101]
	v_mfma_f32_16x16x32_f16 v[86:89], v[198:201], v[182:185], v[86:89]
	v_mfma_f32_16x16x32_f16 v[82:85], v[220:223], v[182:185], v[82:85]
	v_mfma_f32_16x16x32_f16 v[70:73], v[198:201], v[190:193], v[70:73]
	v_mfma_f32_16x16x32_f16 v[66:69], v[220:223], v[190:193], v[66:69]
	v_mfma_f32_16x16x32_f16 v[118:121], v[202:205], v[170:173], v[118:121]
	v_mfma_f32_16x16x32_f16 v[114:117], v[224:227], v[170:173], v[114:117]
	v_mfma_f32_16x16x32_f16 v[102:105], v[202:205], v[178:181], v[102:105]
	v_mfma_f32_16x16x32_f16 v[98:101], v[224:227], v[178:181], v[98:101]
	v_mfma_f32_16x16x32_f16 v[86:89], v[202:205], v[186:189], v[86:89]
	v_mfma_f32_16x16x32_f16 v[82:85], v[224:227], v[186:189], v[82:85]
	v_mfma_f32_16x16x32_f16 v[70:73], v[202:205], v[194:197], v[70:73]
	v_mfma_f32_16x16x32_f16 v[66:69], v[224:227], v[194:197], v[66:69]
	s_barrier
	global_load_lds_dwordx4 v[146:147], off
	v_lshl_add_u64 v[206:207], s[42:43], 0, v[136:137]
	s_add_i32 m0, s45, 0x2000
	s_nop 0
	global_load_lds_dwordx4 v[206:207], off
	s_mov_b32 m0, s72
	v_lshl_add_u64 v[212:213], s[48:49], 0, v[130:131]
	ds_read_b128 v[166:169], v153 offset:16384
	ds_read_b128 v[170:173], v153 offset:17408
	ds_read_b128 v[174:177], v153 offset:18432
	ds_read_b128 v[178:181], v153 offset:19456
	ds_read_b128 v[182:185], v153 offset:20480
	ds_read_b128 v[186:189], v153 offset:21504
	ds_read_b128 v[190:193], v153 offset:22528
	ds_read_b128 v[194:197], v153 offset:23552
	global_load_lds_dwordx4 v[212:213], off
	v_lshl_add_u64 v[228:229], s[48:49], 0, v[134:135]
	s_mov_b32 m0, s73
	s_nop 0
	global_load_lds_dwordx4 v[228:229], off
	s_waitcnt vmcnt(6) lgkmcnt(0)
	s_barrier
	v_mfma_f32_16x16x32_f16 v[62:65], v[142:145], v[166:169], v[62:65]
	v_mfma_f32_16x16x32_f16 v[58:61], v[158:161], v[166:169], v[58:61]
	v_mfma_f32_16x16x32_f16 v[46:49], v[142:145], v[174:177], v[46:49]
	v_mfma_f32_16x16x32_f16 v[42:45], v[158:161], v[174:177], v[42:45]
	v_mfma_f32_16x16x32_f16 v[30:33], v[142:145], v[182:185], v[30:33]
	v_mfma_f32_16x16x32_f16 v[26:29], v[158:161], v[182:185], v[26:29]
	v_mfma_f32_16x16x32_f16 v[14:17], v[142:145], v[190:193], v[14:17]
	v_mfma_f32_16x16x32_f16 v[10:13], v[158:161], v[190:193], v[10:13]
	v_mfma_f32_16x16x32_f16 v[62:65], v[154:157], v[170:173], v[62:65]
	v_mfma_f32_16x16x32_f16 v[58:61], v[162:165], v[170:173], v[58:61]
	v_mfma_f32_16x16x32_f16 v[46:49], v[154:157], v[178:181], v[46:49]
	v_mfma_f32_16x16x32_f16 v[42:45], v[162:165], v[178:181], v[42:45]
	v_mfma_f32_16x16x32_f16 v[30:33], v[154:157], v[186:189], v[30:33]
	v_mfma_f32_16x16x32_f16 v[26:29], v[162:165], v[186:189], v[26:29]
	v_mfma_f32_16x16x32_f16 v[14:17], v[154:157], v[194:197], v[14:17]
	v_mfma_f32_16x16x32_f16 v[10:13], v[162:165], v[194:197], v[10:13]
	v_mfma_f32_16x16x32_f16 v[54:57], v[198:201], v[166:169], v[54:57]
	v_mfma_f32_16x16x32_f16 v[50:53], v[220:223], v[166:169], v[50:53]
	v_mfma_f32_16x16x32_f16 v[38:41], v[198:201], v[174:177], v[38:41]
	v_mfma_f32_16x16x32_f16 v[34:37], v[220:223], v[174:177], v[34:37]
	v_mfma_f32_16x16x32_f16 v[22:25], v[198:201], v[182:185], v[22:25]
	v_mfma_f32_16x16x32_f16 v[18:21], v[220:223], v[182:185], v[18:21]
	v_mfma_f32_16x16x32_f16 v[6:9], v[198:201], v[190:193], v[6:9]
	v_mfma_f32_16x16x32_f16 v[2:5], v[220:223], v[190:193], v[2:5]
	v_mfma_f32_16x16x32_f16 v[54:57], v[202:205], v[170:173], v[54:57]
	v_mfma_f32_16x16x32_f16 v[50:53], v[224:227], v[170:173], v[50:53]
	v_mfma_f32_16x16x32_f16 v[38:41], v[202:205], v[178:181], v[38:41]
	v_mfma_f32_16x16x32_f16 v[34:37], v[224:227], v[178:181], v[34:37]
	v_mfma_f32_16x16x32_f16 v[22:25], v[202:205], v[186:189], v[22:25]
	v_mfma_f32_16x16x32_f16 v[18:21], v[224:227], v[186:189], v[18:21]
	v_mfma_f32_16x16x32_f16 v[6:9], v[202:205], v[194:197], v[6:9]
	v_mfma_f32_16x16x32_f16 v[2:5], v[224:227], v[194:197], v[2:5]
	s_barrier
; #define PG8_STAGE(bufoff, gbase, voff) do { _Pragma("unroll") for (int _i = 0; _i < 2; ++_i) \
;         __builtin_amdgcn_global_load_lds((const unsigned*)((const char*)(gbase) + (voff)[_i]), (LAS unsigned*)(lds + (bufoff) + ldsw + _i * 8192), 16, 0, 0); } while (0)
; #define PG8_LDA(dst, b, h) do { _Pragma("unroll") for (int m = 0; m < 4; ++m) _Pragma("unroll") for (int k = 0; k < 2; ++k) dst[m][k] = *(const LAS h16x8*)(lds + PG8_SA(b, h) + aoff + m * 2048 + k * 1024); } while (0)
; #define PG8_LDB(dst, b, h) do { _Pragma("unroll") for (int n = 0; n < 2; ++n) _Pragma("unroll") for (int k = 0; k < 2; ++k) dst[n][k] = *(const LAS h16x8*)(lds + PG8_SB(b, h) + boff + n * 2048 + k * 1024); } while (0)
; #define PG8_MMA(ai, bj, At, Bt_) do { __builtin_amdgcn_s_setprio(1); _Pragma("unroll") for (int m = 0; m < 4; ++m) _Pragma("unroll") for (int n = 0; n < 2; ++n) _Pragma("unroll") for (int k = 0; k < 2; ++k) \
;         acc[ai][bj][m][n] = __builtin_amdgcn_mfma_f32_16x16x32_f16(Bt_[n][k], At[m][k], acc[ai][bj][m][n], 0, 0, 0); __builtin_amdgcn_s_setprio(0); } while (0)
; #define PG8_WAIT_V(n) asm volatile("s_waitcnt vmcnt(" #n ")" ::: "memory")
; #define PG8_WAIT_L(n) asm volatile("s_waitcnt lgkmcnt(" #n ")" ::: "memory")
; #define PG8_BAR __builtin_amdgcn_s_barrier()
; #define PG8_SCHED __builtin_amdgcn_sched_barrier(0)
; template <class Epi, class AMap>
; __device__ __forceinline__ void gemm_phase(LAS unsigned char* lds, const AMap am, const int lda, const h16* Bt, const int ldb, const int M, const int N, const int K, const Epi& E) {
;     ...
;             PG8_STAGE(PG8_SB(0, 1), b2 + hstepB, voffB);
;             PG8_WAIT_V(6); PG8_BAR; PG8_MMA(1, 1, At, B1); PG8_BAR;
;             PG8_LDB(B0, 1, 0); PG8_SCHED; PG8_LDA(At, 1, 0); PG8_STAGE(PG8_SA(0, 1), a2 + hstepA, voffA);
;             PG8_WAIT_L(8); PG8_BAR; PG8_WAIT_L(0); PG8_MMA(0, 0, At, B0); PG8_BAR; PG8_SCHED;
;             PG8_LDB(B1, 1, 1); PG8_STAGE(PG8_SB(1, 0), b3, voffB);
;             PG8_BAR; PG8_WAIT_L(0); PG8_MMA(0, 1, At, B1); PG8_BAR;
	s_add_u32 s50, s42, 0x80000
	s_addc_u32 s51, s43, 0
	s_add_i32 s45, s60, s65
	v_lshl_add_u64 v[232:233], s[50:51], 0, v[132:133]
	s_mov_b32 m0, s45
	s_nop 0
	global_load_lds_dwordx4 v[232:233], off
	v_lshl_add_u64 v[232:233], s[50:51], 0, v[136:137]
	s_add_i32 m0, s45, 0x2000
	s_nop 0
	global_load_lds_dwordx4 v[232:233], off
	s_add_i32 s45, 0, 0x18000
	v_add_u32_e32 v0, s45, v149
	ds_read_b128 v[142:145], v0
	ds_read_b128 v[154:157], v0 offset:1024
	ds_read_b128 v[158:161], v0 offset:2048
	ds_read_b128 v[162:165], v0 offset:3072
	s_add_u32 s48, s48, 0x80000
	s_addc_u32 s49, s49, 0
	s_mov_b32 m0, s74
	v_lshl_add_u64 v[232:233], s[48:49], 0, v[130:131]
	ds_read_b128 v[166:169], v153 offset:32768
	ds_read_b128 v[170:173], v153 offset:33792
	ds_read_b128 v[174:177], v153 offset:34816
	ds_read_b128 v[178:181], v153 offset:35840
	ds_read_b128 v[182:185], v153 offset:36864
	ds_read_b128 v[186:189], v153 offset:37888
	ds_read_b128 v[190:193], v153 offset:38912
	ds_read_b128 v[194:197], v153 offset:39936
	global_load_lds_dwordx4 v[232:233], off
	v_lshl_add_u64 v[232:233], s[48:49], 0, v[134:135]
	s_mov_b32 m0, s75
	s_nop 0
	global_load_lds_dwordx4 v[232:233], off
	s_waitcnt lgkmcnt(11)
	s_add_i32 s48, 0, 0x1c000
	s_add_i32 s45, s45, s65
	v_add_u32_e32 v0, s48, v149
	v_lshl_add_u64 v[146:147], v[146:147], 0, s[92:93]
	s_mov_b32 m0, s45
	ds_read_b128 v[198:201], v0
	ds_read_b128 v[202:205], v0 offset:1024
	ds_read_b128 v[220:223], v0 offset:2048
	ds_read_b128 v[224:227], v0 offset:3072
	s_waitcnt vmcnt(8) lgkmcnt(0)
	s_barrier
	v_mfma_f32_16x16x32_f16 v[126:129], v[142:145], v[166:169], v[126:129]
	v_mfma_f32_16x16x32_f16 v[122:125], v[158:161], v[166:169], v[122:125]
	v_mfma_f32_16x16x32_f16 v[110:113], v[142:145], v[174:177], v[110:113]
	v_mfma_f32_16x16x32_f16 v[106:109], v[158:161], v[174:177], v[106:109]
	v_mfma_f32_16x16x32_f16 v[94:97], v[142:145], v[182:185], v[94:97]
	v_mfma_f32_16x16x32_f16 v[90:93], v[158:161], v[182:185], v[90:93]
	v_mfma_f32_16x16x32_f16 v[78:81], v[142:145], v[190:193], v[78:81]
	v_mfma_f32_16x16x32_f16 v[74:77], v[158:161], v[190:193], v[74:77]
	v_mfma_f32_16x16x32_f16 v[126:129], v[154:157], v[170:173], v[126:129]
	v_mfma_f32_16x16x32_f16 v[122:125], v[162:165], v[170:173], v[122:125]
	v_mfma_f32_16x16x32_f16 v[110:113], v[154:157], v[178:181], v[110:113]
	v_mfma_f32_16x16x32_f16 v[106:109], v[162:165], v[178:181], v[106:109]
	v_mfma_f32_16x16x32_f16 v[94:97], v[154:157], v[186:189], v[94:97]
	v_mfma_f32_16x16x32_f16 v[90:93], v[162:165], v[186:189], v[90:93]
	v_mfma_f32_16x16x32_f16 v[78:81], v[154:157], v[194:197], v[78:81]
	v_mfma_f32_16x16x32_f16 v[74:77], v[162:165], v[194:197], v[74:77]
	v_mfma_f32_16x16x32_f16 v[118:121], v[198:201], v[166:169], v[118:121]
	v_mfma_f32_16x16x32_f16 v[114:117], v[220:223], v[166:169], v[114:117]
	v_mfma_f32_16x16x32_f16 v[102:105], v[198:201], v[174:177], v[102:105]
	v_mfma_f32_16x16x32_f16 v[98:101], v[220:223], v[174:177], v[98:101]
	v_mfma_f32_16x16x32_f16 v[86:89], v[198:201], v[182:185], v[86:89]
	v_mfma_f32_16x16x32_f16 v[82:85], v[220:223], v[182:185], v[82:85]
	v_mfma_f32_16x16x32_f16 v[70:73], v[198:201], v[190:193], v[70:73]
	v_mfma_f32_16x16x32_f16 v[66:69], v[220:223], v[190:193], v[66:69]
	v_mfma_f32_16x16x32_f16 v[118:121], v[202:205], v[170:173], v[118:121]
	v_mfma_f32_16x16x32_f16 v[114:117], v[224:227], v[170:173], v[114:117]
	v_mfma_f32_16x16x32_f16 v[102:105], v[202:205], v[178:181], v[102:105]
	v_mfma_f32_16x16x32_f16 v[98:101], v[224:227], v[178:181], v[98:101]
	v_mfma_f32_16x16x32_f16 v[86:89], v[202:205], v[186:189], v[86:89]
	v_mfma_f32_16x16x32_f16 v[82:85], v[224:227], v[186:189], v[82:85]
	v_mfma_f32_16x16x32_f16 v[70:73], v[202:205], v[194:197], v[70:73]
	v_mfma_f32_16x16x32_f16 v[66:69], v[224:227], v[194:197], v[66:69]
	s_barrier
; #define PG8_STAGE(bufoff, gbase, voff) do { _Pragma("unroll") for (int _i = 0; _i < 2; ++_i) \
;         __builtin_amdgcn_global_load_lds((const unsigned*)((const char*)(gbase) + (voff)[_i]), (LAS unsigned*)(lds + (bufoff) + ldsw + _i * 8192), 16, 0, 0); } while (0)
; #define PG8_LDA(dst, b, h) do { _Pragma("unroll") for (int m = 0; m < 4; ++m) _Pragma("unroll") for (int k = 0; k < 2; ++k) dst[m][k] = *(const LAS h16x8*)(lds + PG8_SA(b, h) + aoff + m * 2048 + k * 1024); } while (0)
; #define PG8_LDB(dst, b, h) do { _Pragma("unroll") for (int n = 0; n < 2; ++n) _Pragma("unroll") for (int k = 0; k < 2; ++k) dst[n][k] = *(const LAS h16x8*)(lds + PG8_SB(b, h) + boff + n * 2048 + k * 1024); } while (0)
; #define PG8_MMA(ai, bj, At, Bt_) do { __builtin_amdgcn_s_setprio(1); _Pragma("unroll") for (int m = 0; m < 4; ++m) _Pragma("unroll") for (int n = 0; n < 2; ++n) _Pragma("unroll") for (int k = 0; k < 2; ++k) \
;         acc[ai][bj][m][n] = __builtin_amdgcn_mfma_f32_16x16x32_f16(Bt_[n][k], At[m][k], acc[ai][bj][m][n], 0, 0, 0); __builtin_amdgcn_s_setprio(0); } while (0)
; #define PG8_WAIT_V(n) asm volatile("s_waitcnt vmcnt(" #n ")" ::: "memory")
; #define PG8_WAIT_L(n) asm volatile("s_waitcnt lgkmcnt(" #n ")" ::: "memory")
; #define PG8_BAR __builtin_amdgcn_s_barrier()
; #define PG8_SCHED __builtin_amdgcn_sched_barrier(0)
; template <class Epi, class AMap>
; __device__ __forceinline__ void gemm_phase(LAS unsigned char* lds, const AMap am, const int lda, const h16* Bt, const int ldb, const int M, const int N, const int K, const Epi& E) {
;     ...
;             PG8_LDB(B1, 1, 1); PG8_STAGE(PG8_SB(1, 0), b3, voffB);
;             PG8_BAR; PG8_WAIT_L(0); PG8_MMA(0, 1, At, B1); PG8_BAR;
;             PG8_LDA(At, 1, 1); PG8_STAGE(PG8_SA(1, 0), a3, voffA);
;             PG8_BAR; PG8_WAIT_L(0); PG8_MMA(1, 0, At, B0); PG8_BAR; PG8_SCHED;
;             PG8_STAGE(PG8_SB(1, 1), b3 + hstepB, voffB);
;             PG8_WAIT_V(6); PG8_BAR; PG8_MMA(1, 1, At, B1); PG8_BAR;
;         }
;     ...
;     if (wr == 0) PG8_BAR;
	global_load_lds_dwordx4 v[146:147], off
	v_lshl_add_u64 v[146:147], v[206:207], 0, s[92:93]
	s_add_i32 m0, s45, 0x2000
	s_nop 0
	global_load_lds_dwordx4 v[146:147], off
	s_mov_b32 m0, s77
	v_lshl_add_u64 v[146:147], v[212:213], 0, s[92:93]
	ds_read_b128 v[166:169], v153 offset:49152
	ds_read_b128 v[170:173], v153 offset:50176
	ds_read_b128 v[174:177], v153 offset:51200
	ds_read_b128 v[178:181], v153 offset:52224
	ds_read_b128 v[182:185], v153 offset:53248
	ds_read_b128 v[186:189], v153 offset:54272
	ds_read_b128 v[190:193], v153 offset:55296
	ds_read_b128 v[194:197], v153 offset:56320
	global_load_lds_dwordx4 v[146:147], off
	v_lshl_add_u64 v[146:147], v[228:229], 0, s[92:93]
	s_mov_b32 m0, s78
	s_nop 0
	global_load_lds_dwordx4 v[146:147], off
	s_add_u32 s42, s42, 0x80080
	s_addc_u32 s43, s43, 0
	s_add_i32 s45, s48, s65
	v_lshl_add_u64 v[232:233], s[42:43], 0, v[132:133]
	s_mov_b32 m0, s45
	s_nop 0
	global_load_lds_dwordx4 v[232:233], off
	v_lshl_add_u64 v[232:233], s[42:43], 0, v[136:137]
	s_add_i32 m0, s45, 0x2000
	s_nop 0
	global_load_lds_dwordx4 v[232:233], off
	s_add_i32 s35, s35, 2
	s_add_u32 s40, s40, 0x100
	s_addc_u32 s41, s41, 0
	s_add_u32 s21, s21, 0x100
	s_addc_u32 s29, s29, 0
	s_cmp_gt_u32 s35, 29
	s_waitcnt vmcnt(8) lgkmcnt(0)
	s_barrier
	v_mfma_f32_16x16x32_f16 v[62:65], v[142:145], v[166:169], v[62:65]
	v_mfma_f32_16x16x32_f16 v[58:61], v[158:161], v[166:169], v[58:61]
	v_mfma_f32_16x16x32_f16 v[46:49], v[142:145], v[174:177], v[46:49]
	v_mfma_f32_16x16x32_f16 v[42:45], v[158:161], v[174:177], v[42:45]
	v_mfma_f32_16x16x32_f16 v[30:33], v[142:145], v[182:185], v[30:33]
	v_mfma_f32_16x16x32_f16 v[26:29], v[158:161], v[182:185], v[26:29]
	v_mfma_f32_16x16x32_f16 v[14:17], v[142:145], v[190:193], v[14:17]
	v_mfma_f32_16x16x32_f16 v[10:13], v[158:161], v[190:193], v[10:13]
	v_mfma_f32_16x16x32_f16 v[62:65], v[154:157], v[170:173], v[62:65]
	v_mfma_f32_16x16x32_f16 v[58:61], v[162:165], v[170:173], v[58:61]
	v_mfma_f32_16x16x32_f16 v[46:49], v[154:157], v[178:181], v[46:49]
	v_mfma_f32_16x16x32_f16 v[42:45], v[162:165], v[178:181], v[42:45]
	v_mfma_f32_16x16x32_f16 v[30:33], v[154:157], v[186:189], v[30:33]
	v_mfma_f32_16x16x32_f16 v[26:29], v[162:165], v[186:189], v[26:29]
	v_mfma_f32_16x16x32_f16 v[14:17], v[154:157], v[194:197], v[14:17]
	v_mfma_f32_16x16x32_f16 v[10:13], v[162:165], v[194:197], v[10:13]
	v_mfma_f32_16x16x32_f16 v[54:57], v[198:201], v[166:169], v[54:57]
	v_mfma_f32_16x16x32_f16 v[50:53], v[220:223], v[166:169], v[50:53]
	v_mfma_f32_16x16x32_f16 v[38:41], v[198:201], v[174:177], v[38:41]
	v_mfma_f32_16x16x32_f16 v[34:37], v[220:223], v[174:177], v[34:37]
	v_mfma_f32_16x16x32_f16 v[22:25], v[198:201], v[182:185], v[22:25]
	v_mfma_f32_16x16x32_f16 v[18:21], v[220:223], v[182:185], v[18:21]
	v_mfma_f32_16x16x32_f16 v[6:9], v[198:201], v[190:193], v[6:9]
	v_mfma_f32_16x16x32_f16 v[2:5], v[220:223], v[190:193], v[2:5]
	v_mfma_f32_16x16x32_f16 v[54:57], v[202:205], v[170:173], v[54:57]
	v_mfma_f32_16x16x32_f16 v[50:53], v[224:227], v[170:173], v[50:53]
	v_mfma_f32_16x16x32_f16 v[38:41], v[202:205], v[178:181], v[38:41]
	v_mfma_f32_16x16x32_f16 v[34:37], v[224:227], v[178:181], v[34:37]
	v_mfma_f32_16x16x32_f16 v[22:25], v[202:205], v[186:189], v[22:25]
	v_mfma_f32_16x16x32_f16 v[18:21], v[224:227], v[186:189], v[18:21]
	v_mfma_f32_16x16x32_f16 v[6:9], v[202:205], v[194:197], v[6:9]
	v_mfma_f32_16x16x32_f16 v[2:5], v[224:227], v[194:197], v[2:5]
	s_barrier
	s_cbranch_scc0 .LBB0_268
	s_cmpk_gt_u32 s64, 0xff
	s_cbranch_scc1 .Lgx3
	s_barrier

; #define PG8_STAGE(bufoff, gbase, voff) do { _Pragma("unroll") for (int _i = 0; _i < 2; ++_i) \
;         __builtin_amdgcn_global_load_lds((const unsigned*)((const char*)(gbase) + (voff)[_i]), (LAS unsigned*)(lds + (bufoff) + ldsw + _i * 8192), 16, 0, 0); } while (0)
; #define PG8_LDA(dst, b, h) do { _Pragma("unroll") for (int m = 0; m < 4; ++m) _Pragma("unroll") for (int k = 0; k < 2; ++k) dst[m][k] = *(const LAS h16x8*)(lds + PG8_SA(b, h) + aoff + m * 2048 + k * 1024); } while (0)
; #define PG8_LDB(dst, b, h) do { _Pragma("unroll") for (int n = 0; n < 2; ++n) _Pragma("unroll") for (int k = 0; k < 2; ++k) dst[n][k] = *(const LAS h16x8*)(lds + PG8_SB(b, h) + boff + n * 2048 + k * 1024); } while (0)
; #define PG8_MMA(ai, bj, At, Bt_) do { __builtin_amdgcn_s_setprio(1); _Pragma("unroll") for (int m = 0; m < 4; ++m) _Pragma("unroll") for (int n = 0; n < 2; ++n) _Pragma("unroll") for (int k = 0; k < 2; ++k) \
;         acc[ai][bj][m][n] = __builtin_amdgcn_mfma_f32_16x16x32_f16(Bt_[n][k], At[m][k], acc[ai][bj][m][n], 0, 0, 0); __builtin_amdgcn_s_setprio(0); } while (0)
; #define PG8_WAIT_V(n) asm volatile("s_waitcnt vmcnt(" #n ")" ::: "memory")
; template <class Epi, class AMap>
; __device__ __forceinline__ void gemm_phase(LAS unsigned char* lds, const AMap am, const int lda, const h16* Bt, const int ldb, const int M, const int N, const int K, const Epi& E) {
;     ...
;         for (int t = 0; t < nt; t += 2) {
;             const bool last = (t == nt - 2);
;             const char* a1 = cA + (size_t)(t + 1) * kstep;
;             const char* a2 = last ? nA : cA + (size_t)(t + 2) * kstep; const char* b2 = last ? nB : cB + (size_t)(t + 2) * kstep;
;             const char* a3 = a2 + kstep; const char* b3 = b2 + kstep;
;             PG8_LDB(B0, 0, 0); PG8_SCHED; PG8_LDA(At, 0, 0); PG8_STAGE(PG8_SA(1, 1), a1 + hstepA, voffA);
;             PG8_WAIT_L(8); PG8_BAR; PG8_WAIT_L(0); PG8_MMA(0, 0, At, B0); PG8_BAR; PG8_SCHED;
;             PG8_LDB(B1, 0, 1); PG8_STAGE(PG8_SB(0, 0), b2, voffB);
;             PG8_BAR; PG8_WAIT_L(0); PG8_MMA(0, 1, At, B1); PG8_BAR;
;             PG8_LDA(At, 0, 1); PG8_STAGE(PG8_SA(0, 0), a2, voffA);
;             PG8_BAR; PG8_WAIT_L(0); PG8_MMA(1, 0, At, B0); PG8_BAR; PG8_SCHED;
;             PG8_STAGE(PG8_SB(0, 1), b2 + hstepB, voffB);
;             PG8_WAIT_V(6); PG8_BAR; PG8_MMA(1, 1, At, B1); PG8_BAR;
.LBB0_621:
	s_add_i32 s51, s26, 2
	s_add_u32 s0, s22, 0x100
	s_addc_u32 s1, s23, 0
	s_add_i32 s60, 0, 0x10000
	v_add_u32_e32 v152, s60, v155
	ds_read_b128 v[90:93], v152
	ds_read_b128 v[94:97], v152 offset:1024
	ds_read_b128 v[148:151], v152 offset:2048
	ds_read_b128 v[158:161], v152 offset:3072
	s_cmp_eq_u32 s82, s26
	s_cselect_b32 s26, s21, s29
	s_cselect_b32 s49, s65, s1
	s_cselect_b32 s48, s64, s0
	s_cselect_b32 s27, s20, s45
	v_lshl_add_u64 v[152:153], s[22:23], 0, v[144:145]
	s_add_i32 m0, s76, 0xc000
	ds_read_b128 v[162:165], v157
	ds_read_b128 v[166:169], v157 offset:1024
	ds_read_b128 v[170:173], v157 offset:2048
	ds_read_b128 v[174:177], v157 offset:3072
	ds_read_b128 v[178:181], v157 offset:4096
	ds_read_b128 v[182:185], v157 offset:5120
	ds_read_b128 v[186:189], v157 offset:6144
	ds_read_b128 v[190:193], v157 offset:7168
	global_load_lds_dwordx4 v[152:153], off
	v_lshl_add_u64 v[152:153], s[22:23], 0, v[146:147]
	s_add_i32 m0, s76, 0xe000
	s_nop 0
	global_load_lds_dwordx4 v[152:153], off
	s_waitcnt lgkmcnt(11)
	s_add_i32 s62, 0, 0x14000
	v_add_u32_e32 v152, s62, v155
	s_add_i32 s22, s60, s73
	ds_read_b128 v[194:197], v152
	ds_read_b128 v[198:201], v152 offset:1024
	ds_read_b128 v[202:205], v152 offset:2048
	ds_read_b128 v[220:223], v152 offset:3072
	s_waitcnt vmcnt(8) lgkmcnt(0)
	s_barrier
	v_mfma_f32_16x16x32_f16 v[130:133], v[90:93], v[162:165], v[130:133]
	v_mfma_f32_16x16x32_f16 v[134:137], v[148:151], v[162:165], v[134:137]
	v_mfma_f32_16x16x32_f16 v[126:129], v[90:93], v[170:173], v[126:129]
	v_mfma_f32_16x16x32_f16 v[122:125], v[148:151], v[170:173], v[122:125]
	v_mfma_f32_16x16x32_f16 v[118:121], v[90:93], v[178:181], v[118:121]
	v_mfma_f32_16x16x32_f16 v[114:117], v[148:151], v[178:181], v[114:117]
	v_mfma_f32_16x16x32_f16 v[110:113], v[90:93], v[186:189], v[110:113]
	v_mfma_f32_16x16x32_f16 v[106:109], v[148:151], v[186:189], v[106:109]
	v_mfma_f32_16x16x32_f16 v[130:133], v[94:97], v[166:169], v[130:133]
	v_mfma_f32_16x16x32_f16 v[134:137], v[158:161], v[166:169], v[134:137]
	v_mfma_f32_16x16x32_f16 v[126:129], v[94:97], v[174:177], v[126:129]
	v_mfma_f32_16x16x32_f16 v[122:125], v[158:161], v[174:177], v[122:125]
	v_mfma_f32_16x16x32_f16 v[118:121], v[94:97], v[182:185], v[118:121]
	v_mfma_f32_16x16x32_f16 v[114:117], v[158:161], v[182:185], v[114:117]
	v_mfma_f32_16x16x32_f16 v[110:113], v[94:97], v[190:193], v[110:113]
	v_mfma_f32_16x16x32_f16 v[106:109], v[158:161], v[190:193], v[106:109]
	v_mfma_f32_16x16x32_f16 v[62:65], v[194:197], v[162:165], v[62:65]
	v_mfma_f32_16x16x32_f16 v[58:61], v[202:205], v[162:165], v[58:61]
	v_mfma_f32_16x16x32_f16 v[54:57], v[194:197], v[170:173], v[54:57]
	v_mfma_f32_16x16x32_f16 v[50:53], v[202:205], v[170:173], v[50:53]
	v_mfma_f32_16x16x32_f16 v[46:49], v[194:197], v[178:181], v[46:49]
	v_mfma_f32_16x16x32_f16 v[42:45], v[202:205], v[178:181], v[42:45]
	v_mfma_f32_16x16x32_f16 v[38:41], v[194:197], v[186:189], v[38:41]
	v_mfma_f32_16x16x32_f16 v[34:37], v[202:205], v[186:189], v[34:37]
	v_mfma_f32_16x16x32_f16 v[62:65], v[198:201], v[166:169], v[62:65]
	v_mfma_f32_16x16x32_f16 v[58:61], v[220:223], v[166:169], v[58:61]
	v_mfma_f32_16x16x32_f16 v[54:57], v[198:201], v[174:177], v[54:57]
	v_mfma_f32_16x16x32_f16 v[50:53], v[220:223], v[174:177], v[50:53]
	v_mfma_f32_16x16x32_f16 v[46:49], v[198:201], v[182:185], v[46:49]
	v_mfma_f32_16x16x32_f16 v[42:45], v[220:223], v[182:185], v[42:45]
	v_mfma_f32_16x16x32_f16 v[38:41], v[198:201], v[190:193], v[38:41]
	v_mfma_f32_16x16x32_f16 v[34:37], v[220:223], v[190:193], v[34:37]
	s_barrier
	v_lshl_add_u64 v[152:153], s[26:27], 0, v[0:1]
	s_mov_b32 m0, s22
	v_lshl_add_u64 v[206:207], s[26:27], 0, v[142:143]
	global_load_lds_dwordx4 v[152:153], off
	s_add_i32 m0, s22, 0x2000
	s_nop 0
	global_load_lds_dwordx4 v[206:207], off
	s_mov_b32 m0, s76
	v_lshl_add_u64 v[212:213], s[48:49], 0, v[138:139]
	ds_read_b128 v[162:165], v157 offset:16384
	ds_read_b128 v[166:169], v157 offset:17408
	ds_read_b128 v[170:173], v157 offset:18432
	ds_read_b128 v[174:177], v157 offset:19456
	ds_read_b128 v[178:181], v157 offset:20480
	ds_read_b128 v[182:185], v157 offset:21504
	ds_read_b128 v[186:189], v157 offset:22528
	ds_read_b128 v[190:193], v157 offset:23552
	global_load_lds_dwordx4 v[212:213], off
	v_lshl_add_u64 v[224:225], s[48:49], 0, v[140:141]
	s_mov_b32 m0, s77
	s_nop 0
	global_load_lds_dwordx4 v[224:225], off
	s_waitcnt vmcnt(6) lgkmcnt(0)
	s_barrier
	v_mfma_f32_16x16x32_f16 v[102:105], v[90:93], v[162:165], v[102:105]
	v_mfma_f32_16x16x32_f16 v[98:101], v[148:151], v[162:165], v[98:101]
	v_mfma_f32_16x16x32_f16 v[86:89], v[90:93], v[170:173], v[86:89]
	v_mfma_f32_16x16x32_f16 v[82:85], v[148:151], v[170:173], v[82:85]
	v_mfma_f32_16x16x32_f16 v[78:81], v[90:93], v[178:181], v[78:81]
	v_mfma_f32_16x16x32_f16 v[74:77], v[148:151], v[178:181], v[74:77]
	v_mfma_f32_16x16x32_f16 v[70:73], v[90:93], v[186:189], v[70:73]
	v_mfma_f32_16x16x32_f16 v[66:69], v[148:151], v[186:189], v[66:69]
	v_mfma_f32_16x16x32_f16 v[102:105], v[94:97], v[166:169], v[102:105]
	v_mfma_f32_16x16x32_f16 v[98:101], v[158:161], v[166:169], v[98:101]
	v_mfma_f32_16x16x32_f16 v[86:89], v[94:97], v[174:177], v[86:89]
	v_mfma_f32_16x16x32_f16 v[82:85], v[158:161], v[174:177], v[82:85]
	v_mfma_f32_16x16x32_f16 v[78:81], v[94:97], v[182:185], v[78:81]
	v_mfma_f32_16x16x32_f16 v[74:77], v[158:161], v[182:185], v[74:77]
	v_mfma_f32_16x16x32_f16 v[70:73], v[94:97], v[190:193], v[70:73]
	v_mfma_f32_16x16x32_f16 v[66:69], v[158:161], v[190:193], v[66:69]
	v_mfma_f32_16x16x32_f16 v[30:33], v[194:197], v[162:165], v[30:33]
	v_mfma_f32_16x16x32_f16 v[26:29], v[202:205], v[162:165], v[26:29]
	v_mfma_f32_16x16x32_f16 v[22:25], v[194:197], v[170:173], v[22:25]
	v_mfma_f32_16x16x32_f16 v[18:21], v[202:205], v[170:173], v[18:21]
	v_mfma_f32_16x16x32_f16 v[14:17], v[194:197], v[178:181], v[14:17]
	v_mfma_f32_16x16x32_f16 v[10:13], v[202:205], v[178:181], v[10:13]
	v_mfma_f32_16x16x32_f16 v[6:9], v[194:197], v[186:189], v[6:9]
	v_mfma_f32_16x16x32_f16 v[2:5], v[202:205], v[186:189], v[2:5]
	v_mfma_f32_16x16x32_f16 v[30:33], v[198:201], v[166:169], v[30:33]
	v_mfma_f32_16x16x32_f16 v[26:29], v[220:223], v[166:169], v[26:29]
	v_mfma_f32_16x16x32_f16 v[22:25], v[198:201], v[174:177], v[22:25]
	v_mfma_f32_16x16x32_f16 v[18:21], v[220:223], v[174:177], v[18:21]
	v_mfma_f32_16x16x32_f16 v[14:17], v[198:201], v[182:185], v[14:17]
	v_mfma_f32_16x16x32_f16 v[10:13], v[220:223], v[182:185], v[10:13]
	v_mfma_f32_16x16x32_f16 v[6:9], v[198:201], v[190:193], v[6:9]
	v_mfma_f32_16x16x32_f16 v[2:5], v[220:223], v[190:193], v[2:5]
	s_barrier
; #define PG8_STAGE(bufoff, gbase, voff) do { _Pragma("unroll") for (int _i = 0; _i < 2; ++_i) \
;         __builtin_amdgcn_global_load_lds((const unsigned*)((const char*)(gbase) + (voff)[_i]), (LAS unsigned*)(lds + (bufoff) + ldsw + _i * 8192), 16, 0, 0); } while (0)
; #define PG8_LDA(dst, b, h) do { _Pragma("unroll") for (int m = 0; m < 4; ++m) _Pragma("unroll") for (int k = 0; k < 2; ++k) dst[m][k] = *(const LAS h16x8*)(lds + PG8_SA(b, h) + aoff + m * 2048 + k * 1024); } while (0)
; #define PG8_LDB(dst, b, h) do { _Pragma("unroll") for (int n = 0; n < 2; ++n) _Pragma("unroll") for (int k = 0; k < 2; ++k) dst[n][k] = *(const LAS h16x8*)(lds + PG8_SB(b, h) + boff + n * 2048 + k * 1024); } while (0)
; #define PG8_MMA(ai, bj, At, Bt_) do { __builtin_amdgcn_s_setprio(1); _Pragma("unroll") for (int m = 0; m < 4; ++m) _Pragma("unroll") for (int n = 0; n < 2; ++n) _Pragma("unroll") for (int k = 0; k < 2; ++k) \
;         acc[ai][bj][m][n] = __builtin_amdgcn_mfma_f32_16x16x32_f16(Bt_[n][k], At[m][k], acc[ai][bj][m][n], 0, 0, 0); __builtin_amdgcn_s_setprio(0); } while (0)
; #define PG8_WAIT_V(n) asm volatile("s_waitcnt vmcnt(" #n ")" ::: "memory")
; #define PG8_WAIT_L(n) asm volatile("s_waitcnt lgkmcnt(" #n ")" ::: "memory")
; #define PG8_BAR __builtin_amdgcn_s_barrier()
; #define PG8_SCHED __builtin_amdgcn_sched_barrier(0)
; template <class Epi, class AMap>
; __device__ __forceinline__ void gemm_phase(LAS unsigned char* lds, const AMap am, const int lda, const h16* Bt, const int ldb, const int M, const int N, const int K, const Epi& E) {
;     ...
;             PG8_STAGE(PG8_SB(0, 1), b2 + hstepB, voffB);
;             PG8_WAIT_V(6); PG8_BAR; PG8_MMA(1, 1, At, B1); PG8_BAR;
;             PG8_LDB(B0, 1, 0); PG8_SCHED; PG8_LDA(At, 1, 0); PG8_STAGE(PG8_SA(0, 1), a2 + hstepA, voffA);
;             PG8_WAIT_L(8); PG8_BAR; PG8_WAIT_L(0); PG8_MMA(0, 0, At, B0); PG8_BAR; PG8_SCHED;
;             PG8_LDB(B1, 1, 1); PG8_STAGE(PG8_SB(1, 0), b3, voffB);
;             PG8_BAR; PG8_WAIT_L(0); PG8_MMA(0, 1, At, B1); PG8_BAR;
	s_add_u32 s22, s26, 0x10000
	s_addc_u32 s23, s27, 0
	s_add_i32 s60, s62, s73
	v_lshl_add_u64 v[232:233], s[22:23], 0, v[0:1]
	s_mov_b32 m0, s60
	s_nop 0
	global_load_lds_dwordx4 v[232:233], off
	v_lshl_add_u64 v[232:233], s[22:23], 0, v[142:143]
	s_add_i32 m0, s60, 0x2000
	s_nop 0
	global_load_lds_dwordx4 v[232:233], off
	s_add_i32 s60, 0, 0x18000
	v_add_u32_e32 v234, s60, v155
	ds_read_b128 v[90:93], v234
	ds_read_b128 v[94:97], v234 offset:1024
	ds_read_b128 v[148:151], v234 offset:2048
	ds_read_b128 v[158:161], v234 offset:3072
	s_add_u32 s22, s48, 0x1c0000
	s_addc_u32 s23, s49, 0
	s_mov_b32 m0, s78
	v_lshl_add_u64 v[232:233], s[22:23], 0, v[138:139]
	ds_read_b128 v[162:165], v157 offset:32768
	ds_read_b128 v[166:169], v157 offset:33792
	ds_read_b128 v[170:173], v157 offset:34816
	ds_read_b128 v[174:177], v157 offset:35840
	ds_read_b128 v[178:181], v157 offset:36864
	ds_read_b128 v[182:185], v157 offset:37888
	ds_read_b128 v[186:189], v157 offset:38912
	ds_read_b128 v[190:193], v157 offset:39936
	global_load_lds_dwordx4 v[232:233], off
	v_lshl_add_u64 v[232:233], s[22:23], 0, v[140:141]
	s_mov_b32 m0, s79
	s_nop 0
	global_load_lds_dwordx4 v[232:233], off
	s_waitcnt lgkmcnt(11)
	s_add_i32 s48, 0, 0x1c000
	s_add_i32 s22, s60, s73
	v_add_u32_e32 v214, s48, v155
	v_lshl_add_u64 v[152:153], v[152:153], 0, s[92:93]
	s_mov_b32 m0, s22
	ds_read_b128 v[194:197], v214
	ds_read_b128 v[198:201], v214 offset:1024
	ds_read_b128 v[202:205], v214 offset:2048
	ds_read_b128 v[220:223], v214 offset:3072
	s_waitcnt vmcnt(8) lgkmcnt(0)
	s_barrier
	v_mfma_f32_16x16x32_f16 v[130:133], v[90:93], v[162:165], v[130:133]
	v_mfma_f32_16x16x32_f16 v[134:137], v[148:151], v[162:165], v[134:137]
	v_mfma_f32_16x16x32_f16 v[126:129], v[90:93], v[170:173], v[126:129]
	v_mfma_f32_16x16x32_f16 v[122:125], v[148:151], v[170:173], v[122:125]
	v_mfma_f32_16x16x32_f16 v[118:121], v[90:93], v[178:181], v[118:121]
	v_mfma_f32_16x16x32_f16 v[114:117], v[148:151], v[178:181], v[114:117]
	v_mfma_f32_16x16x32_f16 v[110:113], v[90:93], v[186:189], v[110:113]
	v_mfma_f32_16x16x32_f16 v[106:109], v[148:151], v[186:189], v[106:109]
	v_mfma_f32_16x16x32_f16 v[130:133], v[94:97], v[166:169], v[130:133]
	v_mfma_f32_16x16x32_f16 v[134:137], v[158:161], v[166:169], v[134:137]
	v_mfma_f32_16x16x32_f16 v[126:129], v[94:97], v[174:177], v[126:129]
	v_mfma_f32_16x16x32_f16 v[122:125], v[158:161], v[174:177], v[122:125]
	v_mfma_f32_16x16x32_f16 v[118:121], v[94:97], v[182:185], v[118:121]
	v_mfma_f32_16x16x32_f16 v[114:117], v[158:161], v[182:185], v[114:117]
	v_mfma_f32_16x16x32_f16 v[110:113], v[94:97], v[190:193], v[110:113]
	v_mfma_f32_16x16x32_f16 v[106:109], v[158:161], v[190:193], v[106:109]
	v_mfma_f32_16x16x32_f16 v[62:65], v[194:197], v[162:165], v[62:65]
	v_mfma_f32_16x16x32_f16 v[58:61], v[202:205], v[162:165], v[58:61]
	v_mfma_f32_16x16x32_f16 v[54:57], v[194:197], v[170:173], v[54:57]
	v_mfma_f32_16x16x32_f16 v[50:53], v[202:205], v[170:173], v[50:53]
	v_mfma_f32_16x16x32_f16 v[46:49], v[194:197], v[178:181], v[46:49]
	v_mfma_f32_16x16x32_f16 v[42:45], v[202:205], v[178:181], v[42:45]
	v_mfma_f32_16x16x32_f16 v[38:41], v[194:197], v[186:189], v[38:41]
	v_mfma_f32_16x16x32_f16 v[34:37], v[202:205], v[186:189], v[34:37]
	v_mfma_f32_16x16x32_f16 v[62:65], v[198:201], v[166:169], v[62:65]
	v_mfma_f32_16x16x32_f16 v[58:61], v[220:223], v[166:169], v[58:61]
	v_mfma_f32_16x16x32_f16 v[54:57], v[198:201], v[174:177], v[54:57]
	v_mfma_f32_16x16x32_f16 v[50:53], v[220:223], v[174:177], v[50:53]
	v_mfma_f32_16x16x32_f16 v[46:49], v[198:201], v[182:185], v[46:49]
	v_mfma_f32_16x16x32_f16 v[42:45], v[220:223], v[182:185], v[42:45]
	v_mfma_f32_16x16x32_f16 v[38:41], v[198:201], v[190:193], v[38:41]
	v_mfma_f32_16x16x32_f16 v[34:37], v[220:223], v[190:193], v[34:37]
	s_barrier
; #define PG8_STAGE(bufoff, gbase, voff) do { _Pragma("unroll") for (int _i = 0; _i < 2; ++_i) \
;         __builtin_amdgcn_global_load_lds((const unsigned*)((const char*)(gbase) + (voff)[_i]), (LAS unsigned*)(lds + (bufoff) + ldsw + _i * 8192), 16, 0, 0); } while (0)
; #define PG8_LDA(dst, b, h) do { _Pragma("unroll") for (int m = 0; m < 4; ++m) _Pragma("unroll") for (int k = 0; k < 2; ++k) dst[m][k] = *(const LAS h16x8*)(lds + PG8_SA(b, h) + aoff + m * 2048 + k * 1024); } while (0)
; #define PG8_LDB(dst, b, h) do { _Pragma("unroll") for (int n = 0; n < 2; ++n) _Pragma("unroll") for (int k = 0; k < 2; ++k) dst[n][k] = *(const LAS h16x8*)(lds + PG8_SB(b, h) + boff + n * 2048 + k * 1024); } while (0)
; #define PG8_MMA(ai, bj, At, Bt_) do { __builtin_amdgcn_s_setprio(1); _Pragma("unroll") for (int m = 0; m < 4; ++m) _Pragma("unroll") for (int n = 0; n < 2; ++n) _Pragma("unroll") for (int k = 0; k < 2; ++k) \
;         acc[ai][bj][m][n] = __builtin_amdgcn_mfma_f32_16x16x32_f16(Bt_[n][k], At[m][k], acc[ai][bj][m][n], 0, 0, 0); __builtin_amdgcn_s_setprio(0); } while (0)
; #define PG8_WAIT_V(n) asm volatile("s_waitcnt vmcnt(" #n ")" ::: "memory")
; #define PG8_WAIT_L(n) asm volatile("s_waitcnt lgkmcnt(" #n ")" ::: "memory")
; #define PG8_BAR __builtin_amdgcn_s_barrier()
; #define PG8_SCHED __builtin_amdgcn_sched_barrier(0)
; template <class Epi, class AMap>
; __device__ __forceinline__ void gemm_phase(LAS unsigned char* lds, const AMap am, const int lda, const h16* Bt, const int ldb, const int M, const int N, const int K, const Epi& E) {
;     ...
;             PG8_LDB(B1, 1, 1); PG8_STAGE(PG8_SB(1, 0), b3, voffB);
;             PG8_BAR; PG8_WAIT_L(0); PG8_MMA(0, 1, At, B1); PG8_BAR;
;             PG8_LDA(At, 1, 1); PG8_STAGE(PG8_SA(1, 0), a3, voffA);
;             PG8_BAR; PG8_WAIT_L(0); PG8_MMA(1, 0, At, B0); PG8_BAR; PG8_SCHED;
;             PG8_STAGE(PG8_SB(1, 1), b3 + hstepB, voffB);
;             PG8_WAIT_V(6); PG8_BAR; PG8_MMA(1, 1, At, B1); PG8_BAR;
;         }
;     ...
;     if (wr == 0) PG8_BAR;
	global_load_lds_dwordx4 v[152:153], off
	v_lshl_add_u64 v[152:153], v[206:207], 0, s[92:93]
	s_add_i32 m0, s22, 0x2000
	s_nop 0
	global_load_lds_dwordx4 v[152:153], off
	s_mov_b32 m0, s80
	v_lshl_add_u64 v[152:153], v[212:213], 0, s[92:93]
	ds_read_b128 v[162:165], v157 offset:49152
	ds_read_b128 v[166:169], v157 offset:50176
	ds_read_b128 v[170:173], v157 offset:51200
	ds_read_b128 v[174:177], v157 offset:52224
	ds_read_b128 v[178:181], v157 offset:53248
	ds_read_b128 v[182:185], v157 offset:54272
	ds_read_b128 v[186:189], v157 offset:55296
	ds_read_b128 v[190:193], v157 offset:56320
	global_load_lds_dwordx4 v[152:153], off
	v_lshl_add_u64 v[152:153], v[224:225], 0, s[92:93]
	s_mov_b32 m0, s81
	s_nop 0
	global_load_lds_dwordx4 v[152:153], off
	s_add_u32 s22, s26, 0x10080
	s_addc_u32 s23, s27, 0
	s_add_i32 s26, s48, s73
	v_lshl_add_u64 v[232:233], s[22:23], 0, v[0:1]
	s_mov_b32 m0, s26
	s_nop 0
	global_load_lds_dwordx4 v[232:233], off
	v_lshl_add_u64 v[232:233], s[22:23], 0, v[142:143]
	s_add_i32 m0, s26, 0x2000
	s_nop 0
	global_load_lds_dwordx4 v[232:233], off
	s_add_u32 s29, s29, 0x100
	s_addc_u32 s45, s45, 0
	s_cmp_ge_i32 s51, s24
	s_mov_b64 s[22:23], s[0:1]
	s_mov_b32 s26, s51
	s_waitcnt vmcnt(8) lgkmcnt(0)
	s_barrier
	v_mfma_f32_16x16x32_f16 v[102:105], v[90:93], v[162:165], v[102:105]
	v_mfma_f32_16x16x32_f16 v[98:101], v[148:151], v[162:165], v[98:101]
	v_mfma_f32_16x16x32_f16 v[86:89], v[90:93], v[170:173], v[86:89]
	v_mfma_f32_16x16x32_f16 v[82:85], v[148:151], v[170:173], v[82:85]
	v_mfma_f32_16x16x32_f16 v[78:81], v[90:93], v[178:181], v[78:81]
	v_mfma_f32_16x16x32_f16 v[74:77], v[148:151], v[178:181], v[74:77]
	v_mfma_f32_16x16x32_f16 v[70:73], v[90:93], v[186:189], v[70:73]
	v_mfma_f32_16x16x32_f16 v[66:69], v[148:151], v[186:189], v[66:69]
	v_mfma_f32_16x16x32_f16 v[102:105], v[94:97], v[166:169], v[102:105]
	v_mfma_f32_16x16x32_f16 v[98:101], v[158:161], v[166:169], v[98:101]
	v_mfma_f32_16x16x32_f16 v[86:89], v[94:97], v[174:177], v[86:89]
	v_mfma_f32_16x16x32_f16 v[82:85], v[158:161], v[174:177], v[82:85]
	v_mfma_f32_16x16x32_f16 v[78:81], v[94:97], v[182:185], v[78:81]
	v_mfma_f32_16x16x32_f16 v[74:77], v[158:161], v[182:185], v[74:77]
	v_mfma_f32_16x16x32_f16 v[70:73], v[94:97], v[190:193], v[70:73]
	v_mfma_f32_16x16x32_f16 v[66:69], v[158:161], v[190:193], v[66:69]
	v_mfma_f32_16x16x32_f16 v[30:33], v[194:197], v[162:165], v[30:33]
	v_mfma_f32_16x16x32_f16 v[26:29], v[202:205], v[162:165], v[26:29]
	v_mfma_f32_16x16x32_f16 v[22:25], v[194:197], v[170:173], v[22:25]
	v_mfma_f32_16x16x32_f16 v[18:21], v[202:205], v[170:173], v[18:21]
	v_mfma_f32_16x16x32_f16 v[14:17], v[194:197], v[178:181], v[14:17]
	v_mfma_f32_16x16x32_f16 v[10:13], v[202:205], v[178:181], v[10:13]
	v_mfma_f32_16x16x32_f16 v[6:9], v[194:197], v[186:189], v[6:9]
	v_mfma_f32_16x16x32_f16 v[2:5], v[202:205], v[186:189], v[2:5]
	v_mfma_f32_16x16x32_f16 v[30:33], v[198:201], v[166:169], v[30:33]
	v_mfma_f32_16x16x32_f16 v[26:29], v[220:223], v[166:169], v[26:29]
	v_mfma_f32_16x16x32_f16 v[22:25], v[198:201], v[174:177], v[22:25]
	v_mfma_f32_16x16x32_f16 v[18:21], v[220:223], v[174:177], v[18:21]
	v_mfma_f32_16x16x32_f16 v[14:17], v[198:201], v[182:185], v[14:17]
	v_mfma_f32_16x16x32_f16 v[10:13], v[220:223], v[182:185], v[10:13]
	v_mfma_f32_16x16x32_f16 v[6:9], v[198:201], v[190:193], v[6:9]
	v_mfma_f32_16x16x32_f16 v[2:5], v[220:223], v[190:193], v[2:5]
	s_barrier
	s_cbranch_scc0 .LBB0_621
	s_cmpk_gt_u32 s71, 0xff
	s_cbranch_scc1 .Lgx4
	s_barrier

; #define PG8_STAGE(bufoff, gbase, voff) do { _Pragma("unroll") for (int _i = 0; _i < 2; ++_i) \
;         __builtin_amdgcn_global_load_lds((const unsigned*)((const char*)(gbase) + (voff)[_i]), (LAS unsigned*)(lds + (bufoff) + ldsw + _i * 8192), 16, 0, 0); } while (0)
; #define PG8_LDA(dst, b, h) do { _Pragma("unroll") for (int m = 0; m < 4; ++m) _Pragma("unroll") for (int k = 0; k < 2; ++k) dst[m][k] = *(const LAS h16x8*)(lds + PG8_SA(b, h) + aoff + m * 2048 + k * 1024); } while (0)
; #define PG8_LDB(dst, b, h) do { _Pragma("unroll") for (int n = 0; n < 2; ++n) _Pragma("unroll") for (int k = 0; k < 2; ++k) dst[n][k] = *(const LAS h16x8*)(lds + PG8_SB(b, h) + boff + n * 2048 + k * 1024); } while (0)
; #define PG8_MMA(ai, bj, At, Bt_) do { __builtin_amdgcn_s_setprio(1); _Pragma("unroll") for (int m = 0; m < 4; ++m) _Pragma("unroll") for (int n = 0; n < 2; ++n) _Pragma("unroll") for (int k = 0; k < 2; ++k) \
;         acc[ai][bj][m][n] = __builtin_amdgcn_mfma_f32_16x16x32_f16(Bt_[n][k], At[m][k], acc[ai][bj][m][n], 0, 0, 0); __builtin_amdgcn_s_setprio(0); } while (0)
; #define PG8_WAIT_V(n) asm volatile("s_waitcnt vmcnt(" #n ")" ::: "memory")
; template <class Epi, class AMap>
; __device__ __forceinline__ void gemm_phase(LAS unsigned char* lds, const AMap am, const int lda, const h16* Bt, const int ldb, const int M, const int N, const int K, const Epi& E) {
;     ...
;         for (int t = 0; t < nt; t += 2) {
;             const bool last = (t == nt - 2);
;             const char* a1 = cA + (size_t)(t + 1) * kstep;
;             const char* a2 = last ? nA : cA + (size_t)(t + 2) * kstep; const char* b2 = last ? nB : cB + (size_t)(t + 2) * kstep;
;             const char* a3 = a2 + kstep; const char* b3 = b2 + kstep;
;             PG8_LDB(B0, 0, 0); PG8_SCHED; PG8_LDA(At, 0, 0); PG8_STAGE(PG8_SA(1, 1), a1 + hstepA, voffA);
;             PG8_WAIT_L(8); PG8_BAR; PG8_WAIT_L(0); PG8_MMA(0, 0, At, B0); PG8_BAR; PG8_SCHED;
;             PG8_LDB(B1, 0, 1); PG8_STAGE(PG8_SB(0, 0), b2, voffB);
;             PG8_BAR; PG8_WAIT_L(0); PG8_MMA(0, 1, At, B1); PG8_BAR;
;             PG8_LDA(At, 0, 1); PG8_STAGE(PG8_SA(0, 0), a2, voffA);
;             PG8_BAR; PG8_WAIT_L(0); PG8_MMA(1, 0, At, B0); PG8_BAR; PG8_SCHED;
;             PG8_STAGE(PG8_SB(0, 1), b2 + hstepB, voffB);
;             PG8_WAIT_V(6); PG8_BAR; PG8_MMA(1, 1, At, B1); PG8_BAR;
.LBB0_644:
	s_add_i32 s51, s26, 2
	s_add_u32 s0, s22, 0x100
	s_addc_u32 s1, s23, 0
	s_add_i32 s60, 0, 0x10000
	v_add_u32_e32 v234, s60, v203
	ds_read_b128 v[130:133], v234
	ds_read_b128 v[134:137], v234 offset:1024
	ds_read_b128 v[138:141], v234 offset:2048
	ds_read_b128 v[152:155], v234 offset:3072
	s_cmp_eq_u32 s80, s26
	s_cselect_b32 s26, s21, s29
	s_cselect_b32 s49, s47, s1
	s_cselect_b32 s48, s46, s0
	s_cselect_b32 s27, s20, s45
	v_lshl_add_u64 v[232:233], s[22:23], 0, v[148:149]
	s_add_i32 m0, s74, 0xc000
	ds_read_b128 v[156:159], v205
	ds_read_b128 v[160:163], v205 offset:1024
	ds_read_b128 v[164:167], v205 offset:2048
	ds_read_b128 v[168:171], v205 offset:3072
	ds_read_b128 v[172:175], v205 offset:4096
	ds_read_b128 v[176:179], v205 offset:5120
	ds_read_b128 v[180:183], v205 offset:6144
	ds_read_b128 v[184:187], v205 offset:7168
	global_load_lds_dwordx4 v[232:233], off
	v_lshl_add_u64 v[232:233], s[22:23], 0, v[150:151]
	s_add_i32 m0, s74, 0xe000
	s_nop 0
	global_load_lds_dwordx4 v[232:233], off
	s_waitcnt lgkmcnt(11)
	s_add_i32 s62, 0, 0x14000
	v_add_u32_e32 v200, s62, v203
	s_add_i32 s22, s60, s71
	ds_read_b128 v[188:191], v200
	ds_read_b128 v[192:195], v200 offset:1024
	ds_read_b128 v[196:199], v200 offset:2048
	ds_read_b128 v[220:223], v200 offset:3072
	s_waitcnt vmcnt(8) lgkmcnt(0)
	s_barrier
	v_mfma_f32_16x16x32_f16 v[122:125], v[130:133], v[156:159], v[122:125]
	v_mfma_f32_16x16x32_f16 v[126:129], v[138:141], v[156:159], v[126:129]
	v_mfma_f32_16x16x32_f16 v[110:113], v[130:133], v[164:167], v[110:113]
	v_mfma_f32_16x16x32_f16 v[106:109], v[138:141], v[164:167], v[106:109]
	v_mfma_f32_16x16x32_f16 v[94:97], v[130:133], v[172:175], v[94:97]
	v_mfma_f32_16x16x32_f16 v[90:93], v[138:141], v[172:175], v[90:93]
	v_mfma_f32_16x16x32_f16 v[78:81], v[130:133], v[180:183], v[78:81]
	v_mfma_f32_16x16x32_f16 v[74:77], v[138:141], v[180:183], v[74:77]
	v_mfma_f32_16x16x32_f16 v[122:125], v[134:137], v[160:163], v[122:125]
	v_mfma_f32_16x16x32_f16 v[126:129], v[152:155], v[160:163], v[126:129]
	v_mfma_f32_16x16x32_f16 v[110:113], v[134:137], v[168:171], v[110:113]
	v_mfma_f32_16x16x32_f16 v[106:109], v[152:155], v[168:171], v[106:109]
	v_mfma_f32_16x16x32_f16 v[94:97], v[134:137], v[176:179], v[94:97]
	v_mfma_f32_16x16x32_f16 v[90:93], v[152:155], v[176:179], v[90:93]
	v_mfma_f32_16x16x32_f16 v[78:81], v[134:137], v[184:187], v[78:81]
	v_mfma_f32_16x16x32_f16 v[74:77], v[152:155], v[184:187], v[74:77]
	v_mfma_f32_16x16x32_f16 v[118:121], v[188:191], v[156:159], v[118:121]
	v_mfma_f32_16x16x32_f16 v[114:117], v[196:199], v[156:159], v[114:117]
	v_mfma_f32_16x16x32_f16 v[102:105], v[188:191], v[164:167], v[102:105]
	v_mfma_f32_16x16x32_f16 v[98:101], v[196:199], v[164:167], v[98:101]
	v_mfma_f32_16x16x32_f16 v[86:89], v[188:191], v[172:175], v[86:89]
	v_mfma_f32_16x16x32_f16 v[82:85], v[196:199], v[172:175], v[82:85]
	v_mfma_f32_16x16x32_f16 v[70:73], v[188:191], v[180:183], v[70:73]
	v_mfma_f32_16x16x32_f16 v[66:69], v[196:199], v[180:183], v[66:69]
	v_mfma_f32_16x16x32_f16 v[118:121], v[192:195], v[160:163], v[118:121]
	v_mfma_f32_16x16x32_f16 v[114:117], v[220:223], v[160:163], v[114:117]
	v_mfma_f32_16x16x32_f16 v[102:105], v[192:195], v[168:171], v[102:105]
	v_mfma_f32_16x16x32_f16 v[98:101], v[220:223], v[168:171], v[98:101]
	v_mfma_f32_16x16x32_f16 v[86:89], v[192:195], v[176:179], v[86:89]
	v_mfma_f32_16x16x32_f16 v[82:85], v[220:223], v[176:179], v[82:85]
	v_mfma_f32_16x16x32_f16 v[70:73], v[192:195], v[184:187], v[70:73]
	v_mfma_f32_16x16x32_f16 v[66:69], v[220:223], v[184:187], v[66:69]
	s_barrier
	v_lshl_add_u64 v[200:201], s[26:27], 0, v[0:1]
	s_mov_b32 m0, s22
	v_lshl_add_u64 v[206:207], s[26:27], 0, v[146:147]
	global_load_lds_dwordx4 v[200:201], off
	s_add_i32 m0, s22, 0x2000
	s_nop 0
	global_load_lds_dwordx4 v[206:207], off
	s_mov_b32 m0, s74
	v_lshl_add_u64 v[212:213], s[48:49], 0, v[142:143]
	ds_read_b128 v[156:159], v205 offset:16384
	ds_read_b128 v[160:163], v205 offset:17408
	ds_read_b128 v[164:167], v205 offset:18432
	ds_read_b128 v[168:171], v205 offset:19456
	ds_read_b128 v[172:175], v205 offset:20480
	ds_read_b128 v[176:179], v205 offset:21504
	ds_read_b128 v[180:183], v205 offset:22528
	ds_read_b128 v[184:187], v205 offset:23552
	global_load_lds_dwordx4 v[212:213], off
	v_lshl_add_u64 v[224:225], s[48:49], 0, v[144:145]
	s_mov_b32 m0, s75
	s_nop 0
	global_load_lds_dwordx4 v[224:225], off
	s_waitcnt vmcnt(6) lgkmcnt(0)
	s_barrier
	v_mfma_f32_16x16x32_f16 v[62:65], v[130:133], v[156:159], v[62:65]
	v_mfma_f32_16x16x32_f16 v[58:61], v[138:141], v[156:159], v[58:61]
	v_mfma_f32_16x16x32_f16 v[46:49], v[130:133], v[164:167], v[46:49]
	v_mfma_f32_16x16x32_f16 v[42:45], v[138:141], v[164:167], v[42:45]
	v_mfma_f32_16x16x32_f16 v[30:33], v[130:133], v[172:175], v[30:33]
	v_mfma_f32_16x16x32_f16 v[26:29], v[138:141], v[172:175], v[26:29]
	v_mfma_f32_16x16x32_f16 v[14:17], v[130:133], v[180:183], v[14:17]
	v_mfma_f32_16x16x32_f16 v[10:13], v[138:141], v[180:183], v[10:13]
	v_mfma_f32_16x16x32_f16 v[62:65], v[134:137], v[160:163], v[62:65]
	v_mfma_f32_16x16x32_f16 v[58:61], v[152:155], v[160:163], v[58:61]
	v_mfma_f32_16x16x32_f16 v[46:49], v[134:137], v[168:171], v[46:49]
	v_mfma_f32_16x16x32_f16 v[42:45], v[152:155], v[168:171], v[42:45]
	v_mfma_f32_16x16x32_f16 v[30:33], v[134:137], v[176:179], v[30:33]
	v_mfma_f32_16x16x32_f16 v[26:29], v[152:155], v[176:179], v[26:29]
	v_mfma_f32_16x16x32_f16 v[14:17], v[134:137], v[184:187], v[14:17]
	v_mfma_f32_16x16x32_f16 v[10:13], v[152:155], v[184:187], v[10:13]
	v_mfma_f32_16x16x32_f16 v[54:57], v[188:191], v[156:159], v[54:57]
	v_mfma_f32_16x16x32_f16 v[50:53], v[196:199], v[156:159], v[50:53]
	v_mfma_f32_16x16x32_f16 v[38:41], v[188:191], v[164:167], v[38:41]
	v_mfma_f32_16x16x32_f16 v[34:37], v[196:199], v[164:167], v[34:37]
	v_mfma_f32_16x16x32_f16 v[22:25], v[188:191], v[172:175], v[22:25]
	v_mfma_f32_16x16x32_f16 v[18:21], v[196:199], v[172:175], v[18:21]
	v_mfma_f32_16x16x32_f16 v[6:9], v[188:191], v[180:183], v[6:9]
	v_mfma_f32_16x16x32_f16 v[2:5], v[196:199], v[180:183], v[2:5]
	v_mfma_f32_16x16x32_f16 v[54:57], v[192:195], v[160:163], v[54:57]
	v_mfma_f32_16x16x32_f16 v[50:53], v[220:223], v[160:163], v[50:53]
	v_mfma_f32_16x16x32_f16 v[38:41], v[192:195], v[168:171], v[38:41]
	v_mfma_f32_16x16x32_f16 v[34:37], v[220:223], v[168:171], v[34:37]
	v_mfma_f32_16x16x32_f16 v[22:25], v[192:195], v[176:179], v[22:25]
	v_mfma_f32_16x16x32_f16 v[18:21], v[220:223], v[176:179], v[18:21]
	v_mfma_f32_16x16x32_f16 v[6:9], v[192:195], v[184:187], v[6:9]
	v_mfma_f32_16x16x32_f16 v[2:5], v[220:223], v[184:187], v[2:5]
	s_barrier
; #define PG8_STAGE(bufoff, gbase, voff) do { _Pragma("unroll") for (int _i = 0; _i < 2; ++_i) \
;         __builtin_amdgcn_global_load_lds((const unsigned*)((const char*)(gbase) + (voff)[_i]), (LAS unsigned*)(lds + (bufoff) + ldsw + _i * 8192), 16, 0, 0); } while (0)
; #define PG8_LDA(dst, b, h) do { _Pragma("unroll") for (int m = 0; m < 4; ++m) _Pragma("unroll") for (int k = 0; k < 2; ++k) dst[m][k] = *(const LAS h16x8*)(lds + PG8_SA(b, h) + aoff + m * 2048 + k * 1024); } while (0)
; #define PG8_LDB(dst, b, h) do { _Pragma("unroll") for (int n = 0; n < 2; ++n) _Pragma("unroll") for (int k = 0; k < 2; ++k) dst[n][k] = *(const LAS h16x8*)(lds + PG8_SB(b, h) + boff + n * 2048 + k * 1024); } while (0)
; #define PG8_MMA(ai, bj, At, Bt_) do { __builtin_amdgcn_s_setprio(1); _Pragma("unroll") for (int m = 0; m < 4; ++m) _Pragma("unroll") for (int n = 0; n < 2; ++n) _Pragma("unroll") for (int k = 0; k < 2; ++k) \
;         acc[ai][bj][m][n] = __builtin_amdgcn_mfma_f32_16x16x32_f16(Bt_[n][k], At[m][k], acc[ai][bj][m][n], 0, 0, 0); __builtin_amdgcn_s_setprio(0); } while (0)
; #define PG8_WAIT_V(n) asm volatile("s_waitcnt vmcnt(" #n ")" ::: "memory")
; #define PG8_WAIT_L(n) asm volatile("s_waitcnt lgkmcnt(" #n ")" ::: "memory")
; #define PG8_BAR __builtin_amdgcn_s_barrier()
; #define PG8_SCHED __builtin_amdgcn_sched_barrier(0)
; template <class Epi, class AMap>
; __device__ __forceinline__ void gemm_phase(LAS unsigned char* lds, const AMap am, const int lda, const h16* Bt, const int ldb, const int M, const int N, const int K, const Epi& E) {
;     ...
;             PG8_STAGE(PG8_SB(0, 1), b2 + hstepB, voffB);
;             PG8_WAIT_V(6); PG8_BAR; PG8_MMA(1, 1, At, B1); PG8_BAR;
;             PG8_LDB(B0, 1, 0); PG8_SCHED; PG8_LDA(At, 1, 0); PG8_STAGE(PG8_SA(0, 1), a2 + hstepA, voffA);
;             PG8_WAIT_L(8); PG8_BAR; PG8_WAIT_L(0); PG8_MMA(0, 0, At, B0); PG8_BAR; PG8_SCHED;
;             PG8_LDB(B1, 1, 1); PG8_STAGE(PG8_SB(1, 0), b3, voffB);
;             PG8_BAR; PG8_WAIT_L(0); PG8_MMA(0, 1, At, B1); PG8_BAR;
	s_add_u32 s22, s26, 0x10000
	s_addc_u32 s23, s27, 0
	s_add_i32 s60, s62, s71
	v_lshl_add_u64 v[232:233], s[22:23], 0, v[0:1]
	s_mov_b32 m0, s60
	s_nop 0
	global_load_lds_dwordx4 v[232:233], off
	v_lshl_add_u64 v[232:233], s[22:23], 0, v[146:147]
	s_add_i32 m0, s60, 0x2000
	s_nop 0
	global_load_lds_dwordx4 v[232:233], off
	s_add_i32 s60, 0, 0x18000
	v_add_u32_e32 v234, s60, v203
	ds_read_b128 v[130:133], v234
	ds_read_b128 v[134:137], v234 offset:1024
	ds_read_b128 v[138:141], v234 offset:2048
	ds_read_b128 v[152:155], v234 offset:3072
	s_add_u32 s22, s48, 0x1c0000
	s_addc_u32 s23, s49, 0
	s_mov_b32 m0, s76
	v_lshl_add_u64 v[232:233], s[22:23], 0, v[142:143]
	ds_read_b128 v[156:159], v205 offset:32768
	ds_read_b128 v[160:163], v205 offset:33792
	ds_read_b128 v[164:167], v205 offset:34816
	ds_read_b128 v[168:171], v205 offset:35840
	ds_read_b128 v[172:175], v205 offset:36864
	ds_read_b128 v[176:179], v205 offset:37888
	ds_read_b128 v[180:183], v205 offset:38912
	ds_read_b128 v[184:187], v205 offset:39936
	global_load_lds_dwordx4 v[232:233], off
	v_lshl_add_u64 v[232:233], s[22:23], 0, v[144:145]
	s_mov_b32 m0, s77
	s_nop 0
	global_load_lds_dwordx4 v[232:233], off
	s_waitcnt lgkmcnt(11)
	s_add_i32 s48, 0, 0x1c000
	s_add_i32 s22, s60, s71
	v_add_u32_e32 v214, s48, v203
	v_lshl_add_u64 v[200:201], v[200:201], 0, s[92:93]
	s_mov_b32 m0, s22
	ds_read_b128 v[188:191], v214
	ds_read_b128 v[192:195], v214 offset:1024
	ds_read_b128 v[196:199], v214 offset:2048
	ds_read_b128 v[220:223], v214 offset:3072
	s_waitcnt vmcnt(8) lgkmcnt(0)
	s_barrier
	v_mfma_f32_16x16x32_f16 v[122:125], v[130:133], v[156:159], v[122:125]
	v_mfma_f32_16x16x32_f16 v[126:129], v[138:141], v[156:159], v[126:129]
	v_mfma_f32_16x16x32_f16 v[110:113], v[130:133], v[164:167], v[110:113]
	v_mfma_f32_16x16x32_f16 v[106:109], v[138:141], v[164:167], v[106:109]
	v_mfma_f32_16x16x32_f16 v[94:97], v[130:133], v[172:175], v[94:97]
	v_mfma_f32_16x16x32_f16 v[90:93], v[138:141], v[172:175], v[90:93]
	v_mfma_f32_16x16x32_f16 v[78:81], v[130:133], v[180:183], v[78:81]
	v_mfma_f32_16x16x32_f16 v[74:77], v[138:141], v[180:183], v[74:77]
	v_mfma_f32_16x16x32_f16 v[122:125], v[134:137], v[160:163], v[122:125]
	v_mfma_f32_16x16x32_f16 v[126:129], v[152:155], v[160:163], v[126:129]
	v_mfma_f32_16x16x32_f16 v[110:113], v[134:137], v[168:171], v[110:113]
	v_mfma_f32_16x16x32_f16 v[106:109], v[152:155], v[168:171], v[106:109]
	v_mfma_f32_16x16x32_f16 v[94:97], v[134:137], v[176:179], v[94:97]
	v_mfma_f32_16x16x32_f16 v[90:93], v[152:155], v[176:179], v[90:93]
	v_mfma_f32_16x16x32_f16 v[78:81], v[134:137], v[184:187], v[78:81]
	v_mfma_f32_16x16x32_f16 v[74:77], v[152:155], v[184:187], v[74:77]
	v_mfma_f32_16x16x32_f16 v[118:121], v[188:191], v[156:159], v[118:121]
	v_mfma_f32_16x16x32_f16 v[114:117], v[196:199], v[156:159], v[114:117]
	v_mfma_f32_16x16x32_f16 v[102:105], v[188:191], v[164:167], v[102:105]
	v_mfma_f32_16x16x32_f16 v[98:101], v[196:199], v[164:167], v[98:101]
	v_mfma_f32_16x16x32_f16 v[86:89], v[188:191], v[172:175], v[86:89]
	v_mfma_f32_16x16x32_f16 v[82:85], v[196:199], v[172:175], v[82:85]
	v_mfma_f32_16x16x32_f16 v[70:73], v[188:191], v[180:183], v[70:73]
	v_mfma_f32_16x16x32_f16 v[66:69], v[196:199], v[180:183], v[66:69]
	v_mfma_f32_16x16x32_f16 v[118:121], v[192:195], v[160:163], v[118:121]
	v_mfma_f32_16x16x32_f16 v[114:117], v[220:223], v[160:163], v[114:117]
	v_mfma_f32_16x16x32_f16 v[102:105], v[192:195], v[168:171], v[102:105]
	v_mfma_f32_16x16x32_f16 v[98:101], v[220:223], v[168:171], v[98:101]
	v_mfma_f32_16x16x32_f16 v[86:89], v[192:195], v[176:179], v[86:89]
	v_mfma_f32_16x16x32_f16 v[82:85], v[220:223], v[176:179], v[82:85]
	v_mfma_f32_16x16x32_f16 v[70:73], v[192:195], v[184:187], v[70:73]
	v_mfma_f32_16x16x32_f16 v[66:69], v[220:223], v[184:187], v[66:69]
	s_barrier
; #define PG8_STAGE(bufoff, gbase, voff) do { _Pragma("unroll") for (int _i = 0; _i < 2; ++_i) \
;         __builtin_amdgcn_global_load_lds((const unsigned*)((const char*)(gbase) + (voff)[_i]), (LAS unsigned*)(lds + (bufoff) + ldsw + _i * 8192), 16, 0, 0); } while (0)
; #define PG8_LDA(dst, b, h) do { _Pragma("unroll") for (int m = 0; m < 4; ++m) _Pragma("unroll") for (int k = 0; k < 2; ++k) dst[m][k] = *(const LAS h16x8*)(lds + PG8_SA(b, h) + aoff + m * 2048 + k * 1024); } while (0)
; #define PG8_LDB(dst, b, h) do { _Pragma("unroll") for (int n = 0; n < 2; ++n) _Pragma("unroll") for (int k = 0; k < 2; ++k) dst[n][k] = *(const LAS h16x8*)(lds + PG8_SB(b, h) + boff + n * 2048 + k * 1024); } while (0)
; #define PG8_MMA(ai, bj, At, Bt_) do { __builtin_amdgcn_s_setprio(1); _Pragma("unroll") for (int m = 0; m < 4; ++m) _Pragma("unroll") for (int n = 0; n < 2; ++n) _Pragma("unroll") for (int k = 0; k < 2; ++k) \
;         acc[ai][bj][m][n] = __builtin_amdgcn_mfma_f32_16x16x32_f16(Bt_[n][k], At[m][k], acc[ai][bj][m][n], 0, 0, 0); __builtin_amdgcn_s_setprio(0); } while (0)
; #define PG8_WAIT_V(n) asm volatile("s_waitcnt vmcnt(" #n ")" ::: "memory")
; #define PG8_WAIT_L(n) asm volatile("s_waitcnt lgkmcnt(" #n ")" ::: "memory")
; #define PG8_BAR __builtin_amdgcn_s_barrier()
; #define PG8_SCHED __builtin_amdgcn_sched_barrier(0)
; template <class Epi, class AMap>
; __device__ __forceinline__ void gemm_phase(LAS unsigned char* lds, const AMap am, const int lda, const h16* Bt, const int ldb, const int M, const int N, const int K, const Epi& E) {
;     ...
;             PG8_LDB(B1, 1, 1); PG8_STAGE(PG8_SB(1, 0), b3, voffB);
;             PG8_BAR; PG8_WAIT_L(0); PG8_MMA(0, 1, At, B1); PG8_BAR;
;             PG8_LDA(At, 1, 1); PG8_STAGE(PG8_SA(1, 0), a3, voffA);
;             PG8_BAR; PG8_WAIT_L(0); PG8_MMA(1, 0, At, B0); PG8_BAR; PG8_SCHED;
;             PG8_STAGE(PG8_SB(1, 1), b3 + hstepB, voffB);
;             PG8_WAIT_V(6); PG8_BAR; PG8_MMA(1, 1, At, B1); PG8_BAR;
;         }
;     ...
;     if (wr == 0) PG8_BAR;
	global_load_lds_dwordx4 v[200:201], off
	v_lshl_add_u64 v[200:201], v[206:207], 0, s[92:93]
	s_add_i32 m0, s22, 0x2000
	s_nop 0
	global_load_lds_dwordx4 v[200:201], off
	s_mov_b32 m0, s78
	v_lshl_add_u64 v[200:201], v[212:213], 0, s[92:93]
	ds_read_b128 v[156:159], v205 offset:49152
	ds_read_b128 v[160:163], v205 offset:50176
	ds_read_b128 v[164:167], v205 offset:51200
	ds_read_b128 v[168:171], v205 offset:52224
	ds_read_b128 v[172:175], v205 offset:53248
	ds_read_b128 v[176:179], v205 offset:54272
	ds_read_b128 v[180:183], v205 offset:55296
	ds_read_b128 v[184:187], v205 offset:56320
	global_load_lds_dwordx4 v[200:201], off
	v_lshl_add_u64 v[200:201], v[224:225], 0, s[92:93]
	s_mov_b32 m0, s79
	s_nop 0
	global_load_lds_dwordx4 v[200:201], off
	s_add_u32 s22, s26, 0x10080
	s_addc_u32 s23, s27, 0
	s_add_i32 s26, s48, s71
	v_lshl_add_u64 v[232:233], s[22:23], 0, v[0:1]
	s_mov_b32 m0, s26
	s_nop 0
	global_load_lds_dwordx4 v[232:233], off
	v_lshl_add_u64 v[232:233], s[22:23], 0, v[146:147]
	s_add_i32 m0, s26, 0x2000
	s_nop 0
	global_load_lds_dwordx4 v[232:233], off
	s_add_u32 s29, s29, 0x100
	s_addc_u32 s45, s45, 0
	s_cmp_ge_i32 s51, s24
	s_mov_b64 s[22:23], s[0:1]
	s_mov_b32 s26, s51
	s_waitcnt vmcnt(8) lgkmcnt(0)
	s_barrier
	v_mfma_f32_16x16x32_f16 v[62:65], v[130:133], v[156:159], v[62:65]
	v_mfma_f32_16x16x32_f16 v[58:61], v[138:141], v[156:159], v[58:61]
	v_mfma_f32_16x16x32_f16 v[46:49], v[130:133], v[164:167], v[46:49]
	v_mfma_f32_16x16x32_f16 v[42:45], v[138:141], v[164:167], v[42:45]
	v_mfma_f32_16x16x32_f16 v[30:33], v[130:133], v[172:175], v[30:33]
	v_mfma_f32_16x16x32_f16 v[26:29], v[138:141], v[172:175], v[26:29]
	v_mfma_f32_16x16x32_f16 v[14:17], v[130:133], v[180:183], v[14:17]
	v_mfma_f32_16x16x32_f16 v[10:13], v[138:141], v[180:183], v[10:13]
	v_mfma_f32_16x16x32_f16 v[62:65], v[134:137], v[160:163], v[62:65]
	v_mfma_f32_16x16x32_f16 v[58:61], v[152:155], v[160:163], v[58:61]
	v_mfma_f32_16x16x32_f16 v[46:49], v[134:137], v[168:171], v[46:49]
	v_mfma_f32_16x16x32_f16 v[42:45], v[152:155], v[168:171], v[42:45]
	v_mfma_f32_16x16x32_f16 v[30:33], v[134:137], v[176:179], v[30:33]
	v_mfma_f32_16x16x32_f16 v[26:29], v[152:155], v[176:179], v[26:29]
	v_mfma_f32_16x16x32_f16 v[14:17], v[134:137], v[184:187], v[14:17]
	v_mfma_f32_16x16x32_f16 v[10:13], v[152:155], v[184:187], v[10:13]
	v_mfma_f32_16x16x32_f16 v[54:57], v[188:191], v[156:159], v[54:57]
	v_mfma_f32_16x16x32_f16 v[50:53], v[196:199], v[156:159], v[50:53]
	v_mfma_f32_16x16x32_f16 v[38:41], v[188:191], v[164:167], v[38:41]
	v_mfma_f32_16x16x32_f16 v[34:37], v[196:199], v[164:167], v[34:37]
	v_mfma_f32_16x16x32_f16 v[22:25], v[188:191], v[172:175], v[22:25]
	v_mfma_f32_16x16x32_f16 v[18:21], v[196:199], v[172:175], v[18:21]
	v_mfma_f32_16x16x32_f16 v[6:9], v[188:191], v[180:183], v[6:9]
	v_mfma_f32_16x16x32_f16 v[2:5], v[196:199], v[180:183], v[2:5]
	v_mfma_f32_16x16x32_f16 v[54:57], v[192:195], v[160:163], v[54:57]
	v_mfma_f32_16x16x32_f16 v[50:53], v[220:223], v[160:163], v[50:53]
	v_mfma_f32_16x16x32_f16 v[38:41], v[192:195], v[168:171], v[38:41]
	v_mfma_f32_16x16x32_f16 v[34:37], v[220:223], v[168:171], v[34:37]
	v_mfma_f32_16x16x32_f16 v[22:25], v[192:195], v[176:179], v[22:25]
	v_mfma_f32_16x16x32_f16 v[18:21], v[220:223], v[176:179], v[18:21]
	v_mfma_f32_16x16x32_f16 v[6:9], v[192:195], v[184:187], v[6:9]
	v_mfma_f32_16x16x32_f16 v[2:5], v[220:223], v[184:187], v[2:5]
	s_barrier
	s_cbranch_scc0 .LBB0_644
	s_cmpk_gt_u32 s69, 0xff
	s_cbranch_scc1 .Lgx5
	s_barrier

; #define PG8_STAGE(bufoff, gbase, voff) do { _Pragma("unroll") for (int _i = 0; _i < 2; ++_i) \
;         __builtin_amdgcn_global_load_lds((const unsigned*)((const char*)(gbase) + (voff)[_i]), (LAS unsigned*)(lds + (bufoff) + ldsw + _i * 8192), 16, 0, 0); } while (0)
; #define PG8_LDA(dst, b, h) do { _Pragma("unroll") for (int m = 0; m < 4; ++m) _Pragma("unroll") for (int k = 0; k < 2; ++k) dst[m][k] = *(const LAS h16x8*)(lds + PG8_SA(b, h) + aoff + m * 2048 + k * 1024); } while (0)
; #define PG8_LDB(dst, b, h) do { _Pragma("unroll") for (int n = 0; n < 2; ++n) _Pragma("unroll") for (int k = 0; k < 2; ++k) dst[n][k] = *(const LAS h16x8*)(lds + PG8_SB(b, h) + boff + n * 2048 + k * 1024); } while (0)
; #define PG8_MMA(ai, bj, At, Bt_) do { __builtin_amdgcn_s_setprio(1); _Pragma("unroll") for (int m = 0; m < 4; ++m) _Pragma("unroll") for (int n = 0; n < 2; ++n) _Pragma("unroll") for (int k = 0; k < 2; ++k) \
;         acc[ai][bj][m][n] = __builtin_amdgcn_mfma_f32_16x16x32_f16(Bt_[n][k], At[m][k], acc[ai][bj][m][n], 0, 0, 0); __builtin_amdgcn_s_setprio(0); } while (0)
; #define PG8_WAIT_V(n) asm volatile("s_waitcnt vmcnt(" #n ")" ::: "memory")
; template <class Epi, class AMap>
; __device__ __forceinline__ void gemm_phase(LAS unsigned char* lds, const AMap am, const int lda, const h16* Bt, const int ldb, const int M, const int N, const int K, const Epi& E) {
;     ...
;         for (int t = 0; t < nt; t += 2) {
;             const bool last = (t == nt - 2);
;             const char* a1 = cA + (size_t)(t + 1) * kstep;
;             const char* a2 = last ? nA : cA + (size_t)(t + 2) * kstep; const char* b2 = last ? nB : cB + (size_t)(t + 2) * kstep;
;             const char* a3 = a2 + kstep; const char* b3 = b2 + kstep;
;             PG8_LDB(B0, 0, 0); PG8_SCHED; PG8_LDA(At, 0, 0); PG8_STAGE(PG8_SA(1, 1), a1 + hstepA, voffA);
;             PG8_WAIT_L(8); PG8_BAR; PG8_WAIT_L(0); PG8_MMA(0, 0, At, B0); PG8_BAR; PG8_SCHED;
;             PG8_LDB(B1, 0, 1); PG8_STAGE(PG8_SB(0, 0), b2, voffB);
;             PG8_BAR; PG8_WAIT_L(0); PG8_MMA(0, 1, At, B1); PG8_BAR;
;             PG8_LDA(At, 0, 1); PG8_STAGE(PG8_SA(0, 0), a2, voffA);
;             PG8_BAR; PG8_WAIT_L(0); PG8_MMA(1, 0, At, B0); PG8_BAR; PG8_SCHED;
;             PG8_STAGE(PG8_SB(0, 1), b2 + hstepB, voffB);
;             PG8_WAIT_V(6); PG8_BAR; PG8_MMA(1, 1, At, B1); PG8_BAR;
.LBB0_667:
	s_add_i32 s60, s46, 2
	s_add_u32 s0, s44, 0x100
	s_addc_u32 s1, s45, 0
	s_add_i32 s66, 0, 0x10000
	v_add_u32_e32 v234, s66, v161
	ds_read_b128 v[140:143], v234
	ds_read_b128 v[144:147], v234 offset:1024
	ds_read_b128 v[148:151], v234 offset:2048
	ds_read_b128 v[152:155], v234 offset:3072
	s_cmp_eq_u32 s73, s46
	s_cselect_b32 s46, s21, s27
	s_cselect_b32 s49, s41, s1
	s_cselect_b32 s48, s40, s0
	s_cselect_b32 s47, s20, s29
	v_lshl_add_u64 v[232:233], s[44:45], 0, v[136:137]
	s_add_i32 m0, s65, 0xc000
	ds_read_b128 v[156:159], v163
	ds_read_b128 v[164:167], v163 offset:1024
	ds_read_b128 v[168:171], v163 offset:2048
	ds_read_b128 v[172:175], v163 offset:3072
	ds_read_b128 v[176:179], v163 offset:4096
	ds_read_b128 v[180:183], v163 offset:5120
	ds_read_b128 v[184:187], v163 offset:6144
	ds_read_b128 v[188:191], v163 offset:7168
	global_load_lds_dwordx4 v[232:233], off
	v_lshl_add_u64 v[232:233], s[44:45], 0, v[138:139]
	s_add_i32 m0, s65, 0xe000
	s_nop 0
	global_load_lds_dwordx4 v[232:233], off
	s_waitcnt lgkmcnt(11)
	s_add_i32 s78, 0, 0x14000
	s_add_i32 s44, s66, s62
	v_add_u32_e32 v234, s78, v161
	v_lshl_add_u64 v[212:213], s[46:47], 0, v[0:1]
	s_mov_b32 m0, s44
	ds_read_b128 v[192:195], v234
	ds_read_b128 v[196:199], v234 offset:1024
	ds_read_b128 v[200:203], v234 offset:2048
	ds_read_b128 v[204:207], v234 offset:3072
	s_waitcnt vmcnt(8) lgkmcnt(0)
	s_barrier
	v_mfma_f32_16x16x32_f16 v[126:129], v[140:143], v[156:159], v[126:129]
	v_mfma_f32_16x16x32_f16 v[122:125], v[148:151], v[156:159], v[122:125]
	v_mfma_f32_16x16x32_f16 v[118:121], v[140:143], v[168:171], v[118:121]
	v_mfma_f32_16x16x32_f16 v[114:117], v[148:151], v[168:171], v[114:117]
	v_mfma_f32_16x16x32_f16 v[110:113], v[140:143], v[176:179], v[110:113]
	v_mfma_f32_16x16x32_f16 v[106:109], v[148:151], v[176:179], v[106:109]
	v_mfma_f32_16x16x32_f16 v[102:105], v[140:143], v[184:187], v[102:105]
	v_mfma_f32_16x16x32_f16 v[98:101], v[148:151], v[184:187], v[98:101]
	v_mfma_f32_16x16x32_f16 v[126:129], v[144:147], v[164:167], v[126:129]
	v_mfma_f32_16x16x32_f16 v[122:125], v[152:155], v[164:167], v[122:125]
	v_mfma_f32_16x16x32_f16 v[118:121], v[144:147], v[172:175], v[118:121]
	v_mfma_f32_16x16x32_f16 v[114:117], v[152:155], v[172:175], v[114:117]
	v_mfma_f32_16x16x32_f16 v[110:113], v[144:147], v[180:183], v[110:113]
	v_mfma_f32_16x16x32_f16 v[106:109], v[152:155], v[180:183], v[106:109]
	v_mfma_f32_16x16x32_f16 v[102:105], v[144:147], v[188:191], v[102:105]
	v_mfma_f32_16x16x32_f16 v[98:101], v[152:155], v[188:191], v[98:101]
	v_mfma_f32_16x16x32_f16 v[94:97], v[192:195], v[156:159], v[94:97]
	v_mfma_f32_16x16x32_f16 v[86:89], v[200:203], v[156:159], v[86:89]
	v_mfma_f32_16x16x32_f16 v[78:81], v[192:195], v[168:171], v[78:81]
	v_mfma_f32_16x16x32_f16 v[70:73], v[200:203], v[168:171], v[70:73]
	v_mfma_f32_16x16x32_f16 v[62:65], v[192:195], v[176:179], v[62:65]
	v_mfma_f32_16x16x32_f16 v[54:57], v[200:203], v[176:179], v[54:57]
	v_mfma_f32_16x16x32_f16 v[46:49], v[192:195], v[184:187], v[46:49]
	v_mfma_f32_16x16x32_f16 v[38:41], v[200:203], v[184:187], v[38:41]
	v_mfma_f32_16x16x32_f16 v[94:97], v[196:199], v[164:167], v[94:97]
	v_mfma_f32_16x16x32_f16 v[86:89], v[204:207], v[164:167], v[86:89]
	v_mfma_f32_16x16x32_f16 v[78:81], v[196:199], v[172:175], v[78:81]
	v_mfma_f32_16x16x32_f16 v[70:73], v[204:207], v[172:175], v[70:73]
	v_mfma_f32_16x16x32_f16 v[62:65], v[196:199], v[180:183], v[62:65]
	v_mfma_f32_16x16x32_f16 v[54:57], v[204:207], v[180:183], v[54:57]
	v_mfma_f32_16x16x32_f16 v[46:49], v[196:199], v[188:191], v[46:49]
	v_mfma_f32_16x16x32_f16 v[38:41], v[204:207], v[188:191], v[38:41]
	s_barrier
	global_load_lds_dwordx4 v[212:213], off
	v_lshl_add_u64 v[220:221], s[46:47], 0, v[134:135]
	s_add_i32 m0, s44, 0x2000
	s_nop 0
	global_load_lds_dwordx4 v[220:221], off
	s_mov_b32 m0, s65
	v_lshl_add_u64 v[222:223], s[48:49], 0, v[130:131]
	ds_read_b128 v[156:159], v163 offset:16384
	ds_read_b128 v[164:167], v163 offset:17408
	ds_read_b128 v[168:171], v163 offset:18432
	ds_read_b128 v[172:175], v163 offset:19456
	ds_read_b128 v[176:179], v163 offset:20480
	ds_read_b128 v[180:183], v163 offset:21504
	ds_read_b128 v[184:187], v163 offset:22528
	ds_read_b128 v[188:191], v163 offset:23552
	global_load_lds_dwordx4 v[222:223], off
	v_lshl_add_u64 v[224:225], s[48:49], 0, v[132:133]
	s_mov_b32 m0, s68
	s_nop 0
	global_load_lds_dwordx4 v[224:225], off
	s_waitcnt vmcnt(6) lgkmcnt(0)
	s_barrier
	v_mfma_f32_16x16x32_f16 v[90:93], v[140:143], v[156:159], v[90:93]
	v_mfma_f32_16x16x32_f16 v[82:85], v[148:151], v[156:159], v[82:85]
	v_mfma_f32_16x16x32_f16 v[74:77], v[140:143], v[168:171], v[74:77]
	v_mfma_f32_16x16x32_f16 v[66:69], v[148:151], v[168:171], v[66:69]
	v_mfma_f32_16x16x32_f16 v[58:61], v[140:143], v[176:179], v[58:61]
	v_mfma_f32_16x16x32_f16 v[50:53], v[148:151], v[176:179], v[50:53]
	v_mfma_f32_16x16x32_f16 v[42:45], v[140:143], v[184:187], v[42:45]
	v_mfma_f32_16x16x32_f16 v[34:37], v[148:151], v[184:187], v[34:37]
	v_mfma_f32_16x16x32_f16 v[90:93], v[144:147], v[164:167], v[90:93]
	v_mfma_f32_16x16x32_f16 v[82:85], v[152:155], v[164:167], v[82:85]
	v_mfma_f32_16x16x32_f16 v[74:77], v[144:147], v[172:175], v[74:77]
	v_mfma_f32_16x16x32_f16 v[66:69], v[152:155], v[172:175], v[66:69]
	v_mfma_f32_16x16x32_f16 v[58:61], v[144:147], v[180:183], v[58:61]
	v_mfma_f32_16x16x32_f16 v[50:53], v[152:155], v[180:183], v[50:53]
	v_mfma_f32_16x16x32_f16 v[42:45], v[144:147], v[188:191], v[42:45]
	v_mfma_f32_16x16x32_f16 v[34:37], v[152:155], v[188:191], v[34:37]
	v_mfma_f32_16x16x32_f16 v[30:33], v[192:195], v[156:159], v[30:33]
	v_mfma_f32_16x16x32_f16 v[26:29], v[200:203], v[156:159], v[26:29]
	v_mfma_f32_16x16x32_f16 v[22:25], v[192:195], v[168:171], v[22:25]
	v_mfma_f32_16x16x32_f16 v[18:21], v[200:203], v[168:171], v[18:21]
	v_mfma_f32_16x16x32_f16 v[14:17], v[192:195], v[176:179], v[14:17]
	v_mfma_f32_16x16x32_f16 v[10:13], v[200:203], v[176:179], v[10:13]
	v_mfma_f32_16x16x32_f16 v[6:9], v[192:195], v[184:187], v[6:9]
	v_mfma_f32_16x16x32_f16 v[2:5], v[200:203], v[184:187], v[2:5]
	v_mfma_f32_16x16x32_f16 v[30:33], v[196:199], v[164:167], v[30:33]
	v_mfma_f32_16x16x32_f16 v[26:29], v[204:207], v[164:167], v[26:29]
	v_mfma_f32_16x16x32_f16 v[22:25], v[196:199], v[172:175], v[22:25]
	v_mfma_f32_16x16x32_f16 v[18:21], v[204:207], v[172:175], v[18:21]
	v_mfma_f32_16x16x32_f16 v[14:17], v[196:199], v[180:183], v[14:17]
	v_mfma_f32_16x16x32_f16 v[10:13], v[204:207], v[180:183], v[10:13]
	v_mfma_f32_16x16x32_f16 v[6:9], v[196:199], v[188:191], v[6:9]
	v_mfma_f32_16x16x32_f16 v[2:5], v[204:207], v[188:191], v[2:5]
	s_barrier
; #define PG8_STAGE(bufoff, gbase, voff) do { _Pragma("unroll") for (int _i = 0; _i < 2; ++_i) \
;         __builtin_amdgcn_global_load_lds((const unsigned*)((const char*)(gbase) + (voff)[_i]), (LAS unsigned*)(lds + (bufoff) + ldsw + _i * 8192), 16, 0, 0); } while (0)
; #define PG8_LDA(dst, b, h) do { _Pragma("unroll") for (int m = 0; m < 4; ++m) _Pragma("unroll") for (int k = 0; k < 2; ++k) dst[m][k] = *(const LAS h16x8*)(lds + PG8_SA(b, h) + aoff + m * 2048 + k * 1024); } while (0)
; #define PG8_LDB(dst, b, h) do { _Pragma("unroll") for (int n = 0; n < 2; ++n) _Pragma("unroll") for (int k = 0; k < 2; ++k) dst[n][k] = *(const LAS h16x8*)(lds + PG8_SB(b, h) + boff + n * 2048 + k * 1024); } while (0)
; #define PG8_MMA(ai, bj, At, Bt_) do { __builtin_amdgcn_s_setprio(1); _Pragma("unroll") for (int m = 0; m < 4; ++m) _Pragma("unroll") for (int n = 0; n < 2; ++n) _Pragma("unroll") for (int k = 0; k < 2; ++k) \
;         acc[ai][bj][m][n] = __builtin_amdgcn_mfma_f32_16x16x32_f16(Bt_[n][k], At[m][k], acc[ai][bj][m][n], 0, 0, 0); __builtin_amdgcn_s_setprio(0); } while (0)
; #define PG8_WAIT_V(n) asm volatile("s_waitcnt vmcnt(" #n ")" ::: "memory")
; #define PG8_WAIT_L(n) asm volatile("s_waitcnt lgkmcnt(" #n ")" ::: "memory")
; #define PG8_BAR __builtin_amdgcn_s_barrier()
; #define PG8_SCHED __builtin_amdgcn_sched_barrier(0)
; template <class Epi, class AMap>
; __device__ __forceinline__ void gemm_phase(LAS unsigned char* lds, const AMap am, const int lda, const h16* Bt, const int ldb, const int M, const int N, const int K, const Epi& E) {
;     ...
;             PG8_STAGE(PG8_SB(0, 1), b2 + hstepB, voffB);
;             PG8_WAIT_V(6); PG8_BAR; PG8_MMA(1, 1, At, B1); PG8_BAR;
;             PG8_LDB(B0, 1, 0); PG8_SCHED; PG8_LDA(At, 1, 0); PG8_STAGE(PG8_SA(0, 1), a2 + hstepA, voffA);
;             PG8_WAIT_L(8); PG8_BAR; PG8_WAIT_L(0); PG8_MMA(0, 0, At, B0); PG8_BAR; PG8_SCHED;
;             PG8_LDB(B1, 1, 1); PG8_STAGE(PG8_SB(1, 0), b3, voffB);
;             PG8_BAR; PG8_WAIT_L(0); PG8_MMA(0, 1, At, B1); PG8_BAR;
	s_add_u32 s44, s46, 0x10000
	s_addc_u32 s45, s47, 0
	s_add_i32 s66, s78, s62
	v_lshl_add_u64 v[232:233], s[44:45], 0, v[0:1]
	s_mov_b32 m0, s66
	s_nop 0
	global_load_lds_dwordx4 v[232:233], off
	v_lshl_add_u64 v[232:233], s[44:45], 0, v[134:135]
	s_add_i32 m0, s66, 0x2000
	s_nop 0
	global_load_lds_dwordx4 v[232:233], off
	s_add_i32 s66, 0, 0x18000
	v_add_u32_e32 v234, s66, v161
	ds_read_b128 v[140:143], v234
	ds_read_b128 v[144:147], v234 offset:1024
	ds_read_b128 v[148:151], v234 offset:2048
	ds_read_b128 v[152:155], v234 offset:3072
	s_add_u32 s44, s48, 0x1c0000
	s_addc_u32 s45, s49, 0
	s_mov_b32 m0, s69
	v_lshl_add_u64 v[232:233], s[44:45], 0, v[130:131]
	ds_read_b128 v[156:159], v163 offset:32768
	ds_read_b128 v[164:167], v163 offset:33792
	ds_read_b128 v[168:171], v163 offset:34816
	ds_read_b128 v[172:175], v163 offset:35840
	ds_read_b128 v[176:179], v163 offset:36864
	ds_read_b128 v[180:183], v163 offset:37888
	ds_read_b128 v[184:187], v163 offset:38912
	ds_read_b128 v[188:191], v163 offset:39936
	global_load_lds_dwordx4 v[232:233], off
	v_lshl_add_u64 v[232:233], s[44:45], 0, v[132:133]
	s_mov_b32 m0, s70
	s_nop 0
	global_load_lds_dwordx4 v[232:233], off
	s_waitcnt lgkmcnt(11)
	s_add_i32 s48, 0, 0x1c000
	s_add_i32 s44, s66, s62
	v_add_u32_e32 v234, s48, v161
	v_lshl_add_u64 v[212:213], v[212:213], 0, s[92:93]
	s_mov_b32 m0, s44
	ds_read_b128 v[192:195], v234
	ds_read_b128 v[196:199], v234 offset:1024
	ds_read_b128 v[200:203], v234 offset:2048
	ds_read_b128 v[204:207], v234 offset:3072
	s_waitcnt vmcnt(8) lgkmcnt(0)
	s_barrier
	v_mfma_f32_16x16x32_f16 v[126:129], v[140:143], v[156:159], v[126:129]
	v_mfma_f32_16x16x32_f16 v[122:125], v[148:151], v[156:159], v[122:125]
	v_mfma_f32_16x16x32_f16 v[118:121], v[140:143], v[168:171], v[118:121]
	v_mfma_f32_16x16x32_f16 v[114:117], v[148:151], v[168:171], v[114:117]
	v_mfma_f32_16x16x32_f16 v[110:113], v[140:143], v[176:179], v[110:113]
	v_mfma_f32_16x16x32_f16 v[106:109], v[148:151], v[176:179], v[106:109]
	v_mfma_f32_16x16x32_f16 v[102:105], v[140:143], v[184:187], v[102:105]
	v_mfma_f32_16x16x32_f16 v[98:101], v[148:151], v[184:187], v[98:101]
	v_mfma_f32_16x16x32_f16 v[126:129], v[144:147], v[164:167], v[126:129]
	v_mfma_f32_16x16x32_f16 v[122:125], v[152:155], v[164:167], v[122:125]
	v_mfma_f32_16x16x32_f16 v[118:121], v[144:147], v[172:175], v[118:121]
	v_mfma_f32_16x16x32_f16 v[114:117], v[152:155], v[172:175], v[114:117]
	v_mfma_f32_16x16x32_f16 v[110:113], v[144:147], v[180:183], v[110:113]
	v_mfma_f32_16x16x32_f16 v[106:109], v[152:155], v[180:183], v[106:109]
	v_mfma_f32_16x16x32_f16 v[102:105], v[144:147], v[188:191], v[102:105]
	v_mfma_f32_16x16x32_f16 v[98:101], v[152:155], v[188:191], v[98:101]
	v_mfma_f32_16x16x32_f16 v[94:97], v[192:195], v[156:159], v[94:97]
	v_mfma_f32_16x16x32_f16 v[86:89], v[200:203], v[156:159], v[86:89]
	v_mfma_f32_16x16x32_f16 v[78:81], v[192:195], v[168:171], v[78:81]
	v_mfma_f32_16x16x32_f16 v[70:73], v[200:203], v[168:171], v[70:73]
	v_mfma_f32_16x16x32_f16 v[62:65], v[192:195], v[176:179], v[62:65]
	v_mfma_f32_16x16x32_f16 v[54:57], v[200:203], v[176:179], v[54:57]
	v_mfma_f32_16x16x32_f16 v[46:49], v[192:195], v[184:187], v[46:49]
	v_mfma_f32_16x16x32_f16 v[38:41], v[200:203], v[184:187], v[38:41]
	v_mfma_f32_16x16x32_f16 v[94:97], v[196:199], v[164:167], v[94:97]
	v_mfma_f32_16x16x32_f16 v[86:89], v[204:207], v[164:167], v[86:89]
	v_mfma_f32_16x16x32_f16 v[78:81], v[196:199], v[172:175], v[78:81]
	v_mfma_f32_16x16x32_f16 v[70:73], v[204:207], v[172:175], v[70:73]
	v_mfma_f32_16x16x32_f16 v[62:65], v[196:199], v[180:183], v[62:65]
	v_mfma_f32_16x16x32_f16 v[54:57], v[204:207], v[180:183], v[54:57]
	v_mfma_f32_16x16x32_f16 v[46:49], v[196:199], v[188:191], v[46:49]
	v_mfma_f32_16x16x32_f16 v[38:41], v[204:207], v[188:191], v[38:41]
	s_barrier
; #define PG8_STAGE(bufoff, gbase, voff) do { _Pragma("unroll") for (int _i = 0; _i < 2; ++_i) \
;         __builtin_amdgcn_global_load_lds((const unsigned*)((const char*)(gbase) + (voff)[_i]), (LAS unsigned*)(lds + (bufoff) + ldsw + _i * 8192), 16, 0, 0); } while (0)
; #define PG8_LDA(dst, b, h) do { _Pragma("unroll") for (int m = 0; m < 4; ++m) _Pragma("unroll") for (int k = 0; k < 2; ++k) dst[m][k] = *(const LAS h16x8*)(lds + PG8_SA(b, h) + aoff + m * 2048 + k * 1024); } while (0)
; #define PG8_LDB(dst, b, h) do { _Pragma("unroll") for (int n = 0; n < 2; ++n) _Pragma("unroll") for (int k = 0; k < 2; ++k) dst[n][k] = *(const LAS h16x8*)(lds + PG8_SB(b, h) + boff + n * 2048 + k * 1024); } while (0)
; #define PG8_MMA(ai, bj, At, Bt_) do { __builtin_amdgcn_s_setprio(1); _Pragma("unroll") for (int m = 0; m < 4; ++m) _Pragma("unroll") for (int n = 0; n < 2; ++n) _Pragma("unroll") for (int k = 0; k < 2; ++k) \
;         acc[ai][bj][m][n] = __builtin_amdgcn_mfma_f32_16x16x32_f16(Bt_[n][k], At[m][k], acc[ai][bj][m][n], 0, 0, 0); __builtin_amdgcn_s_setprio(0); } while (0)
; #define PG8_WAIT_V(n) asm volatile("s_waitcnt vmcnt(" #n ")" ::: "memory")
; #define PG8_WAIT_L(n) asm volatile("s_waitcnt lgkmcnt(" #n ")" ::: "memory")
; #define PG8_BAR __builtin_amdgcn_s_barrier()
; #define PG8_SCHED __builtin_amdgcn_sched_barrier(0)
; template <class Epi, class AMap>
; __device__ __forceinline__ void gemm_phase(LAS unsigned char* lds, const AMap am, const int lda, const h16* Bt, const int ldb, const int M, const int N, const int K, const Epi& E) {
;     ...
;             PG8_LDB(B1, 1, 1); PG8_STAGE(PG8_SB(1, 0), b3, voffB);
;             PG8_BAR; PG8_WAIT_L(0); PG8_MMA(0, 1, At, B1); PG8_BAR;
;             PG8_LDA(At, 1, 1); PG8_STAGE(PG8_SA(1, 0), a3, voffA);
;             PG8_BAR; PG8_WAIT_L(0); PG8_MMA(1, 0, At, B0); PG8_BAR; PG8_SCHED;
;             PG8_STAGE(PG8_SB(1, 1), b3 + hstepB, voffB);
;             PG8_WAIT_V(6); PG8_BAR; PG8_MMA(1, 1, At, B1); PG8_BAR;
;         }
;     ...
;     if (wr == 0) PG8_BAR;
	global_load_lds_dwordx4 v[212:213], off
	v_lshl_add_u64 v[212:213], v[220:221], 0, s[92:93]
	s_add_i32 m0, s44, 0x2000
	s_nop 0
	global_load_lds_dwordx4 v[212:213], off
	s_mov_b32 m0, s71
	v_lshl_add_u64 v[212:213], v[222:223], 0, s[92:93]
	ds_read_b128 v[156:159], v163 offset:49152
	ds_read_b128 v[164:167], v163 offset:50176
	ds_read_b128 v[168:171], v163 offset:51200
	ds_read_b128 v[172:175], v163 offset:52224
	ds_read_b128 v[176:179], v163 offset:53248
	ds_read_b128 v[180:183], v163 offset:54272
	ds_read_b128 v[184:187], v163 offset:55296
	ds_read_b128 v[188:191], v163 offset:56320
	global_load_lds_dwordx4 v[212:213], off
	v_lshl_add_u64 v[212:213], v[224:225], 0, s[92:93]
	s_mov_b32 m0, s72
	s_nop 0
	global_load_lds_dwordx4 v[212:213], off
	s_add_u32 s44, s46, 0x10080
	s_addc_u32 s45, s47, 0
	s_add_i32 s46, s48, s62
	v_lshl_add_u64 v[232:233], s[44:45], 0, v[0:1]
	s_mov_b32 m0, s46
	s_nop 0
	global_load_lds_dwordx4 v[232:233], off
	v_lshl_add_u64 v[232:233], s[44:45], 0, v[134:135]
	s_add_i32 m0, s46, 0x2000
	s_nop 0
	global_load_lds_dwordx4 v[232:233], off
	s_add_u32 s27, s27, 0x100
	s_addc_u32 s29, s29, 0
	s_cmp_ge_i32 s60, s24
	s_mov_b64 s[44:45], s[0:1]
	s_mov_b32 s46, s60
	s_waitcnt vmcnt(8) lgkmcnt(0)
	s_barrier
	v_mfma_f32_16x16x32_f16 v[90:93], v[140:143], v[156:159], v[90:93]
	v_mfma_f32_16x16x32_f16 v[82:85], v[148:151], v[156:159], v[82:85]
	v_mfma_f32_16x16x32_f16 v[74:77], v[140:143], v[168:171], v[74:77]
	v_mfma_f32_16x16x32_f16 v[66:69], v[148:151], v[168:171], v[66:69]
	v_mfma_f32_16x16x32_f16 v[58:61], v[140:143], v[176:179], v[58:61]
	v_mfma_f32_16x16x32_f16 v[50:53], v[148:151], v[176:179], v[50:53]
	v_mfma_f32_16x16x32_f16 v[42:45], v[140:143], v[184:187], v[42:45]
	v_mfma_f32_16x16x32_f16 v[34:37], v[148:151], v[184:187], v[34:37]
	v_mfma_f32_16x16x32_f16 v[90:93], v[144:147], v[164:167], v[90:93]
	v_mfma_f32_16x16x32_f16 v[82:85], v[152:155], v[164:167], v[82:85]
	v_mfma_f32_16x16x32_f16 v[74:77], v[144:147], v[172:175], v[74:77]
	v_mfma_f32_16x16x32_f16 v[66:69], v[152:155], v[172:175], v[66:69]
	v_mfma_f32_16x16x32_f16 v[58:61], v[144:147], v[180:183], v[58:61]
	v_mfma_f32_16x16x32_f16 v[50:53], v[152:155], v[180:183], v[50:53]
	v_mfma_f32_16x16x32_f16 v[42:45], v[144:147], v[188:191], v[42:45]
	v_mfma_f32_16x16x32_f16 v[34:37], v[152:155], v[188:191], v[34:37]
	v_mfma_f32_16x16x32_f16 v[30:33], v[192:195], v[156:159], v[30:33]
	v_mfma_f32_16x16x32_f16 v[26:29], v[200:203], v[156:159], v[26:29]
	v_mfma_f32_16x16x32_f16 v[22:25], v[192:195], v[168:171], v[22:25]
	v_mfma_f32_16x16x32_f16 v[18:21], v[200:203], v[168:171], v[18:21]
	v_mfma_f32_16x16x32_f16 v[14:17], v[192:195], v[176:179], v[14:17]
	v_mfma_f32_16x16x32_f16 v[10:13], v[200:203], v[176:179], v[10:13]
	v_mfma_f32_16x16x32_f16 v[6:9], v[192:195], v[184:187], v[6:9]
	v_mfma_f32_16x16x32_f16 v[2:5], v[200:203], v[184:187], v[2:5]
	v_mfma_f32_16x16x32_f16 v[30:33], v[196:199], v[164:167], v[30:33]
	v_mfma_f32_16x16x32_f16 v[26:29], v[204:207], v[164:167], v[26:29]
	v_mfma_f32_16x16x32_f16 v[22:25], v[196:199], v[172:175], v[22:25]
	v_mfma_f32_16x16x32_f16 v[18:21], v[204:207], v[172:175], v[18:21]
	v_mfma_f32_16x16x32_f16 v[14:17], v[196:199], v[180:183], v[14:17]
	v_mfma_f32_16x16x32_f16 v[10:13], v[204:207], v[180:183], v[10:13]
	v_mfma_f32_16x16x32_f16 v[6:9], v[196:199], v[188:191], v[6:9]
	v_mfma_f32_16x16x32_f16 v[2:5], v[204:207], v[188:191], v[2:5]
	s_barrier
	s_cbranch_scc0 .LBB0_667
	s_cmpk_gt_u32 s50, 0xff
	s_cbranch_scc1 .Lgx6
	s_barrier

; #define PG8_STAGE(bufoff, gbase, voff) do { _Pragma("unroll") for (int _i = 0; _i < 2; ++_i) \
;         __builtin_amdgcn_global_load_lds((const unsigned*)((const char*)(gbase) + (voff)[_i]), (LAS unsigned*)(lds + (bufoff) + ldsw + _i * 8192), 16, 0, 0); } while (0)
; #define PG8_LDA(dst, b, h) do { _Pragma("unroll") for (int m = 0; m < 4; ++m) _Pragma("unroll") for (int k = 0; k < 2; ++k) dst[m][k] = *(const LAS h16x8*)(lds + PG8_SA(b, h) + aoff + m * 2048 + k * 1024); } while (0)
; #define PG8_LDB(dst, b, h) do { _Pragma("unroll") for (int n = 0; n < 2; ++n) _Pragma("unroll") for (int k = 0; k < 2; ++k) dst[n][k] = *(const LAS h16x8*)(lds + PG8_SB(b, h) + boff + n * 2048 + k * 1024); } while (0)
; #define PG8_MMA(ai, bj, At, Bt_) do { __builtin_amdgcn_s_setprio(1); _Pragma("unroll") for (int m = 0; m < 4; ++m) _Pragma("unroll") for (int n = 0; n < 2; ++n) _Pragma("unroll") for (int k = 0; k < 2; ++k) \
;         acc[ai][bj][m][n] = __builtin_amdgcn_mfma_f32_16x16x32_f16(Bt_[n][k], At[m][k], acc[ai][bj][m][n], 0, 0, 0); __builtin_amdgcn_s_setprio(0); } while (0)
; #define PG8_WAIT_V(n) asm volatile("s_waitcnt vmcnt(" #n ")" ::: "memory")
; #define PG8_WAIT_L(n) asm volatile("s_waitcnt lgkmcnt(" #n ")" ::: "memory")
; template <class Epi, class AMap>
; __device__ __forceinline__ void gemm_phase(LAS unsigned char* lds, const AMap am, const int lda, const h16* Bt, const int ldb, const int M, const int N, const int K, const Epi& E) {
;     ...
;             const bool last = (t == nt - 2);
;             const char* a1 = cA + (size_t)(t + 1) * kstep;
;             const char* a2 = last ? nA : cA + (size_t)(t + 2) * kstep; const char* b2 = last ? nB : cB + (size_t)(t + 2) * kstep;
;             const char* a3 = a2 + kstep; const char* b3 = b2 + kstep;
;             PG8_LDB(B0, 0, 0); PG8_SCHED; PG8_LDA(At, 0, 0); PG8_STAGE(PG8_SA(1, 1), a1 + hstepA, voffA);
;             PG8_WAIT_L(8); PG8_BAR; PG8_WAIT_L(0); PG8_MMA(0, 0, At, B0); PG8_BAR; PG8_SCHED;
;             PG8_LDB(B1, 0, 1); PG8_STAGE(PG8_SB(0, 0), b2, voffB);
;             PG8_BAR; PG8_WAIT_L(0); PG8_MMA(0, 1, At, B1); PG8_BAR;
;             PG8_LDA(At, 0, 1); PG8_STAGE(PG8_SA(0, 0), a2, voffA);
;             PG8_BAR; PG8_WAIT_L(0); PG8_MMA(1, 0, At, B0); PG8_BAR; PG8_SCHED;
;             PG8_STAGE(PG8_SB(0, 1), b2 + hstepB, voffB);
;             PG8_WAIT_V(6); PG8_BAR; PG8_MMA(1, 1, At, B1); PG8_BAR;
.LBB0_692:
	s_add_i32 s51, s26, 2
	s_add_u32 s0, s22, 0x100
	s_addc_u32 s1, s23, 0
	s_add_i32 s60, 0, 0x10000
	v_add_u32_e32 v234, s60, v175
	ds_read_b128 v[82:85], v234
	ds_read_b128 v[86:89], v234 offset:1024
	ds_read_b128 v[138:141], v234 offset:2048
	ds_read_b128 v[142:145], v234 offset:3072
	s_cmp_eq_u32 s61, s26
	s_cselect_b32 s26, s21, s29
	s_cselect_b32 s49, s47, s1
	s_cselect_b32 s48, s46, s0
	s_cselect_b32 s27, s20, s45
	v_lshl_add_u64 v[172:173], s[22:23], 0, v[152:153]
	s_add_i32 m0, s74, 0xc000
	ds_read_b128 v[156:159], v177
	ds_read_b128 v[160:163], v177 offset:1024
	ds_read_b128 v[164:167], v177 offset:2048
	ds_read_b128 v[168:171], v177 offset:3072
	ds_read_b128 v[178:181], v177 offset:4096
	ds_read_b128 v[182:185], v177 offset:5120
	ds_read_b128 v[186:189], v177 offset:6144
	ds_read_b128 v[190:193], v177 offset:7168
	global_load_lds_dwordx4 v[172:173], off
	v_lshl_add_u64 v[172:173], s[22:23], 0, v[154:155]
	s_add_i32 m0, s74, 0xe000
	s_nop 0
	global_load_lds_dwordx4 v[172:173], off
	s_waitcnt lgkmcnt(11)
	s_add_i32 s62, 0, 0x14000
	v_add_u32_e32 v172, s62, v175
	s_add_i32 s22, s60, s71
	ds_read_b128 v[194:197], v172
	ds_read_b128 v[198:201], v172 offset:1024
	ds_read_b128 v[202:205], v172 offset:2048
	ds_read_b128 v[220:223], v172 offset:3072
	s_waitcnt vmcnt(8) lgkmcnt(0)
	s_barrier
	v_mfma_f32_16x16x32_f16 v[134:137], v[82:85], v[156:159], v[134:137]
	v_mfma_f32_16x16x32_f16 v[130:133], v[138:141], v[156:159], v[130:133]
	v_mfma_f32_16x16x32_f16 v[126:129], v[82:85], v[164:167], v[126:129]
	v_mfma_f32_16x16x32_f16 v[122:125], v[138:141], v[164:167], v[122:125]
	v_mfma_f32_16x16x32_f16 v[118:121], v[82:85], v[178:181], v[118:121]
	v_mfma_f32_16x16x32_f16 v[114:117], v[138:141], v[178:181], v[114:117]
	v_mfma_f32_16x16x32_f16 v[110:113], v[82:85], v[186:189], v[110:113]
	v_mfma_f32_16x16x32_f16 v[106:109], v[138:141], v[186:189], v[106:109]
	v_mfma_f32_16x16x32_f16 v[134:137], v[86:89], v[160:163], v[134:137]
	v_mfma_f32_16x16x32_f16 v[130:133], v[142:145], v[160:163], v[130:133]
	v_mfma_f32_16x16x32_f16 v[126:129], v[86:89], v[168:171], v[126:129]
	v_mfma_f32_16x16x32_f16 v[122:125], v[142:145], v[168:171], v[122:125]
	v_mfma_f32_16x16x32_f16 v[118:121], v[86:89], v[182:185], v[118:121]
	v_mfma_f32_16x16x32_f16 v[114:117], v[142:145], v[182:185], v[114:117]
	v_mfma_f32_16x16x32_f16 v[110:113], v[86:89], v[190:193], v[110:113]
	v_mfma_f32_16x16x32_f16 v[106:109], v[142:145], v[190:193], v[106:109]
	v_mfma_f32_16x16x32_f16 v[62:65], v[194:197], v[156:159], v[62:65]
	v_mfma_f32_16x16x32_f16 v[58:61], v[202:205], v[156:159], v[58:61]
	v_mfma_f32_16x16x32_f16 v[54:57], v[194:197], v[164:167], v[54:57]
	v_mfma_f32_16x16x32_f16 v[50:53], v[202:205], v[164:167], v[50:53]
	v_mfma_f32_16x16x32_f16 v[46:49], v[194:197], v[178:181], v[46:49]
	v_mfma_f32_16x16x32_f16 v[42:45], v[202:205], v[178:181], v[42:45]
	v_mfma_f32_16x16x32_f16 v[38:41], v[194:197], v[186:189], v[38:41]
	v_mfma_f32_16x16x32_f16 v[34:37], v[202:205], v[186:189], v[34:37]
	v_mfma_f32_16x16x32_f16 v[62:65], v[198:201], v[160:163], v[62:65]
	v_mfma_f32_16x16x32_f16 v[58:61], v[220:223], v[160:163], v[58:61]
	v_mfma_f32_16x16x32_f16 v[54:57], v[198:201], v[168:171], v[54:57]
	v_mfma_f32_16x16x32_f16 v[50:53], v[220:223], v[168:171], v[50:53]
	v_mfma_f32_16x16x32_f16 v[46:49], v[198:201], v[182:185], v[46:49]
	v_mfma_f32_16x16x32_f16 v[42:45], v[220:223], v[182:185], v[42:45]
	v_mfma_f32_16x16x32_f16 v[38:41], v[198:201], v[190:193], v[38:41]
	v_mfma_f32_16x16x32_f16 v[34:37], v[220:223], v[190:193], v[34:37]
	s_barrier
	v_lshl_add_u64 v[172:173], s[26:27], 0, v[0:1]
	s_mov_b32 m0, s22
	v_lshl_add_u64 v[206:207], s[26:27], 0, v[150:151]
	global_load_lds_dwordx4 v[172:173], off
	s_add_i32 m0, s22, 0x2000
	s_nop 0
	global_load_lds_dwordx4 v[206:207], off
	s_mov_b32 m0, s74
	v_lshl_add_u64 v[212:213], s[48:49], 0, v[146:147]
	ds_read_b128 v[156:159], v177 offset:16384
	ds_read_b128 v[160:163], v177 offset:17408
	ds_read_b128 v[164:167], v177 offset:18432
	ds_read_b128 v[168:171], v177 offset:19456
	ds_read_b128 v[178:181], v177 offset:20480
	ds_read_b128 v[182:185], v177 offset:21504
	ds_read_b128 v[186:189], v177 offset:22528
	ds_read_b128 v[190:193], v177 offset:23552
	global_load_lds_dwordx4 v[212:213], off
	v_lshl_add_u64 v[224:225], s[48:49], 0, v[148:149]
	s_mov_b32 m0, s75
	s_nop 0
	global_load_lds_dwordx4 v[224:225], off
	s_waitcnt vmcnt(6) lgkmcnt(0)
	s_barrier
	v_mfma_f32_16x16x32_f16 v[102:105], v[82:85], v[156:159], v[102:105]
	v_mfma_f32_16x16x32_f16 v[98:101], v[138:141], v[156:159], v[98:101]
	v_mfma_f32_16x16x32_f16 v[94:97], v[82:85], v[164:167], v[94:97]
	v_mfma_f32_16x16x32_f16 v[90:93], v[138:141], v[164:167], v[90:93]
	v_mfma_f32_16x16x32_f16 v[78:81], v[82:85], v[178:181], v[78:81]
	v_mfma_f32_16x16x32_f16 v[74:77], v[138:141], v[178:181], v[74:77]
	v_mfma_f32_16x16x32_f16 v[70:73], v[82:85], v[186:189], v[70:73]
	v_mfma_f32_16x16x32_f16 v[66:69], v[138:141], v[186:189], v[66:69]
	v_mfma_f32_16x16x32_f16 v[102:105], v[86:89], v[160:163], v[102:105]
	v_mfma_f32_16x16x32_f16 v[98:101], v[142:145], v[160:163], v[98:101]
	v_mfma_f32_16x16x32_f16 v[94:97], v[86:89], v[168:171], v[94:97]
	v_mfma_f32_16x16x32_f16 v[90:93], v[142:145], v[168:171], v[90:93]
	v_mfma_f32_16x16x32_f16 v[78:81], v[86:89], v[182:185], v[78:81]
	v_mfma_f32_16x16x32_f16 v[74:77], v[142:145], v[182:185], v[74:77]
	v_mfma_f32_16x16x32_f16 v[70:73], v[86:89], v[190:193], v[70:73]
	v_mfma_f32_16x16x32_f16 v[66:69], v[142:145], v[190:193], v[66:69]
	v_mfma_f32_16x16x32_f16 v[30:33], v[194:197], v[156:159], v[30:33]
	v_mfma_f32_16x16x32_f16 v[26:29], v[202:205], v[156:159], v[26:29]
	v_mfma_f32_16x16x32_f16 v[22:25], v[194:197], v[164:167], v[22:25]
	v_mfma_f32_16x16x32_f16 v[18:21], v[202:205], v[164:167], v[18:21]
	v_mfma_f32_16x16x32_f16 v[14:17], v[194:197], v[178:181], v[14:17]
	v_mfma_f32_16x16x32_f16 v[10:13], v[202:205], v[178:181], v[10:13]
	v_mfma_f32_16x16x32_f16 v[6:9], v[194:197], v[186:189], v[6:9]
	v_mfma_f32_16x16x32_f16 v[2:5], v[202:205], v[186:189], v[2:5]
	v_mfma_f32_16x16x32_f16 v[30:33], v[198:201], v[160:163], v[30:33]
	v_mfma_f32_16x16x32_f16 v[26:29], v[220:223], v[160:163], v[26:29]
	v_mfma_f32_16x16x32_f16 v[22:25], v[198:201], v[168:171], v[22:25]
	v_mfma_f32_16x16x32_f16 v[18:21], v[220:223], v[168:171], v[18:21]
	v_mfma_f32_16x16x32_f16 v[14:17], v[198:201], v[182:185], v[14:17]
	v_mfma_f32_16x16x32_f16 v[10:13], v[220:223], v[182:185], v[10:13]
	v_mfma_f32_16x16x32_f16 v[6:9], v[198:201], v[190:193], v[6:9]
	v_mfma_f32_16x16x32_f16 v[2:5], v[220:223], v[190:193], v[2:5]
	s_barrier
; #define PG8_STAGE(bufoff, gbase, voff) do { _Pragma("unroll") for (int _i = 0; _i < 2; ++_i) \
;         __builtin_amdgcn_global_load_lds((const unsigned*)((const char*)(gbase) + (voff)[_i]), (LAS unsigned*)(lds + (bufoff) + ldsw + _i * 8192), 16, 0, 0); } while (0)
; #define PG8_LDA(dst, b, h) do { _Pragma("unroll") for (int m = 0; m < 4; ++m) _Pragma("unroll") for (int k = 0; k < 2; ++k) dst[m][k] = *(const LAS h16x8*)(lds + PG8_SA(b, h) + aoff + m * 2048 + k * 1024); } while (0)
; #define PG8_LDB(dst, b, h) do { _Pragma("unroll") for (int n = 0; n < 2; ++n) _Pragma("unroll") for (int k = 0; k < 2; ++k) dst[n][k] = *(const LAS h16x8*)(lds + PG8_SB(b, h) + boff + n * 2048 + k * 1024); } while (0)
; #define PG8_MMA(ai, bj, At, Bt_) do { __builtin_amdgcn_s_setprio(1); _Pragma("unroll") for (int m = 0; m < 4; ++m) _Pragma("unroll") for (int n = 0; n < 2; ++n) _Pragma("unroll") for (int k = 0; k < 2; ++k) \
;         acc[ai][bj][m][n] = __builtin_amdgcn_mfma_f32_16x16x32_f16(Bt_[n][k], At[m][k], acc[ai][bj][m][n], 0, 0, 0); __builtin_amdgcn_s_setprio(0); } while (0)
; #define PG8_WAIT_V(n) asm volatile("s_waitcnt vmcnt(" #n ")" ::: "memory")
; #define PG8_WAIT_L(n) asm volatile("s_waitcnt lgkmcnt(" #n ")" ::: "memory")
; #define PG8_BAR __builtin_amdgcn_s_barrier()
; #define PG8_SCHED __builtin_amdgcn_sched_barrier(0)
; template <class Epi, class AMap>
; __device__ __forceinline__ void gemm_phase(LAS unsigned char* lds, const AMap am, const int lda, const h16* Bt, const int ldb, const int M, const int N, const int K, const Epi& E) {
;     ...
;             PG8_STAGE(PG8_SB(0, 1), b2 + hstepB, voffB);
;             PG8_WAIT_V(6); PG8_BAR; PG8_MMA(1, 1, At, B1); PG8_BAR;
;             PG8_LDB(B0, 1, 0); PG8_SCHED; PG8_LDA(At, 1, 0); PG8_STAGE(PG8_SA(0, 1), a2 + hstepA, voffA);
;             PG8_WAIT_L(8); PG8_BAR; PG8_WAIT_L(0); PG8_MMA(0, 0, At, B0); PG8_BAR; PG8_SCHED;
;             PG8_LDB(B1, 1, 1); PG8_STAGE(PG8_SB(1, 0), b3, voffB);
;             PG8_BAR; PG8_WAIT_L(0); PG8_MMA(0, 1, At, B1); PG8_BAR;
	s_add_u32 s22, s26, 0x10000
	s_addc_u32 s23, s27, 0
	s_add_i32 s60, s62, s71
	v_lshl_add_u64 v[232:233], s[22:23], 0, v[0:1]
	s_mov_b32 m0, s60
	s_nop 0
	global_load_lds_dwordx4 v[232:233], off
	v_lshl_add_u64 v[232:233], s[22:23], 0, v[150:151]
	s_add_i32 m0, s60, 0x2000
	s_nop 0
	global_load_lds_dwordx4 v[232:233], off
	s_add_i32 s60, 0, 0x18000
	v_add_u32_e32 v234, s60, v175
	ds_read_b128 v[82:85], v234
	ds_read_b128 v[86:89], v234 offset:1024
	ds_read_b128 v[138:141], v234 offset:2048
	ds_read_b128 v[142:145], v234 offset:3072
	s_add_u32 s22, s48, 0x1c0000
	s_addc_u32 s23, s49, 0
	s_mov_b32 m0, s76
	v_lshl_add_u64 v[232:233], s[22:23], 0, v[146:147]
	ds_read_b128 v[156:159], v177 offset:32768
	ds_read_b128 v[160:163], v177 offset:33792
	ds_read_b128 v[164:167], v177 offset:34816
	ds_read_b128 v[168:171], v177 offset:35840
	ds_read_b128 v[178:181], v177 offset:36864
	ds_read_b128 v[182:185], v177 offset:37888
	ds_read_b128 v[186:189], v177 offset:38912
	ds_read_b128 v[190:193], v177 offset:39936
	global_load_lds_dwordx4 v[232:233], off
	v_lshl_add_u64 v[232:233], s[22:23], 0, v[148:149]
	s_mov_b32 m0, s77
	s_nop 0
	global_load_lds_dwordx4 v[232:233], off
	s_waitcnt lgkmcnt(11)
	s_add_i32 s48, 0, 0x1c000
	s_add_i32 s22, s60, s71
	v_add_u32_e32 v214, s48, v175
	v_lshl_add_u64 v[172:173], v[172:173], 0, s[92:93]
	s_mov_b32 m0, s22
	ds_read_b128 v[194:197], v214
	ds_read_b128 v[198:201], v214 offset:1024
	ds_read_b128 v[202:205], v214 offset:2048
	ds_read_b128 v[220:223], v214 offset:3072
	s_waitcnt vmcnt(8) lgkmcnt(0)
	s_barrier
	v_mfma_f32_16x16x32_f16 v[134:137], v[82:85], v[156:159], v[134:137]
	v_mfma_f32_16x16x32_f16 v[130:133], v[138:141], v[156:159], v[130:133]
	v_mfma_f32_16x16x32_f16 v[126:129], v[82:85], v[164:167], v[126:129]
	v_mfma_f32_16x16x32_f16 v[122:125], v[138:141], v[164:167], v[122:125]
	v_mfma_f32_16x16x32_f16 v[118:121], v[82:85], v[178:181], v[118:121]
	v_mfma_f32_16x16x32_f16 v[114:117], v[138:141], v[178:181], v[114:117]
	v_mfma_f32_16x16x32_f16 v[110:113], v[82:85], v[186:189], v[110:113]
	v_mfma_f32_16x16x32_f16 v[106:109], v[138:141], v[186:189], v[106:109]
	v_mfma_f32_16x16x32_f16 v[134:137], v[86:89], v[160:163], v[134:137]
	v_mfma_f32_16x16x32_f16 v[130:133], v[142:145], v[160:163], v[130:133]
	v_mfma_f32_16x16x32_f16 v[126:129], v[86:89], v[168:171], v[126:129]
	v_mfma_f32_16x16x32_f16 v[122:125], v[142:145], v[168:171], v[122:125]
	v_mfma_f32_16x16x32_f16 v[118:121], v[86:89], v[182:185], v[118:121]
	v_mfma_f32_16x16x32_f16 v[114:117], v[142:145], v[182:185], v[114:117]
	v_mfma_f32_16x16x32_f16 v[110:113], v[86:89], v[190:193], v[110:113]
	v_mfma_f32_16x16x32_f16 v[106:109], v[142:145], v[190:193], v[106:109]
	v_mfma_f32_16x16x32_f16 v[62:65], v[194:197], v[156:159], v[62:65]
	v_mfma_f32_16x16x32_f16 v[58:61], v[202:205], v[156:159], v[58:61]
	v_mfma_f32_16x16x32_f16 v[54:57], v[194:197], v[164:167], v[54:57]
	v_mfma_f32_16x16x32_f16 v[50:53], v[202:205], v[164:167], v[50:53]
	v_mfma_f32_16x16x32_f16 v[46:49], v[194:197], v[178:181], v[46:49]
	v_mfma_f32_16x16x32_f16 v[42:45], v[202:205], v[178:181], v[42:45]
	v_mfma_f32_16x16x32_f16 v[38:41], v[194:197], v[186:189], v[38:41]
	v_mfma_f32_16x16x32_f16 v[34:37], v[202:205], v[186:189], v[34:37]
	v_mfma_f32_16x16x32_f16 v[62:65], v[198:201], v[160:163], v[62:65]
	v_mfma_f32_16x16x32_f16 v[58:61], v[220:223], v[160:163], v[58:61]
	v_mfma_f32_16x16x32_f16 v[54:57], v[198:201], v[168:171], v[54:57]
	v_mfma_f32_16x16x32_f16 v[50:53], v[220:223], v[168:171], v[50:53]
	v_mfma_f32_16x16x32_f16 v[46:49], v[198:201], v[182:185], v[46:49]
	v_mfma_f32_16x16x32_f16 v[42:45], v[220:223], v[182:185], v[42:45]
	v_mfma_f32_16x16x32_f16 v[38:41], v[198:201], v[190:193], v[38:41]
	v_mfma_f32_16x16x32_f16 v[34:37], v[220:223], v[190:193], v[34:37]
	s_barrier
; #define PG8_STAGE(bufoff, gbase, voff) do { _Pragma("unroll") for (int _i = 0; _i < 2; ++_i) \
;         __builtin_amdgcn_global_load_lds((const unsigned*)((const char*)(gbase) + (voff)[_i]), (LAS unsigned*)(lds + (bufoff) + ldsw + _i * 8192), 16, 0, 0); } while (0)
; #define PG8_LDA(dst, b, h) do { _Pragma("unroll") for (int m = 0; m < 4; ++m) _Pragma("unroll") for (int k = 0; k < 2; ++k) dst[m][k] = *(const LAS h16x8*)(lds + PG8_SA(b, h) + aoff + m * 2048 + k * 1024); } while (0)
; #define PG8_MMA(ai, bj, At, Bt_) do { __builtin_amdgcn_s_setprio(1); _Pragma("unroll") for (int m = 0; m < 4; ++m) _Pragma("unroll") for (int n = 0; n < 2; ++n) _Pragma("unroll") for (int k = 0; k < 2; ++k) \
;         acc[ai][bj][m][n] = __builtin_amdgcn_mfma_f32_16x16x32_f16(Bt_[n][k], At[m][k], acc[ai][bj][m][n], 0, 0, 0); __builtin_amdgcn_s_setprio(0); } while (0)
; #define PG8_WAIT_V(n) asm volatile("s_waitcnt vmcnt(" #n ")" ::: "memory")
; #define PG8_WAIT_L(n) asm volatile("s_waitcnt lgkmcnt(" #n ")" ::: "memory")
; #define PG8_BAR __builtin_amdgcn_s_barrier()
; #define PG8_SCHED __builtin_amdgcn_sched_barrier(0)
; template <class Epi, class AMap>
; __device__ __forceinline__ void gemm_phase(LAS unsigned char* lds, const AMap am, const int lda, const h16* Bt, const int ldb, const int M, const int N, const int K, const Epi& E) {
;     ...
;             PG8_LDA(At, 1, 1); PG8_STAGE(PG8_SA(1, 0), a3, voffA);
;             PG8_BAR; PG8_WAIT_L(0); PG8_MMA(1, 0, At, B0); PG8_BAR; PG8_SCHED;
;             PG8_STAGE(PG8_SB(1, 1), b3 + hstepB, voffB);
;             PG8_WAIT_V(6); PG8_BAR; PG8_MMA(1, 1, At, B1); PG8_BAR;
;         }
;     ...
;     if (wr == 0) PG8_BAR;
	global_load_lds_dwordx4 v[172:173], off
	v_lshl_add_u64 v[172:173], v[206:207], 0, s[92:93]
	s_add_i32 m0, s22, 0x2000
	s_nop 0
	global_load_lds_dwordx4 v[172:173], off
	s_mov_b32 m0, s79
	v_lshl_add_u64 v[172:173], v[212:213], 0, s[92:93]
	ds_read_b128 v[156:159], v177 offset:49152
	ds_read_b128 v[160:163], v177 offset:50176
	ds_read_b128 v[164:167], v177 offset:51200
	ds_read_b128 v[168:171], v177 offset:52224
	ds_read_b128 v[178:181], v177 offset:53248
	ds_read_b128 v[182:185], v177 offset:54272
	ds_read_b128 v[186:189], v177 offset:55296
	ds_read_b128 v[190:193], v177 offset:56320
	global_load_lds_dwordx4 v[172:173], off
	v_lshl_add_u64 v[172:173], v[224:225], 0, s[92:93]
	s_mov_b32 m0, s80
	s_nop 0
	global_load_lds_dwordx4 v[172:173], off
	s_add_u32 s22, s26, 0x10080
	s_addc_u32 s23, s27, 0
	s_add_i32 s26, s48, s71
	v_lshl_add_u64 v[232:233], s[22:23], 0, v[0:1]
	s_mov_b32 m0, s26
	s_nop 0
	global_load_lds_dwordx4 v[232:233], off
	v_lshl_add_u64 v[232:233], s[22:23], 0, v[150:151]
	s_add_i32 m0, s26, 0x2000
	s_nop 0
	global_load_lds_dwordx4 v[232:233], off
	s_add_u32 s29, s29, 0x100
	s_addc_u32 s45, s45, 0
	s_cmp_ge_i32 s51, s24
	s_mov_b64 s[22:23], s[0:1]
	s_mov_b32 s26, s51
	s_waitcnt vmcnt(8) lgkmcnt(0)
	s_barrier
	v_mfma_f32_16x16x32_f16 v[102:105], v[82:85], v[156:159], v[102:105]
	v_mfma_f32_16x16x32_f16 v[98:101], v[138:141], v[156:159], v[98:101]
	v_mfma_f32_16x16x32_f16 v[94:97], v[82:85], v[164:167], v[94:97]
	v_mfma_f32_16x16x32_f16 v[90:93], v[138:141], v[164:167], v[90:93]
	v_mfma_f32_16x16x32_f16 v[78:81], v[82:85], v[178:181], v[78:81]
	v_mfma_f32_16x16x32_f16 v[74:77], v[138:141], v[178:181], v[74:77]
	v_mfma_f32_16x16x32_f16 v[70:73], v[82:85], v[186:189], v[70:73]
	v_mfma_f32_16x16x32_f16 v[66:69], v[138:141], v[186:189], v[66:69]
	v_mfma_f32_16x16x32_f16 v[102:105], v[86:89], v[160:163], v[102:105]
	v_mfma_f32_16x16x32_f16 v[98:101], v[142:145], v[160:163], v[98:101]
	v_mfma_f32_16x16x32_f16 v[94:97], v[86:89], v[168:171], v[94:97]
	v_mfma_f32_16x16x32_f16 v[90:93], v[142:145], v[168:171], v[90:93]
	v_mfma_f32_16x16x32_f16 v[78:81], v[86:89], v[182:185], v[78:81]
	v_mfma_f32_16x16x32_f16 v[74:77], v[142:145], v[182:185], v[74:77]
	v_mfma_f32_16x16x32_f16 v[70:73], v[86:89], v[190:193], v[70:73]
	v_mfma_f32_16x16x32_f16 v[66:69], v[142:145], v[190:193], v[66:69]
	v_mfma_f32_16x16x32_f16 v[30:33], v[194:197], v[156:159], v[30:33]
	v_mfma_f32_16x16x32_f16 v[26:29], v[202:205], v[156:159], v[26:29]
	v_mfma_f32_16x16x32_f16 v[22:25], v[194:197], v[164:167], v[22:25]
	v_mfma_f32_16x16x32_f16 v[18:21], v[202:205], v[164:167], v[18:21]
	v_mfma_f32_16x16x32_f16 v[14:17], v[194:197], v[178:181], v[14:17]
	v_mfma_f32_16x16x32_f16 v[10:13], v[202:205], v[178:181], v[10:13]
	v_mfma_f32_16x16x32_f16 v[6:9], v[194:197], v[186:189], v[6:9]
	v_mfma_f32_16x16x32_f16 v[2:5], v[202:205], v[186:189], v[2:5]
	v_mfma_f32_16x16x32_f16 v[30:33], v[198:201], v[160:163], v[30:33]
	v_mfma_f32_16x16x32_f16 v[26:29], v[220:223], v[160:163], v[26:29]
	v_mfma_f32_16x16x32_f16 v[22:25], v[198:201], v[168:171], v[22:25]
	v_mfma_f32_16x16x32_f16 v[18:21], v[220:223], v[168:171], v[18:21]
	v_mfma_f32_16x16x32_f16 v[14:17], v[198:201], v[182:185], v[14:17]
	v_mfma_f32_16x16x32_f16 v[10:13], v[220:223], v[182:185], v[10:13]
	v_mfma_f32_16x16x32_f16 v[6:9], v[198:201], v[190:193], v[6:9]
	v_mfma_f32_16x16x32_f16 v[2:5], v[220:223], v[190:193], v[2:5]
	s_barrier
	s_cbranch_scc0 .LBB0_692
	s_cmpk_gt_u32 s69, 0xff
	s_cbranch_scc1 .Lgx7
	s_barrier

; #define PG8_STAGE(bufoff, gbase, voff) do { _Pragma("unroll") for (int _i = 0; _i < 2; ++_i) \
;         __builtin_amdgcn_global_load_lds((const unsigned*)((const char*)(gbase) + (voff)[_i]), (LAS unsigned*)(lds + (bufoff) + ldsw + _i * 8192), 16, 0, 0); } while (0)
; #define PG8_LDA(dst, b, h) do { _Pragma("unroll") for (int m = 0; m < 4; ++m) _Pragma("unroll") for (int k = 0; k < 2; ++k) dst[m][k] = *(const LAS h16x8*)(lds + PG8_SA(b, h) + aoff + m * 2048 + k * 1024); } while (0)
; #define PG8_LDB(dst, b, h) do { _Pragma("unroll") for (int n = 0; n < 2; ++n) _Pragma("unroll") for (int k = 0; k < 2; ++k) dst[n][k] = *(const LAS h16x8*)(lds + PG8_SB(b, h) + boff + n * 2048 + k * 1024); } while (0)
; #define PG8_MMA(ai, bj, At, Bt_) do { __builtin_amdgcn_s_setprio(1); _Pragma("unroll") for (int m = 0; m < 4; ++m) _Pragma("unroll") for (int n = 0; n < 2; ++n) _Pragma("unroll") for (int k = 0; k < 2; ++k) \
;         acc[ai][bj][m][n] = __builtin_amdgcn_mfma_f32_16x16x32_f16(Bt_[n][k], At[m][k], acc[ai][bj][m][n], 0, 0, 0); __builtin_amdgcn_s_setprio(0); } while (0)
; #define PG8_WAIT_V(n) asm volatile("s_waitcnt vmcnt(" #n ")" ::: "memory")
; #define PG8_WAIT_L(n) asm volatile("s_waitcnt lgkmcnt(" #n ")" ::: "memory")
; template <class Epi, class AMap>
; __device__ __forceinline__ void gemm_phase(LAS unsigned char* lds, const AMap am, const int lda, const h16* Bt, const int ldb, const int M, const int N, const int K, const Epi& E) {
;     ...
;             const bool last = (t == nt - 2);
;             const char* a1 = cA + (size_t)(t + 1) * kstep;
;             const char* a2 = last ? nA : cA + (size_t)(t + 2) * kstep; const char* b2 = last ? nB : cB + (size_t)(t + 2) * kstep;
;             const char* a3 = a2 + kstep; const char* b3 = b2 + kstep;
;             PG8_LDB(B0, 0, 0); PG8_SCHED; PG8_LDA(At, 0, 0); PG8_STAGE(PG8_SA(1, 1), a1 + hstepA, voffA);
;             PG8_WAIT_L(8); PG8_BAR; PG8_WAIT_L(0); PG8_MMA(0, 0, At, B0); PG8_BAR; PG8_SCHED;
;             PG8_LDB(B1, 0, 1); PG8_STAGE(PG8_SB(0, 0), b2, voffB);
;             PG8_BAR; PG8_WAIT_L(0); PG8_MMA(0, 1, At, B1); PG8_BAR;
;             PG8_LDA(At, 0, 1); PG8_STAGE(PG8_SA(0, 0), a2, voffA);
;             PG8_BAR; PG8_WAIT_L(0); PG8_MMA(1, 0, At, B0); PG8_BAR; PG8_SCHED;
;             PG8_STAGE(PG8_SB(0, 1), b2 + hstepB, voffB);
;             PG8_WAIT_V(6); PG8_BAR; PG8_MMA(1, 1, At, B1); PG8_BAR;
.LBB0_799:
	s_add_u32 s40, s0, 0xfff80080
	s_addc_u32 s41, s1, -1
	s_add_i32 s45, 0, 0x10000
	v_add_u32_e32 v152, s45, v155
	ds_read_b128 v[130:133], v152
	ds_read_b128 v[134:137], v152 offset:1024
	ds_read_b128 v[148:151], v152 offset:2048
	ds_read_b128 v[158:161], v152 offset:3072
	s_cmp_eq_u32 s43, 28
	s_cselect_b32 s49, s47, s41
	s_cselect_b32 s48, s46, s40
	s_cselect_b32 s41, s29, s35
	s_cselect_b32 s40, s20, s21
	v_lshl_add_u64 v[152:153], s[0:1], 0, v[144:145]
	s_add_i32 m0, s23, 0xc000
	ds_read_b128 v[162:165], v157
	ds_read_b128 v[166:169], v157 offset:1024
	ds_read_b128 v[170:173], v157 offset:2048
	ds_read_b128 v[174:177], v157 offset:3072
	ds_read_b128 v[178:181], v157 offset:4096
	ds_read_b128 v[182:185], v157 offset:5120
	ds_read_b128 v[186:189], v157 offset:6144
	ds_read_b128 v[190:193], v157 offset:7168
	global_load_lds_dwordx4 v[152:153], off
	v_lshl_add_u64 v[152:153], s[0:1], 0, v[146:147]
	s_add_i32 m0, s23, 0xe000
	s_nop 0
	global_load_lds_dwordx4 v[152:153], off
	s_waitcnt lgkmcnt(11)
	s_add_i32 s60, 0, 0x14000
	v_add_u32_e32 v152, s60, v155
	s_add_i32 s45, s45, s72
	ds_read_b128 v[194:197], v152
	ds_read_b128 v[198:201], v152 offset:1024
	ds_read_b128 v[202:205], v152 offset:2048
	ds_read_b128 v[220:223], v152 offset:3072
	s_waitcnt vmcnt(8) lgkmcnt(0)
	s_barrier
	v_mfma_f32_16x16x32_f16 v[126:129], v[130:133], v[162:165], v[126:129]
	v_mfma_f32_16x16x32_f16 v[122:125], v[148:151], v[162:165], v[122:125]
	v_mfma_f32_16x16x32_f16 v[110:113], v[130:133], v[170:173], v[110:113]
	v_mfma_f32_16x16x32_f16 v[106:109], v[148:151], v[170:173], v[106:109]
	v_mfma_f32_16x16x32_f16 v[94:97], v[130:133], v[178:181], v[94:97]
	v_mfma_f32_16x16x32_f16 v[90:93], v[148:151], v[178:181], v[90:93]
	v_mfma_f32_16x16x32_f16 v[78:81], v[130:133], v[186:189], v[78:81]
	v_mfma_f32_16x16x32_f16 v[74:77], v[148:151], v[186:189], v[74:77]
	v_mfma_f32_16x16x32_f16 v[126:129], v[134:137], v[166:169], v[126:129]
	v_mfma_f32_16x16x32_f16 v[122:125], v[158:161], v[166:169], v[122:125]
	v_mfma_f32_16x16x32_f16 v[110:113], v[134:137], v[174:177], v[110:113]
	v_mfma_f32_16x16x32_f16 v[106:109], v[158:161], v[174:177], v[106:109]
	v_mfma_f32_16x16x32_f16 v[94:97], v[134:137], v[182:185], v[94:97]
	v_mfma_f32_16x16x32_f16 v[90:93], v[158:161], v[182:185], v[90:93]
	v_mfma_f32_16x16x32_f16 v[78:81], v[134:137], v[190:193], v[78:81]
	v_mfma_f32_16x16x32_f16 v[74:77], v[158:161], v[190:193], v[74:77]
	v_mfma_f32_16x16x32_f16 v[118:121], v[194:197], v[162:165], v[118:121]
	v_mfma_f32_16x16x32_f16 v[114:117], v[202:205], v[162:165], v[114:117]
	v_mfma_f32_16x16x32_f16 v[102:105], v[194:197], v[170:173], v[102:105]
	v_mfma_f32_16x16x32_f16 v[98:101], v[202:205], v[170:173], v[98:101]
	v_mfma_f32_16x16x32_f16 v[86:89], v[194:197], v[178:181], v[86:89]
	v_mfma_f32_16x16x32_f16 v[82:85], v[202:205], v[178:181], v[82:85]
	v_mfma_f32_16x16x32_f16 v[70:73], v[194:197], v[186:189], v[70:73]
	v_mfma_f32_16x16x32_f16 v[66:69], v[202:205], v[186:189], v[66:69]
	v_mfma_f32_16x16x32_f16 v[118:121], v[198:201], v[166:169], v[118:121]
	v_mfma_f32_16x16x32_f16 v[114:117], v[220:223], v[166:169], v[114:117]
	v_mfma_f32_16x16x32_f16 v[102:105], v[198:201], v[174:177], v[102:105]
	v_mfma_f32_16x16x32_f16 v[98:101], v[220:223], v[174:177], v[98:101]
	v_mfma_f32_16x16x32_f16 v[86:89], v[198:201], v[182:185], v[86:89]
	v_mfma_f32_16x16x32_f16 v[82:85], v[220:223], v[182:185], v[82:85]
	v_mfma_f32_16x16x32_f16 v[70:73], v[198:201], v[190:193], v[70:73]
	v_mfma_f32_16x16x32_f16 v[66:69], v[220:223], v[190:193], v[66:69]
	s_barrier
	v_lshl_add_u64 v[152:153], s[40:41], 0, v[0:1]
	s_mov_b32 m0, s45
	v_lshl_add_u64 v[206:207], s[40:41], 0, v[142:143]
	global_load_lds_dwordx4 v[152:153], off
	s_add_i32 m0, s45, 0x2000
	s_nop 0
	global_load_lds_dwordx4 v[206:207], off
	s_mov_b32 m0, s23
	v_lshl_add_u64 v[212:213], s[48:49], 0, v[138:139]
	ds_read_b128 v[162:165], v157 offset:16384
	ds_read_b128 v[166:169], v157 offset:17408
	ds_read_b128 v[170:173], v157 offset:18432
	ds_read_b128 v[174:177], v157 offset:19456
	ds_read_b128 v[178:181], v157 offset:20480
	ds_read_b128 v[182:185], v157 offset:21504
	ds_read_b128 v[186:189], v157 offset:22528
	ds_read_b128 v[190:193], v157 offset:23552
	global_load_lds_dwordx4 v[212:213], off
	v_lshl_add_u64 v[224:225], s[48:49], 0, v[140:141]
	s_mov_b32 m0, s27
	s_nop 0
	global_load_lds_dwordx4 v[224:225], off
	s_waitcnt vmcnt(6) lgkmcnt(0)
	s_barrier
	v_mfma_f32_16x16x32_f16 v[62:65], v[130:133], v[162:165], v[62:65]
	v_mfma_f32_16x16x32_f16 v[58:61], v[148:151], v[162:165], v[58:61]
	v_mfma_f32_16x16x32_f16 v[46:49], v[130:133], v[170:173], v[46:49]
	v_mfma_f32_16x16x32_f16 v[42:45], v[148:151], v[170:173], v[42:45]
	v_mfma_f32_16x16x32_f16 v[30:33], v[130:133], v[178:181], v[30:33]
	v_mfma_f32_16x16x32_f16 v[26:29], v[148:151], v[178:181], v[26:29]
	v_mfma_f32_16x16x32_f16 v[14:17], v[130:133], v[186:189], v[14:17]
	v_mfma_f32_16x16x32_f16 v[10:13], v[148:151], v[186:189], v[10:13]
	v_mfma_f32_16x16x32_f16 v[62:65], v[134:137], v[166:169], v[62:65]
	v_mfma_f32_16x16x32_f16 v[58:61], v[158:161], v[166:169], v[58:61]
	v_mfma_f32_16x16x32_f16 v[46:49], v[134:137], v[174:177], v[46:49]
	v_mfma_f32_16x16x32_f16 v[42:45], v[158:161], v[174:177], v[42:45]
	v_mfma_f32_16x16x32_f16 v[30:33], v[134:137], v[182:185], v[30:33]
	v_mfma_f32_16x16x32_f16 v[26:29], v[158:161], v[182:185], v[26:29]
	v_mfma_f32_16x16x32_f16 v[14:17], v[134:137], v[190:193], v[14:17]
	v_mfma_f32_16x16x32_f16 v[10:13], v[158:161], v[190:193], v[10:13]
	v_mfma_f32_16x16x32_f16 v[54:57], v[194:197], v[162:165], v[54:57]
	v_mfma_f32_16x16x32_f16 v[50:53], v[202:205], v[162:165], v[50:53]
	v_mfma_f32_16x16x32_f16 v[38:41], v[194:197], v[170:173], v[38:41]
	v_mfma_f32_16x16x32_f16 v[34:37], v[202:205], v[170:173], v[34:37]
	v_mfma_f32_16x16x32_f16 v[22:25], v[194:197], v[178:181], v[22:25]
	v_mfma_f32_16x16x32_f16 v[18:21], v[202:205], v[178:181], v[18:21]
	v_mfma_f32_16x16x32_f16 v[6:9], v[194:197], v[186:189], v[6:9]
	v_mfma_f32_16x16x32_f16 v[2:5], v[202:205], v[186:189], v[2:5]
	v_mfma_f32_16x16x32_f16 v[54:57], v[198:201], v[166:169], v[54:57]
	v_mfma_f32_16x16x32_f16 v[50:53], v[220:223], v[166:169], v[50:53]
	v_mfma_f32_16x16x32_f16 v[38:41], v[198:201], v[174:177], v[38:41]
	v_mfma_f32_16x16x32_f16 v[34:37], v[220:223], v[174:177], v[34:37]
	v_mfma_f32_16x16x32_f16 v[22:25], v[198:201], v[182:185], v[22:25]
	v_mfma_f32_16x16x32_f16 v[18:21], v[220:223], v[182:185], v[18:21]
	v_mfma_f32_16x16x32_f16 v[6:9], v[198:201], v[190:193], v[6:9]
	v_mfma_f32_16x16x32_f16 v[2:5], v[220:223], v[190:193], v[2:5]
	s_barrier
; #define PG8_STAGE(bufoff, gbase, voff) do { _Pragma("unroll") for (int _i = 0; _i < 2; ++_i) \
;         __builtin_amdgcn_global_load_lds((const unsigned*)((const char*)(gbase) + (voff)[_i]), (LAS unsigned*)(lds + (bufoff) + ldsw + _i * 8192), 16, 0, 0); } while (0)
; #define PG8_LDA(dst, b, h) do { _Pragma("unroll") for (int m = 0; m < 4; ++m) _Pragma("unroll") for (int k = 0; k < 2; ++k) dst[m][k] = *(const LAS h16x8*)(lds + PG8_SA(b, h) + aoff + m * 2048 + k * 1024); } while (0)
; #define PG8_LDB(dst, b, h) do { _Pragma("unroll") for (int n = 0; n < 2; ++n) _Pragma("unroll") for (int k = 0; k < 2; ++k) dst[n][k] = *(const LAS h16x8*)(lds + PG8_SB(b, h) + boff + n * 2048 + k * 1024); } while (0)
; #define PG8_MMA(ai, bj, At, Bt_) do { __builtin_amdgcn_s_setprio(1); _Pragma("unroll") for (int m = 0; m < 4; ++m) _Pragma("unroll") for (int n = 0; n < 2; ++n) _Pragma("unroll") for (int k = 0; k < 2; ++k) \
;         acc[ai][bj][m][n] = __builtin_amdgcn_mfma_f32_16x16x32_f16(Bt_[n][k], At[m][k], acc[ai][bj][m][n], 0, 0, 0); __builtin_amdgcn_s_setprio(0); } while (0)
; #define PG8_WAIT_V(n) asm volatile("s_waitcnt vmcnt(" #n ")" ::: "memory")
; #define PG8_WAIT_L(n) asm volatile("s_waitcnt lgkmcnt(" #n ")" ::: "memory")
; #define PG8_BAR __builtin_amdgcn_s_barrier()
; #define PG8_SCHED __builtin_amdgcn_sched_barrier(0)
; template <class Epi, class AMap>
; __device__ __forceinline__ void gemm_phase(LAS unsigned char* lds, const AMap am, const int lda, const h16* Bt, const int ldb, const int M, const int N, const int K, const Epi& E) {
;     ...
;             PG8_STAGE(PG8_SB(0, 1), b2 + hstepB, voffB);
;             PG8_WAIT_V(6); PG8_BAR; PG8_MMA(1, 1, At, B1); PG8_BAR;
;             PG8_LDB(B0, 1, 0); PG8_SCHED; PG8_LDA(At, 1, 0); PG8_STAGE(PG8_SA(0, 1), a2 + hstepA, voffA);
;             PG8_WAIT_L(8); PG8_BAR; PG8_WAIT_L(0); PG8_MMA(0, 0, At, B0); PG8_BAR; PG8_SCHED;
;             PG8_LDB(B1, 1, 1); PG8_STAGE(PG8_SB(1, 0), b3, voffB);
;             PG8_BAR; PG8_WAIT_L(0); PG8_MMA(0, 1, At, B1); PG8_BAR;
	s_add_u32 s50, s40, 0x80000
	s_addc_u32 s51, s41, 0
	s_add_i32 s45, s60, s72
	v_lshl_add_u64 v[232:233], s[50:51], 0, v[0:1]
	s_mov_b32 m0, s45
	s_nop 0
	global_load_lds_dwordx4 v[232:233], off
	v_lshl_add_u64 v[232:233], s[50:51], 0, v[142:143]
	s_add_i32 m0, s45, 0x2000
	s_nop 0
	global_load_lds_dwordx4 v[232:233], off
	s_add_i32 s45, 0, 0x18000
	v_add_u32_e32 v234, s45, v155
	ds_read_b128 v[130:133], v234
	ds_read_b128 v[134:137], v234 offset:1024
	ds_read_b128 v[148:151], v234 offset:2048
	ds_read_b128 v[158:161], v234 offset:3072
	s_add_u32 s48, s48, 0x80000
	s_addc_u32 s49, s49, 0
	s_mov_b32 m0, s73
	v_lshl_add_u64 v[232:233], s[48:49], 0, v[138:139]
	ds_read_b128 v[162:165], v157 offset:32768
	ds_read_b128 v[166:169], v157 offset:33792
	ds_read_b128 v[170:173], v157 offset:34816
	ds_read_b128 v[174:177], v157 offset:35840
	ds_read_b128 v[178:181], v157 offset:36864
	ds_read_b128 v[182:185], v157 offset:37888
	ds_read_b128 v[186:189], v157 offset:38912
	ds_read_b128 v[190:193], v157 offset:39936
	global_load_lds_dwordx4 v[232:233], off
	v_lshl_add_u64 v[232:233], s[48:49], 0, v[140:141]
	s_mov_b32 m0, s74
	s_nop 0
	global_load_lds_dwordx4 v[232:233], off
	s_waitcnt lgkmcnt(11)
	s_add_i32 s48, 0, 0x1c000
	s_add_i32 s45, s45, s72
	v_add_u32_e32 v214, s48, v155
	v_lshl_add_u64 v[152:153], v[152:153], 0, s[92:93]
	s_mov_b32 m0, s45
	ds_read_b128 v[194:197], v214
	ds_read_b128 v[198:201], v214 offset:1024
	ds_read_b128 v[202:205], v214 offset:2048
	ds_read_b128 v[220:223], v214 offset:3072
	s_waitcnt vmcnt(8) lgkmcnt(0)
	s_barrier
	v_mfma_f32_16x16x32_f16 v[126:129], v[130:133], v[162:165], v[126:129]
	v_mfma_f32_16x16x32_f16 v[122:125], v[148:151], v[162:165], v[122:125]
	v_mfma_f32_16x16x32_f16 v[110:113], v[130:133], v[170:173], v[110:113]
	v_mfma_f32_16x16x32_f16 v[106:109], v[148:151], v[170:173], v[106:109]
	v_mfma_f32_16x16x32_f16 v[94:97], v[130:133], v[178:181], v[94:97]
	v_mfma_f32_16x16x32_f16 v[90:93], v[148:151], v[178:181], v[90:93]
	v_mfma_f32_16x16x32_f16 v[78:81], v[130:133], v[186:189], v[78:81]
	v_mfma_f32_16x16x32_f16 v[74:77], v[148:151], v[186:189], v[74:77]
	v_mfma_f32_16x16x32_f16 v[126:129], v[134:137], v[166:169], v[126:129]
	v_mfma_f32_16x16x32_f16 v[122:125], v[158:161], v[166:169], v[122:125]
	v_mfma_f32_16x16x32_f16 v[110:113], v[134:137], v[174:177], v[110:113]
	v_mfma_f32_16x16x32_f16 v[106:109], v[158:161], v[174:177], v[106:109]
	v_mfma_f32_16x16x32_f16 v[94:97], v[134:137], v[182:185], v[94:97]
	v_mfma_f32_16x16x32_f16 v[90:93], v[158:161], v[182:185], v[90:93]
	v_mfma_f32_16x16x32_f16 v[78:81], v[134:137], v[190:193], v[78:81]
	v_mfma_f32_16x16x32_f16 v[74:77], v[158:161], v[190:193], v[74:77]
	v_mfma_f32_16x16x32_f16 v[118:121], v[194:197], v[162:165], v[118:121]
	v_mfma_f32_16x16x32_f16 v[114:117], v[202:205], v[162:165], v[114:117]
	v_mfma_f32_16x16x32_f16 v[102:105], v[194:197], v[170:173], v[102:105]
	v_mfma_f32_16x16x32_f16 v[98:101], v[202:205], v[170:173], v[98:101]
	v_mfma_f32_16x16x32_f16 v[86:89], v[194:197], v[178:181], v[86:89]
	v_mfma_f32_16x16x32_f16 v[82:85], v[202:205], v[178:181], v[82:85]
	v_mfma_f32_16x16x32_f16 v[70:73], v[194:197], v[186:189], v[70:73]
	v_mfma_f32_16x16x32_f16 v[66:69], v[202:205], v[186:189], v[66:69]
	v_mfma_f32_16x16x32_f16 v[118:121], v[198:201], v[166:169], v[118:121]
	v_mfma_f32_16x16x32_f16 v[114:117], v[220:223], v[166:169], v[114:117]
	v_mfma_f32_16x16x32_f16 v[102:105], v[198:201], v[174:177], v[102:105]
	v_mfma_f32_16x16x32_f16 v[98:101], v[220:223], v[174:177], v[98:101]
	v_mfma_f32_16x16x32_f16 v[86:89], v[198:201], v[182:185], v[86:89]
	v_mfma_f32_16x16x32_f16 v[82:85], v[220:223], v[182:185], v[82:85]
	v_mfma_f32_16x16x32_f16 v[70:73], v[198:201], v[190:193], v[70:73]
	v_mfma_f32_16x16x32_f16 v[66:69], v[220:223], v[190:193], v[66:69]
	s_barrier
; #define PG8_STAGE(bufoff, gbase, voff) do { _Pragma("unroll") for (int _i = 0; _i < 2; ++_i) \
;         __builtin_amdgcn_global_load_lds((const unsigned*)((const char*)(gbase) + (voff)[_i]), (LAS unsigned*)(lds + (bufoff) + ldsw + _i * 8192), 16, 0, 0); } while (0)
; #define PG8_LDA(dst, b, h) do { _Pragma("unroll") for (int m = 0; m < 4; ++m) _Pragma("unroll") for (int k = 0; k < 2; ++k) dst[m][k] = *(const LAS h16x8*)(lds + PG8_SA(b, h) + aoff + m * 2048 + k * 1024); } while (0)
; #define PG8_MMA(ai, bj, At, Bt_) do { __builtin_amdgcn_s_setprio(1); _Pragma("unroll") for (int m = 0; m < 4; ++m) _Pragma("unroll") for (int n = 0; n < 2; ++n) _Pragma("unroll") for (int k = 0; k < 2; ++k) \
;         acc[ai][bj][m][n] = __builtin_amdgcn_mfma_f32_16x16x32_f16(Bt_[n][k], At[m][k], acc[ai][bj][m][n], 0, 0, 0); __builtin_amdgcn_s_setprio(0); } while (0)
; #define PG8_WAIT_V(n) asm volatile("s_waitcnt vmcnt(" #n ")" ::: "memory")
; #define PG8_WAIT_L(n) asm volatile("s_waitcnt lgkmcnt(" #n ")" ::: "memory")
; #define PG8_BAR __builtin_amdgcn_s_barrier()
; #define PG8_SCHED __builtin_amdgcn_sched_barrier(0)
; template <class Epi, class AMap>
; __device__ __forceinline__ void gemm_phase(LAS unsigned char* lds, const AMap am, const int lda, const h16* Bt, const int ldb, const int M, const int N, const int K, const Epi& E) {
;     ...
;             PG8_LDA(At, 1, 1); PG8_STAGE(PG8_SA(1, 0), a3, voffA);
;             PG8_BAR; PG8_WAIT_L(0); PG8_MMA(1, 0, At, B0); PG8_BAR; PG8_SCHED;
;             PG8_STAGE(PG8_SB(1, 1), b3 + hstepB, voffB);
;             PG8_WAIT_V(6); PG8_BAR; PG8_MMA(1, 1, At, B1); PG8_BAR;
;         }
;     ...
;     if (wr == 0) PG8_BAR;
	global_load_lds_dwordx4 v[152:153], off
	v_lshl_add_u64 v[152:153], v[206:207], 0, s[92:93]
	s_add_i32 m0, s45, 0x2000
	s_nop 0
	global_load_lds_dwordx4 v[152:153], off
	s_mov_b32 m0, s75
	v_lshl_add_u64 v[152:153], v[212:213], 0, s[92:93]
	ds_read_b128 v[162:165], v157 offset:49152
	ds_read_b128 v[166:169], v157 offset:50176
	ds_read_b128 v[170:173], v157 offset:51200
	ds_read_b128 v[174:177], v157 offset:52224
	ds_read_b128 v[178:181], v157 offset:53248
	ds_read_b128 v[182:185], v157 offset:54272
	ds_read_b128 v[186:189], v157 offset:55296
	ds_read_b128 v[190:193], v157 offset:56320
	global_load_lds_dwordx4 v[152:153], off
	v_lshl_add_u64 v[152:153], v[224:225], 0, s[92:93]
	s_mov_b32 m0, s76
	s_nop 0
	global_load_lds_dwordx4 v[152:153], off
	s_add_u32 s40, s40, 0x80080
	s_addc_u32 s41, s41, 0
	s_add_i32 s45, s48, s72
	v_lshl_add_u64 v[232:233], s[40:41], 0, v[0:1]
	s_mov_b32 m0, s45
	s_nop 0
	global_load_lds_dwordx4 v[232:233], off
	v_lshl_add_u64 v[232:233], s[40:41], 0, v[142:143]
	s_add_i32 m0, s45, 0x2000
	s_nop 0
	global_load_lds_dwordx4 v[232:233], off
	s_add_i32 s43, s43, 2
	s_add_u32 s0, s0, 0x100
	s_addc_u32 s1, s1, 0
	s_add_u32 s21, s21, 0x100
	s_addc_u32 s35, s35, 0
	s_cmp_gt_u32 s43, 29
	s_waitcnt vmcnt(8) lgkmcnt(0)
	s_barrier
	v_mfma_f32_16x16x32_f16 v[62:65], v[130:133], v[162:165], v[62:65]
	v_mfma_f32_16x16x32_f16 v[58:61], v[148:151], v[162:165], v[58:61]
	v_mfma_f32_16x16x32_f16 v[46:49], v[130:133], v[170:173], v[46:49]
	v_mfma_f32_16x16x32_f16 v[42:45], v[148:151], v[170:173], v[42:45]
	v_mfma_f32_16x16x32_f16 v[30:33], v[130:133], v[178:181], v[30:33]
	v_mfma_f32_16x16x32_f16 v[26:29], v[148:151], v[178:181], v[26:29]
	v_mfma_f32_16x16x32_f16 v[14:17], v[130:133], v[186:189], v[14:17]
	v_mfma_f32_16x16x32_f16 v[10:13], v[148:151], v[186:189], v[10:13]
	v_mfma_f32_16x16x32_f16 v[62:65], v[134:137], v[166:169], v[62:65]
	v_mfma_f32_16x16x32_f16 v[58:61], v[158:161], v[166:169], v[58:61]
	v_mfma_f32_16x16x32_f16 v[46:49], v[134:137], v[174:177], v[46:49]
	v_mfma_f32_16x16x32_f16 v[42:45], v[158:161], v[174:177], v[42:45]
	v_mfma_f32_16x16x32_f16 v[30:33], v[134:137], v[182:185], v[30:33]
	v_mfma_f32_16x16x32_f16 v[26:29], v[158:161], v[182:185], v[26:29]
	v_mfma_f32_16x16x32_f16 v[14:17], v[134:137], v[190:193], v[14:17]
	v_mfma_f32_16x16x32_f16 v[10:13], v[158:161], v[190:193], v[10:13]
	v_mfma_f32_16x16x32_f16 v[54:57], v[194:197], v[162:165], v[54:57]
	v_mfma_f32_16x16x32_f16 v[50:53], v[202:205], v[162:165], v[50:53]
	v_mfma_f32_16x16x32_f16 v[38:41], v[194:197], v[170:173], v[38:41]
	v_mfma_f32_16x16x32_f16 v[34:37], v[202:205], v[170:173], v[34:37]
	v_mfma_f32_16x16x32_f16 v[22:25], v[194:197], v[178:181], v[22:25]
	v_mfma_f32_16x16x32_f16 v[18:21], v[202:205], v[178:181], v[18:21]
	v_mfma_f32_16x16x32_f16 v[6:9], v[194:197], v[186:189], v[6:9]
	v_mfma_f32_16x16x32_f16 v[2:5], v[202:205], v[186:189], v[2:5]
	v_mfma_f32_16x16x32_f16 v[54:57], v[198:201], v[166:169], v[54:57]
	v_mfma_f32_16x16x32_f16 v[50:53], v[220:223], v[166:169], v[50:53]
	v_mfma_f32_16x16x32_f16 v[38:41], v[198:201], v[174:177], v[38:41]
	v_mfma_f32_16x16x32_f16 v[34:37], v[220:223], v[174:177], v[34:37]
	v_mfma_f32_16x16x32_f16 v[22:25], v[198:201], v[182:185], v[22:25]
	v_mfma_f32_16x16x32_f16 v[18:21], v[220:223], v[182:185], v[18:21]
	v_mfma_f32_16x16x32_f16 v[6:9], v[198:201], v[190:193], v[6:9]
	v_mfma_f32_16x16x32_f16 v[2:5], v[220:223], v[190:193], v[2:5]
	s_barrier
	s_cbranch_scc0 .LBB0_799
	s_cmpk_gt_u32 s71, 0xff
	s_cbranch_scc1 .Lgx8
	s_barrier
